# removed all s_setprio flips from the 10 GEMM K-loops (both wave groups at equal priority)
# speedup vs baseline: 1.0065x; 1.0063x over previous
; #define PG8_STAGE(bufoff, gbase, voff) do { _Pragma("unroll") for (int _i = 0; _i < 2; ++_i) \
;         __builtin_amdgcn_global_load_lds((const GAS unsigned*)((const GAS char*)(gbase) + (voff)[_i]), (PG8_LAS unsigned*)(lds + (bufoff) + ldsw + _i * 8192), 16, 0, 0); } while (0)
; #define PG8_LDA(dst, b, h) do { _Pragma("unroll") for (int m = 0; m < 4; ++m) _Pragma("unroll") for (int k = 0; k < 2; ++k) dst[m][k] = *(const PG8_LAS bf16x8*)(lds + PG8_SA(b, h) + aoff + m * 2048 + k * 1024); } while (0)
; #define PG8_LDB(dst, b, h) do { _Pragma("unroll") for (int n = 0; n < 2; ++n) _Pragma("unroll") for (int k = 0; k < 2; ++k) dst[n][k] = *(const PG8_LAS bf16x8*)(lds + PG8_SB(b, h) + boff + n * 2048 + k * 1024); } while (0)
; #define PG8_MMA(ai, bj, At, Bt) do { __builtin_amdgcn_s_setprio(1); _Pragma("unroll") for (int m = 0; m < 4; ++m) _Pragma("unroll") for (int n = 0; n < 2; ++n) _Pragma("unroll") for (int k = 0; k < 2; ++k) \
;         acc[ai][bj][m][n] = __builtin_amdgcn_mfma_f32_16x16x32_bf16(Bt[n][k], At[m][k], acc[ai][bj][m][n], 0, 0, 0); __builtin_amdgcn_s_setprio(0); } while (0)
; #define PG8_WAIT_V(n) asm volatile("s_waitcnt vmcnt(" #n ")" ::: "memory")
; #define PG8_WAIT_L(n) asm volatile("s_waitcnt lgkmcnt(" #n ")" ::: "memory")
; #define PG8_BAR __builtin_amdgcn_s_barrier()
; #define PG8_SCHED __builtin_amdgcn_sched_barrier(0)
; #define PG8_STAGE(bufoff, gbase, voff) do { _Pragma("unroll") for (int _i = 0; _i < 2; ++_i) \
;         __builtin_amdgcn_global_load_lds((const GAS unsigned*)((const GAS char*)(gbase) + (voff)[_i]), (PG8_LAS unsigned*)(lds + (bufoff) + ldsw + _i * 8192), 16, 0, 0); } while (0)
; #define PG8_LDA(dst, b, h) do { _Pragma("unroll") for (int m = 0; m < 4; ++m) _Pragma("unroll") for (int k = 0; k < 2; ++k) dst[m][k] = *(const PG8_LAS bf16x8*)(lds + PG8_SA(b, h) + aoff + m * 2048 + k * 1024); } while (0)
; #define PG8_BAR __builtin_amdgcn_s_barrier()
; template <class Epi, class Sched>
; __device__ __forceinline__ void gemm_phase_strip(PG8_LAS unsigned char* lds, PG8_LAS unsigned char* slds, PG8_LAS unsigned char* pf, const Gemm g, const Sched& S, const Epi& E, int wv) {
;     ...
;             PG8_LDB(B0, 0, 0); PG8_LDB(B1, 0, 1); PG8_SCHED; PG8_LDA(At, 0, 0); PG8_STAGE(PG8_SA(1, 1), a1 + PG8_HS, voffA);
;             PG8_WAIT_V(8); PG8_WAIT_L(0); PG8_BAR; PG8_MMA(0, 0, At, B0); PG8_MMA(0, 1, At, B1); PG8_BAR; PG8_SCHED;
.LBB0_243:
	s_add_i32 s20, s20, 2
	s_barrier
	s_xor_b32 s57, s57, 0x1000
	s_add_u32 s94, s94, 0x100
	s_addc_u32 s95, s95, 0
	s_cmp_ge_u32 s20, s21
	s_cbranch_scc1 .LBB0_254
.LBB0_244:
	s_cmp_eq_u32 s24, s94
	s_cselect_b64 s[2:3], -1, 0
	s_add_u32 s25, s42, s94
	s_addc_u32 s28, s43, s95
	s_add_u32 s25, s25, 0x100
	s_addc_u32 s40, s28, 0
	s_and_b64 s[28:29], s[2:3], exec
	s_cselect_b32 s29, s7, s40
	s_cselect_b32 s28, s6, s25
	s_add_u32 s25, s48, s94
	s_addc_u32 s44, s85, s95
	s_add_i32 s66, 0, 0x10000
	v_add_u32_e32 v128, s66, v247
	s_add_i32 s67, 0, 0x14000
	ds_read_b128 v[156:159], v128
	ds_read_b128 v[152:155], v128 offset:1024
	ds_read_b128 v[174:177], v128 offset:2048
	ds_read_b128 v[170:173], v128 offset:3072
	v_add_u32_e32 v128, s67, v247
	ds_read_b128 v[166:169], v128
	ds_read_b128 v[162:165], v128 offset:1024
	ds_read_b128 v[182:185], v128 offset:2048
	ds_read_b128 v[178:181], v128 offset:3072
	s_and_b64 s[40:41], s[2:3], exec
	s_cselect_b32 s45, s1, s44
	s_cselect_b32 s44, s11, s25
	v_lshl_add_u64 v[136:137], v[228:229], 0, s[94:95]
	s_add_i32 m0, s53, 0xc000
	ds_read_b128 v[128:131], v250
	ds_read_b128 v[132:135], v250 offset:1024
	ds_read_b128 v[186:189], v250 offset:2048
	ds_read_b128 v[190:193], v250 offset:3072
	ds_read_b128 v[194:197], v250 offset:4096
	ds_read_b128 v[198:201], v250 offset:5120
	ds_read_b128 v[202:205], v250 offset:6144
	ds_read_b128 v[206:209], v250 offset:7168
	global_load_lds_dwordx4 v[136:137], off
	v_lshl_add_u64 v[136:137], v[226:227], 0, s[94:95]
	s_add_i32 m0, s53, 0xe000
	s_nop 0
	global_load_lds_dwordx4 v[136:137], off
	s_waitcnt vmcnt(8)
	s_waitcnt lgkmcnt(0)
	s_barrier
	s_waitcnt lgkmcnt(0)
	v_mfma_f32_16x16x32_bf16 v[136:139], v[156:159], v[128:131], v[148:151]
	v_mfma_f32_16x16x32_bf16 v[140:143], v[174:177], v[128:131], v[144:147]
	v_mfma_f32_16x16x32_bf16 v[116:119], v[156:159], v[186:189], v[116:119]
	v_mfma_f32_16x16x32_bf16 v[112:115], v[174:177], v[186:189], v[112:115]
	v_mfma_f32_16x16x32_bf16 v[100:103], v[156:159], v[194:197], v[100:103]
	v_mfma_f32_16x16x32_bf16 v[96:99], v[174:177], v[194:197], v[96:99]
	v_mfma_f32_16x16x32_bf16 v[84:87], v[156:159], v[202:205], v[84:87]
	v_mfma_f32_16x16x32_bf16 v[80:83], v[174:177], v[202:205], v[80:83]
	v_mfma_f32_16x16x32_bf16 v[136:139], v[152:155], v[132:135], v[136:139]
	v_mfma_f32_16x16x32_bf16 v[140:143], v[170:173], v[132:135], v[140:143]
	v_mfma_f32_16x16x32_bf16 v[116:119], v[152:155], v[190:193], v[116:119]
	v_mfma_f32_16x16x32_bf16 v[112:115], v[170:173], v[190:193], v[112:115]
	v_mfma_f32_16x16x32_bf16 v[100:103], v[152:155], v[198:201], v[100:103]
	v_mfma_f32_16x16x32_bf16 v[96:99], v[170:173], v[198:201], v[96:99]
	v_mfma_f32_16x16x32_bf16 v[84:87], v[152:155], v[206:209], v[84:87]
	v_mfma_f32_16x16x32_bf16 v[80:83], v[170:173], v[206:209], v[80:83]
	v_mfma_f32_16x16x32_bf16 v[124:127], v[166:169], v[128:131], v[124:127]
	v_mfma_f32_16x16x32_bf16 v[120:123], v[182:185], v[128:131], v[120:123]
	v_mfma_f32_16x16x32_bf16 v[108:111], v[166:169], v[186:189], v[108:111]
	v_mfma_f32_16x16x32_bf16 v[104:107], v[182:185], v[186:189], v[104:107]
	v_mfma_f32_16x16x32_bf16 v[92:95], v[166:169], v[194:197], v[92:95]
	v_mfma_f32_16x16x32_bf16 v[88:91], v[182:185], v[194:197], v[88:91]
	v_mfma_f32_16x16x32_bf16 v[76:79], v[166:169], v[202:205], v[76:79]
	v_mfma_f32_16x16x32_bf16 v[72:75], v[182:185], v[202:205], v[72:75]
	v_mfma_f32_16x16x32_bf16 v[124:127], v[162:165], v[132:135], v[124:127]
	v_mfma_f32_16x16x32_bf16 v[120:123], v[178:181], v[132:135], v[120:123]
	v_mfma_f32_16x16x32_bf16 v[108:111], v[162:165], v[190:193], v[108:111]
	v_mfma_f32_16x16x32_bf16 v[104:107], v[178:181], v[190:193], v[104:107]
	v_mfma_f32_16x16x32_bf16 v[92:95], v[162:165], v[198:201], v[92:95]
	v_mfma_f32_16x16x32_bf16 v[88:91], v[178:181], v[198:201], v[88:91]
	v_mfma_f32_16x16x32_bf16 v[76:79], v[162:165], v[206:209], v[76:79]
	v_mfma_f32_16x16x32_bf16 v[72:75], v[178:181], v[206:209], v[72:75]
	s_barrier
; #define PG8_STAGE(bufoff, gbase, voff) do { _Pragma("unroll") for (int _i = 0; _i < 2; ++_i) \
;         __builtin_amdgcn_global_load_lds((const GAS unsigned*)((const GAS char*)(gbase) + (voff)[_i]), (PG8_LAS unsigned*)(lds + (bufoff) + ldsw + _i * 8192), 16, 0, 0); } while (0)
; #define PG8_LDA(dst, b, h) do { _Pragma("unroll") for (int m = 0; m < 4; ++m) _Pragma("unroll") for (int k = 0; k < 2; ++k) dst[m][k] = *(const PG8_LAS bf16x8*)(lds + PG8_SA(b, h) + aoff + m * 2048 + k * 1024); } while (0)
; #define PG8_MMA(ai, bj, At, Bt) do { __builtin_amdgcn_s_setprio(1); _Pragma("unroll") for (int m = 0; m < 4; ++m) _Pragma("unroll") for (int n = 0; n < 2; ++n) _Pragma("unroll") for (int k = 0; k < 2; ++k) \
;         acc[ai][bj][m][n] = __builtin_amdgcn_mfma_f32_16x16x32_bf16(Bt[n][k], At[m][k], acc[ai][bj][m][n], 0, 0, 0); __builtin_amdgcn_s_setprio(0); } while (0)
; #define PG8_WAIT_V(n) asm volatile("s_waitcnt vmcnt(" #n ")" ::: "memory")
; #define PG8_WAIT_L(n) asm volatile("s_waitcnt lgkmcnt(" #n ")" ::: "memory")
; #define PG8_BAR __builtin_amdgcn_s_barrier()
; #define PG8_SCHED __builtin_amdgcn_sched_barrier(0)
; #define PG8_STAGE(bufoff, gbase, voff) do { _Pragma("unroll") for (int _i = 0; _i < 2; ++_i) \
;         __builtin_amdgcn_global_load_lds((const GAS unsigned*)((const GAS char*)(gbase) + (voff)[_i]), (PG8_LAS unsigned*)(lds + (bufoff) + ldsw + _i * 8192), 16, 0, 0); } while (0)
; #define PG8_LDA(dst, b, h) do { _Pragma("unroll") for (int m = 0; m < 4; ++m) _Pragma("unroll") for (int k = 0; k < 2; ++k) dst[m][k] = *(const PG8_LAS bf16x8*)(lds + PG8_SA(b, h) + aoff + m * 2048 + k * 1024); } while (0)
; #define PG8_LDS_S(dst, boffs) do { dst[0] = *(const PG8_LAS bf16x8*)(slds + (boffs) + soff0); dst[1] = *(const PG8_LAS bf16x8*)(slds + (boffs) + (soff0 ^ 64)); } while (0)
; #define PG8_BAR __builtin_amdgcn_s_barrier()
; template <class Epi, class Sched>
; __device__ __forceinline__ void gemm_phase_strip(PG8_LAS unsigned char* lds, PG8_LAS unsigned char* slds, PG8_LAS unsigned char* pf, const Gemm g, const Sched& S, const Epi& E, int wv) {
;     ...
;             PG8_LDA(At, 0, 1); PG8_LDS_S(As, sq); PG8_STAGE(PG8_SB(0, 0), b2, voffB); PG8_STAGE(PG8_SB(0, 1), b2 + hstepB, voffB); PG8_STAGE(PG8_SA(0, 0), a2, voffA);
;             PG8_WAIT_V(8); PG8_WAIT_L(0); PG8_BAR; PG8_MMA(1, 0, At, B0); PG8_MMA(1, 1, At, B1); PG8_MMA_S(); PG8_BAR; PG8_SCHED;
	s_add_i32 s25, s57, 0
	s_add_i32 s25, s25, 0x21000
	v_add_u32_e32 v160, s25, v248
	v_add_u32_e32 v251, s25, v249
	s_add_i32 s25, s66, s81
	v_lshl_add_u64 v[230:231], s[44:45], 0, v[216:217]
	s_mov_b32 m0, s25
	ds_read_b128 v[128:131], v250 offset:16384
	ds_read_b128 v[132:135], v250 offset:17408
	ds_read_b128 v[186:189], v250 offset:18432
	ds_read_b128 v[190:193], v250 offset:19456
	ds_read_b128 v[194:197], v250 offset:20480
	ds_read_b128 v[198:201], v250 offset:21504
	ds_read_b128 v[202:205], v250 offset:22528
	ds_read_b128 v[206:209], v250 offset:23552
	ds_read_b128 v[148:151], v160
	ds_read_b128 v[144:147], v251
	global_load_lds_dwordx4 v[230:231], off
	s_add_i32 m0, s25, 0x2000
	s_add_u32 s40, s44, 0x80000
	v_lshl_add_u64 v[232:233], s[44:45], 0, v[220:221]
	s_addc_u32 s41, s45, 0
	s_add_i32 s25, s67, s81
	global_load_lds_dwordx4 v[232:233], off
	v_lshl_add_u64 v[234:235], s[40:41], 0, v[216:217]
	s_mov_b32 m0, s25
	v_lshl_add_u64 v[236:237], s[28:29], 0, v[218:219]
	global_load_lds_dwordx4 v[234:235], off
	v_lshl_add_u64 v[234:235], s[40:41], 0, v[220:221]
	s_add_i32 m0, s25, 0x2000
	s_nop 0
	global_load_lds_dwordx4 v[234:235], off
	v_lshl_add_u64 v[234:235], s[28:29], 0, v[214:215]
	s_mov_b32 m0, s53
	s_nop 0
	global_load_lds_dwordx4 v[234:235], off
	s_mov_b32 m0, s97
	s_nop 0
	global_load_lds_dwordx4 v[236:237], off
	s_waitcnt vmcnt(8)
	s_waitcnt lgkmcnt(0)
	s_barrier
	s_waitcnt lgkmcnt(0)
	v_mfma_f32_16x16x32_bf16 v[68:71], v[156:159], v[128:131], v[68:71]
	v_mfma_f32_16x16x32_bf16 v[64:67], v[174:177], v[128:131], v[64:67]
	v_mfma_f32_16x16x32_bf16 v[52:55], v[156:159], v[186:189], v[52:55]
	v_mfma_f32_16x16x32_bf16 v[48:51], v[174:177], v[186:189], v[48:51]
	v_mfma_f32_16x16x32_bf16 v[36:39], v[156:159], v[194:197], v[36:39]
	v_mfma_f32_16x16x32_bf16 v[32:35], v[174:177], v[194:197], v[32:35]
	v_mfma_f32_16x16x32_bf16 v[20:23], v[156:159], v[202:205], v[20:23]
	v_mfma_f32_16x16x32_bf16 v[16:19], v[174:177], v[202:205], v[16:19]
	v_mfma_f32_16x16x32_bf16 v[68:71], v[152:155], v[132:135], v[68:71]
	v_mfma_f32_16x16x32_bf16 v[64:67], v[170:173], v[132:135], v[64:67]
	v_mfma_f32_16x16x32_bf16 v[52:55], v[152:155], v[190:193], v[52:55]
	v_mfma_f32_16x16x32_bf16 v[48:51], v[170:173], v[190:193], v[48:51]
	v_mfma_f32_16x16x32_bf16 v[36:39], v[152:155], v[198:201], v[36:39]
	v_mfma_f32_16x16x32_bf16 v[32:35], v[170:173], v[198:201], v[32:35]
	v_mfma_f32_16x16x32_bf16 v[20:23], v[152:155], v[206:209], v[20:23]
	v_mfma_f32_16x16x32_bf16 v[16:19], v[170:173], v[206:209], v[16:19]
	v_mfma_f32_16x16x32_bf16 v[60:63], v[166:169], v[128:131], v[60:63]
	v_mfma_f32_16x16x32_bf16 v[56:59], v[182:185], v[128:131], v[56:59]
	v_mfma_f32_16x16x32_bf16 v[44:47], v[166:169], v[186:189], v[44:47]
	v_mfma_f32_16x16x32_bf16 v[40:43], v[182:185], v[186:189], v[40:43]
	v_mfma_f32_16x16x32_bf16 v[28:31], v[166:169], v[194:197], v[28:31]
	v_mfma_f32_16x16x32_bf16 v[24:27], v[182:185], v[194:197], v[24:27]
	v_mfma_f32_16x16x32_bf16 v[12:15], v[166:169], v[202:205], v[12:15]
	v_mfma_f32_16x16x32_bf16 v[8:11], v[182:185], v[202:205], v[8:11]
	v_mfma_f32_16x16x32_bf16 v[60:63], v[162:165], v[132:135], v[60:63]
	v_mfma_f32_16x16x32_bf16 v[56:59], v[178:181], v[132:135], v[56:59]
	v_mfma_f32_16x16x32_bf16 v[44:47], v[162:165], v[190:193], v[44:47]
	v_mfma_f32_16x16x32_bf16 v[40:43], v[178:181], v[190:193], v[40:43]
	v_mfma_f32_16x16x32_bf16 v[28:31], v[162:165], v[198:201], v[28:31]
	v_mfma_f32_16x16x32_bf16 v[24:27], v[178:181], v[198:201], v[24:27]
	v_mfma_f32_16x16x32_bf16 v[12:15], v[162:165], v[206:209], v[12:15]
	v_mfma_f32_16x16x32_bf16 v[8:11], v[178:181], v[206:209], v[8:11]
	v_cndmask_b32_e64 v128, 0, 1, s[76:77]
	v_cmp_ne_u32_e64 s[40:41], 1, v128
	s_andn2_b64 vcc, exec, s[76:77]
	s_mov_b64 s[66:67], -1
	s_cbranch_vccnz .LBB0_246
	v_mfma_f32_16x16x32_bf16 v[128:131], v[174:177], v[148:151], v[4:7]
	s_mov_b64 s[66:67], 0
	v_mfma_f32_16x16x32_bf16 v[132:135], v[182:185], v[148:151], v[0:3]
	v_mfma_f32_16x16x32_bf16 v[128:131], v[170:173], v[144:147], v[128:131]
	v_mfma_f32_16x16x32_bf16 v[132:135], v[178:181], v[144:147], v[132:135]

; #define PG8_STAGE(bufoff, gbase, voff) do { _Pragma("unroll") for (int _i = 0; _i < 2; ++_i) \
;         __builtin_amdgcn_global_load_lds((const GAS unsigned*)((const GAS char*)(gbase) + (voff)[_i]), (PG8_LAS unsigned*)(lds + (bufoff) + ldsw + _i * 8192), 16, 0, 0); } while (0)
; #define PG8_LDA(dst, b, h) do { _Pragma("unroll") for (int m = 0; m < 4; ++m) _Pragma("unroll") for (int k = 0; k < 2; ++k) dst[m][k] = *(const PG8_LAS bf16x8*)(lds + PG8_SA(b, h) + aoff + m * 2048 + k * 1024); } while (0)
; #define PG8_LDB(dst, b, h) do { _Pragma("unroll") for (int n = 0; n < 2; ++n) _Pragma("unroll") for (int k = 0; k < 2; ++k) dst[n][k] = *(const PG8_LAS bf16x8*)(lds + PG8_SB(b, h) + boff + n * 2048 + k * 1024); } while (0)
; #define PG8_MMA(ai, bj, At, Bt) do { __builtin_amdgcn_s_setprio(1); _Pragma("unroll") for (int m = 0; m < 4; ++m) _Pragma("unroll") for (int n = 0; n < 2; ++n) _Pragma("unroll") for (int k = 0; k < 2; ++k) \
;         acc[ai][bj][m][n] = __builtin_amdgcn_mfma_f32_16x16x32_bf16(Bt[n][k], At[m][k], acc[ai][bj][m][n], 0, 0, 0); __builtin_amdgcn_s_setprio(0); } while (0)
; #define PG8_WAIT_V(n) asm volatile("s_waitcnt vmcnt(" #n ")" ::: "memory")
; #define PG8_WAIT_L(n) asm volatile("s_waitcnt lgkmcnt(" #n ")" ::: "memory")
; #define PG8_BAR __builtin_amdgcn_s_barrier()
; #define PG8_SCHED __builtin_amdgcn_sched_barrier(0)
; #define PG8_STAGE(bufoff, gbase, voff) do { _Pragma("unroll") for (int _i = 0; _i < 2; ++_i) \
;         __builtin_amdgcn_global_load_lds((const GAS unsigned*)((const GAS char*)(gbase) + (voff)[_i]), (PG8_LAS unsigned*)(lds + (bufoff) + ldsw + _i * 8192), 16, 0, 0); } while (0)
; #define PG8_WAIT_V(n) asm volatile("s_waitcnt vmcnt(" #n ")" ::: "memory")
; #define PG8_BAR __builtin_amdgcn_s_barrier()
; template <class Epi, class Sched>
; __device__ __forceinline__ void gemm_phase_strip(PG8_LAS unsigned char* lds, PG8_LAS unsigned char* slds, PG8_LAS unsigned char* pf, const Gemm g, const Sched& S, const Epi& E, int wv) {
;     ...
;             PG8_WAIT_V(8); PG8_WAIT_L(0); PG8_BAR; PG8_MMA(1, 0, At, B0); PG8_MMA(1, 1, At, B1); PG8_MMA_S(); PG8_BAR; PG8_SCHED;
;             PG8_LDB(B0, 1, 0); PG8_LDB(B1, 1, 1); PG8_SCHED; PG8_LDA(At, 1, 0); PG8_STAGE(PG8_SA(0, 1), a2 + (Sched::SPLIT ? ((last && has_next) ? (nxt.kh > 0 ? -(long)hstepA : (long)hstepA) : hsA) : (long)hstepA), voffA); PG8_STAGE_S(sq ^ 4096u, s2);
.LBB0_248:
	s_barrier
	s_nop 3
	v_add_u32_e32 v0, 0, v247
	v_add_u32_e32 v1, 0x18000, v0
	v_add_u32_e32 v0, 0x1c000, v0
	ds_read_b128 v[156:159], v1
	ds_read_b128 v[152:155], v1 offset:1024
	ds_read_b128 v[174:177], v1 offset:2048
	ds_read_b128 v[170:173], v1 offset:3072
	ds_read_b128 v[166:169], v0
	ds_read_b128 v[162:165], v0 offset:1024
	ds_read_b128 v[182:185], v0 offset:2048
	ds_read_b128 v[178:181], v0 offset:3072
	s_and_b64 s[66:67], s[68:69], s[2:3]
	s_and_b64 s[66:67], s[66:67], exec
	s_cselect_b32 s66, s8, s12
	s_cselect_b32 s25, s9, s13
	s_add_u32 s28, s28, s66
	s_addc_u32 s29, s29, s25
	s_mov_b32 m0, s54
	v_lshl_add_u64 v[144:145], s[28:29], 0, v[214:215]
	ds_read_b128 v[202:205], v250 offset:32768
	ds_read_b128 v[206:209], v250 offset:33792
	ds_read_b128 v[194:197], v250 offset:34816
	ds_read_b128 v[198:201], v250 offset:35840
	ds_read_b128 v[186:189], v250 offset:36864
	ds_read_b128 v[190:193], v250 offset:37888
	ds_read_b128 v[0:3], v250 offset:38912
	ds_read_b128 v[4:7], v250 offset:39936
	global_load_lds_dwordx4 v[144:145], off
	v_lshl_add_u64 v[144:145], s[28:29], 0, v[218:219]
	s_mov_b32 m0, s55
	s_nop 0
	global_load_lds_dwordx4 v[144:145], off
	v_mov_b32_e32 v144, v244
	s_and_saveexec_b64 s[28:29], s[34:35]
	s_cbranch_execz .LBB0_250
	s_add_u32 s25, s22, s94
	s_addc_u32 s66, s23, s95
	s_and_b64 s[2:3], s[2:3], exec
	s_cselect_b32 s3, s31, s66
	s_cselect_b32 s2, s30, s25
	s_xor_b32 s25, s57, 0x1000
	s_add_i32 m0, s56, s25
	s_nop 0
	global_load_lds_dwordx4 v144, s[2:3]
; #define PG8_STAGE(bufoff, gbase, voff) do { _Pragma("unroll") for (int _i = 0; _i < 2; ++_i) \
;         __builtin_amdgcn_global_load_lds((const GAS unsigned*)((const GAS char*)(gbase) + (voff)[_i]), (PG8_LAS unsigned*)(lds + (bufoff) + ldsw + _i * 8192), 16, 0, 0); } while (0)
; #define PG8_LDA(dst, b, h) do { _Pragma("unroll") for (int m = 0; m < 4; ++m) _Pragma("unroll") for (int k = 0; k < 2; ++k) dst[m][k] = *(const PG8_LAS bf16x8*)(lds + PG8_SA(b, h) + aoff + m * 2048 + k * 1024); } while (0)
; #define PG8_MMA(ai, bj, At, Bt) do { __builtin_amdgcn_s_setprio(1); _Pragma("unroll") for (int m = 0; m < 4; ++m) _Pragma("unroll") for (int n = 0; n < 2; ++n) _Pragma("unroll") for (int k = 0; k < 2; ++k) \
;         acc[ai][bj][m][n] = __builtin_amdgcn_mfma_f32_16x16x32_bf16(Bt[n][k], At[m][k], acc[ai][bj][m][n], 0, 0, 0); __builtin_amdgcn_s_setprio(0); } while (0)
; #define PG8_WAIT_V(n) asm volatile("s_waitcnt vmcnt(" #n ")" ::: "memory")
; #define PG8_WAIT_L(n) asm volatile("s_waitcnt lgkmcnt(" #n ")" ::: "memory")
; #define PG8_BAR __builtin_amdgcn_s_barrier()
; #define PG8_SCHED __builtin_amdgcn_sched_barrier(0)
; #define PG8_STAGE(bufoff, gbase, voff) do { _Pragma("unroll") for (int _i = 0; _i < 2; ++_i) \
;         __builtin_amdgcn_global_load_lds((const GAS unsigned*)((const GAS char*)(gbase) + (voff)[_i]), (PG8_LAS unsigned*)(lds + (bufoff) + ldsw + _i * 8192), 16, 0, 0); } while (0)
; #define PG8_LDA(dst, b, h) do { _Pragma("unroll") for (int m = 0; m < 4; ++m) _Pragma("unroll") for (int k = 0; k < 2; ++k) dst[m][k] = *(const PG8_LAS bf16x8*)(lds + PG8_SA(b, h) + aoff + m * 2048 + k * 1024); } while (0)
; #define PG8_WAIT_V(n) asm volatile("s_waitcnt vmcnt(" #n ")" ::: "memory")
; template <class Epi, class Sched>
; __device__ __forceinline__ void gemm_phase_strip(PG8_LAS unsigned char* lds, PG8_LAS unsigned char* slds, PG8_LAS unsigned char* pf, const Gemm g, const Sched& S, const Epi& E, int wv) {
;     ...
;             PG8_WAIT_V(9); PG8_WAIT_L(0); PG8_BAR; PG8_MMA(0, 0, At, B0); PG8_MMA(0, 1, At, B1); PG8_BAR; PG8_SCHED;
;             PG8_LDA(At, 1, 1); PG8_LDS_S(As, sq + 2048u); PG8_STAGE(PG8_SB(1, 0), b3, voffB); PG8_STAGE(PG8_SB(1, 1), b3 + hstepB, voffB); PG8_STAGE(PG8_SA(1, 0), a3, voffA);
;             PG8_WAIT_V(9); PG8_WAIT_L(0); PG8_BAR; PG8_MMA(1, 0, At, B0); PG8_MMA(1, 1, At, B1); PG8_MMA_S(); PG8_BAR; PG8_SCHED;
.LBB0_250:
	s_or_b64 exec, exec, s[28:29]
	s_waitcnt vmcnt(9)
	s_waitcnt lgkmcnt(0)
	s_barrier
	s_waitcnt lgkmcnt(0)
	v_mfma_f32_16x16x32_bf16 v[136:139], v[156:159], v[202:205], v[136:139]
	v_mfma_f32_16x16x32_bf16 v[148:151], v[152:155], v[206:209], v[136:139]
	v_mfma_f32_16x16x32_bf16 v[136:139], v[174:177], v[202:205], v[140:143]
	v_mfma_f32_16x16x32_bf16 v[116:119], v[156:159], v[194:197], v[116:119]
	v_mfma_f32_16x16x32_bf16 v[112:115], v[174:177], v[194:197], v[112:115]
	v_mfma_f32_16x16x32_bf16 v[100:103], v[156:159], v[186:189], v[100:103]
	v_mfma_f32_16x16x32_bf16 v[96:99], v[174:177], v[186:189], v[96:99]
	v_mfma_f32_16x16x32_bf16 v[84:87], v[156:159], v[0:3], v[84:87]
	v_mfma_f32_16x16x32_bf16 v[80:83], v[174:177], v[0:3], v[80:83]
	v_mfma_f32_16x16x32_bf16 v[144:147], v[170:173], v[206:209], v[136:139]
	v_mfma_f32_16x16x32_bf16 v[116:119], v[152:155], v[198:201], v[116:119]
	v_mfma_f32_16x16x32_bf16 v[112:115], v[170:173], v[198:201], v[112:115]
	v_mfma_f32_16x16x32_bf16 v[100:103], v[152:155], v[190:193], v[100:103]
	v_mfma_f32_16x16x32_bf16 v[96:99], v[170:173], v[190:193], v[96:99]
	v_mfma_f32_16x16x32_bf16 v[84:87], v[152:155], v[4:7], v[84:87]
	v_mfma_f32_16x16x32_bf16 v[80:83], v[170:173], v[4:7], v[80:83]
	v_mfma_f32_16x16x32_bf16 v[124:127], v[166:169], v[202:205], v[124:127]
	v_mfma_f32_16x16x32_bf16 v[120:123], v[182:185], v[202:205], v[120:123]
	v_mfma_f32_16x16x32_bf16 v[108:111], v[166:169], v[194:197], v[108:111]
	v_mfma_f32_16x16x32_bf16 v[104:107], v[182:185], v[194:197], v[104:107]
	v_mfma_f32_16x16x32_bf16 v[92:95], v[166:169], v[186:189], v[92:95]
	v_mfma_f32_16x16x32_bf16 v[88:91], v[182:185], v[186:189], v[88:91]
	v_mfma_f32_16x16x32_bf16 v[76:79], v[166:169], v[0:3], v[76:79]
	v_mfma_f32_16x16x32_bf16 v[0:3], v[182:185], v[0:3], v[72:75]
	v_mfma_f32_16x16x32_bf16 v[124:127], v[162:165], v[206:209], v[124:127]
	v_mfma_f32_16x16x32_bf16 v[120:123], v[178:181], v[206:209], v[120:123]
	v_mfma_f32_16x16x32_bf16 v[108:111], v[162:165], v[198:201], v[108:111]
	v_mfma_f32_16x16x32_bf16 v[104:107], v[178:181], v[198:201], v[104:107]
	v_mfma_f32_16x16x32_bf16 v[92:95], v[162:165], v[190:193], v[92:95]
	v_mfma_f32_16x16x32_bf16 v[88:91], v[178:181], v[190:193], v[88:91]
	v_mfma_f32_16x16x32_bf16 v[76:79], v[162:165], v[4:7], v[76:79]
	v_mfma_f32_16x16x32_bf16 v[72:75], v[178:181], v[4:7], v[0:3]
	s_barrier
	s_mov_b32 m0, s93
	v_lshl_add_u64 v[230:231], v[230:231], 0, s[16:17]
	s_add_u32 s2, s44, 0x80080
	ds_read_b128 v[0:3], v250 offset:49152
	ds_read_b128 v[4:7], v250 offset:50176
	ds_read_b128 v[186:189], v250 offset:51200
	ds_read_b128 v[190:193], v250 offset:52224
	ds_read_b128 v[194:197], v250 offset:53248
	ds_read_b128 v[198:201], v250 offset:54272
	ds_read_b128 v[202:205], v250 offset:55296
	ds_read_b128 v[206:209], v250 offset:56320
	ds_read_b128 v[140:143], v160 offset:2048
	ds_read_b128 v[136:139], v251 offset:2048
	global_load_lds_dwordx4 v[230:231], off
	v_lshl_add_u64 v[230:231], v[232:233], 0, s[16:17]
	s_mov_b32 m0, s89
	s_addc_u32 s3, s45, 0
	global_load_lds_dwordx4 v[230:231], off
	v_lshl_add_u64 v[230:231], s[2:3], 0, v[216:217]
	s_mov_b32 m0, s88
	s_nop 0
	global_load_lds_dwordx4 v[230:231], off
	v_lshl_add_u64 v[230:231], s[2:3], 0, v[220:221]
	s_mov_b32 m0, s27
	s_nop 0
	global_load_lds_dwordx4 v[230:231], off
	v_lshl_add_u64 v[230:231], v[234:235], 0, s[16:17]
	s_mov_b32 m0, s78
	s_nop 0
	global_load_lds_dwordx4 v[230:231], off
	v_lshl_add_u64 v[230:231], v[236:237], 0, s[16:17]
	s_mov_b32 m0, s79
	s_nop 0
	global_load_lds_dwordx4 v[230:231], off
	s_waitcnt vmcnt(9)
	s_waitcnt lgkmcnt(0)
	s_barrier
	s_waitcnt lgkmcnt(0)
	v_mfma_f32_16x16x32_bf16 v[68:71], v[156:159], v[0:3], v[68:71]
	v_mfma_f32_16x16x32_bf16 v[64:67], v[174:177], v[0:3], v[64:67]
	v_mfma_f32_16x16x32_bf16 v[52:55], v[156:159], v[186:189], v[52:55]
	v_mfma_f32_16x16x32_bf16 v[48:51], v[174:177], v[186:189], v[48:51]
	v_mfma_f32_16x16x32_bf16 v[36:39], v[156:159], v[194:197], v[36:39]
	v_mfma_f32_16x16x32_bf16 v[32:35], v[174:177], v[194:197], v[32:35]
	v_mfma_f32_16x16x32_bf16 v[20:23], v[156:159], v[202:205], v[20:23]
	v_mfma_f32_16x16x32_bf16 v[16:19], v[174:177], v[202:205], v[16:19]
	v_mfma_f32_16x16x32_bf16 v[68:71], v[152:155], v[4:7], v[68:71]
	v_mfma_f32_16x16x32_bf16 v[64:67], v[170:173], v[4:7], v[64:67]
	v_mfma_f32_16x16x32_bf16 v[52:55], v[152:155], v[190:193], v[52:55]
	v_mfma_f32_16x16x32_bf16 v[48:51], v[170:173], v[190:193], v[48:51]
	v_mfma_f32_16x16x32_bf16 v[36:39], v[152:155], v[198:201], v[36:39]
	v_mfma_f32_16x16x32_bf16 v[32:35], v[170:173], v[198:201], v[32:35]
	v_mfma_f32_16x16x32_bf16 v[20:23], v[152:155], v[206:209], v[20:23]
	v_mfma_f32_16x16x32_bf16 v[16:19], v[170:173], v[206:209], v[16:19]
	v_mfma_f32_16x16x32_bf16 v[60:63], v[166:169], v[0:3], v[60:63]
	v_mfma_f32_16x16x32_bf16 v[0:3], v[182:185], v[0:3], v[56:59]
	v_mfma_f32_16x16x32_bf16 v[56:59], v[178:181], v[4:7], v[0:3]
	v_mfma_f32_16x16x32_bf16 v[0:3], v[166:169], v[186:189], v[44:47]
	v_mfma_f32_16x16x32_bf16 v[44:47], v[162:165], v[190:193], v[0:3]
	v_mfma_f32_16x16x32_bf16 v[0:3], v[182:185], v[186:189], v[40:43]
	v_mfma_f32_16x16x32_bf16 v[40:43], v[178:181], v[190:193], v[0:3]
	v_mfma_f32_16x16x32_bf16 v[0:3], v[166:169], v[194:197], v[28:31]
	v_mfma_f32_16x16x32_bf16 v[28:31], v[162:165], v[198:201], v[0:3]
	v_mfma_f32_16x16x32_bf16 v[0:3], v[182:185], v[194:197], v[24:27]
	v_mfma_f32_16x16x32_bf16 v[24:27], v[178:181], v[198:201], v[0:3]
	v_mfma_f32_16x16x32_bf16 v[0:3], v[166:169], v[202:205], v[12:15]
	v_mfma_f32_16x16x32_bf16 v[12:15], v[162:165], v[206:209], v[0:3]
	v_mfma_f32_16x16x32_bf16 v[0:3], v[182:185], v[202:205], v[8:11]
	v_mfma_f32_16x16x32_bf16 v[60:63], v[162:165], v[4:7], v[60:63]
	v_mfma_f32_16x16x32_bf16 v[8:11], v[178:181], v[206:209], v[0:3]
	s_and_b64 vcc, exec, s[40:41]
	s_mov_b64 s[2:3], -1
	s_cbranch_vccnz .LBB0_252
	v_mfma_f32_16x16x32_bf16 v[0:3], v[174:177], v[140:143], v[128:131]
	s_mov_b64 s[2:3], 0
	v_mfma_f32_16x16x32_bf16 v[174:177], v[182:185], v[140:143], v[132:135]
	v_mfma_f32_16x16x32_bf16 v[4:7], v[170:173], v[136:139], v[0:3]
	v_mfma_f32_16x16x32_bf16 v[0:3], v[178:181], v[136:139], v[174:177]

; #define PG8_STAGE(bufoff, gbase, voff) do { _Pragma("unroll") for (int _i = 0; _i < 2; ++_i) \
;         __builtin_amdgcn_global_load_lds((const GAS unsigned*)((const GAS char*)(gbase) + (voff)[_i]), (PG8_LAS unsigned*)(lds + (bufoff) + ldsw + _i * 8192), 16, 0, 0); } while (0)
; #define PG8_LDA(dst, b, h) do { _Pragma("unroll") for (int m = 0; m < 4; ++m) _Pragma("unroll") for (int k = 0; k < 2; ++k) dst[m][k] = *(const PG8_LAS bf16x8*)(lds + PG8_SA(b, h) + aoff + m * 2048 + k * 1024); } while (0)
; #define PG8_LDB(dst, b, h) do { _Pragma("unroll") for (int n = 0; n < 2; ++n) _Pragma("unroll") for (int k = 0; k < 2; ++k) dst[n][k] = *(const PG8_LAS bf16x8*)(lds + PG8_SB(b, h) + boff + n * 2048 + k * 1024); } while (0)
; #define PG8_MMA(ai, bj, At, Bt) do { __builtin_amdgcn_s_setprio(1); _Pragma("unroll") for (int m = 0; m < 4; ++m) _Pragma("unroll") for (int n = 0; n < 2; ++n) _Pragma("unroll") for (int k = 0; k < 2; ++k) \
;         acc[ai][bj][m][n] = __builtin_amdgcn_mfma_f32_16x16x32_bf16(Bt[n][k], At[m][k], acc[ai][bj][m][n], 0, 0, 0); __builtin_amdgcn_s_setprio(0); } while (0)
; #define PG8_WAIT_V(n) asm volatile("s_waitcnt vmcnt(" #n ")" ::: "memory")
; #define PG8_WAIT_L(n) asm volatile("s_waitcnt lgkmcnt(" #n ")" ::: "memory")
; #define PG8_BAR __builtin_amdgcn_s_barrier()
; #define PG8_SCHED __builtin_amdgcn_sched_barrier(0)
; #define PG8_STAGE(bufoff, gbase, voff) do { _Pragma("unroll") for (int _i = 0; _i < 2; ++_i) \
;         __builtin_amdgcn_global_load_lds((const GAS unsigned*)((const GAS char*)(gbase) + (voff)[_i]), (PG8_LAS unsigned*)(lds + (bufoff) + ldsw + _i * 8192), 16, 0, 0); } while (0)
; #define PG8_LDA(dst, b, h) do { _Pragma("unroll") for (int m = 0; m < 4; ++m) _Pragma("unroll") for (int k = 0; k < 2; ++k) dst[m][k] = *(const PG8_LAS bf16x8*)(lds + PG8_SA(b, h) + aoff + m * 2048 + k * 1024); } while (0)
; #define PG8_BAR __builtin_amdgcn_s_barrier()
; template <class Epi, class Sched>
; __device__ __forceinline__ void gemm_phase_strip(PG8_LAS unsigned char* lds, PG8_LAS unsigned char* slds, PG8_LAS unsigned char* pf, const Gemm g, const Sched& S, const Epi& E, int wv) {
;     ...
;             PG8_LDB(B0, 0, 0); PG8_LDB(B1, 0, 1); PG8_SCHED; PG8_LDA(At, 0, 0); PG8_STAGE(PG8_SA(1, 1), a1 + PG8_HS, voffA);
;             PG8_WAIT_V(8); PG8_WAIT_L(0); PG8_BAR; PG8_MMA(0, 0, At, B0); PG8_MMA(0, 1, At, B1); PG8_BAR; PG8_SCHED;
.LBB0_538:
	s_barrier
	s_xor_b32 s34, s34, 0x1000
	s_add_i32 s22, s22, 2
	s_add_u32 s68, s68, 0x100
	s_addc_u32 s69, s69, 0
	s_cmp_gt_u32 s22, 29
	s_cbranch_scc1 .LBB0_549
.LBB0_539:
	s_add_u32 s2, s66, s68
	s_addc_u32 s3, s67, s69
	s_add_u32 s23, s2, 0x100
	s_addc_u32 s28, s3, 0
	s_add_u32 s40, s57, s68
	s_addc_u32 s41, s65, s69
	s_add_i32 s74, 0, 0x10000
	s_add_i32 s75, 0, 0x14000
	v_add_u32_e32 v136, s74, v234
	ds_read_b128 v[148:151], v136
	ds_read_b128 v[144:147], v136 offset:1024
	ds_read_b128 v[166:169], v136 offset:2048
	ds_read_b128 v[162:165], v136 offset:3072
	v_add_u32_e32 v136, s75, v234
	ds_read_b128 v[156:159], v136
	ds_read_b128 v[152:155], v136 offset:1024
	ds_read_b128 v[174:177], v136 offset:2048
	ds_read_b128 v[170:173], v136 offset:3072
	s_cmpk_eq_i32 s68, 0xf00
	s_cselect_b64 s[2:3], -1, 0
	s_and_b64 s[24:25], s[2:3], exec
	s_cselect_b32 s29, s59, s28
	s_cselect_b32 s28, s58, s23
	s_cselect_b32 s73, s21, s41
	s_cselect_b32 s72, s51, s40
	v_lshl_add_u64 v[222:223], v[220:221], 0, s[68:69]
	s_add_i32 m0, s1, 0xc000
	ds_read_b128 v[136:139], v237
	ds_read_b128 v[140:143], v237 offset:1024
	ds_read_b128 v[178:181], v237 offset:2048
	ds_read_b128 v[182:185], v237 offset:3072
	ds_read_b128 v[186:189], v237 offset:4096
	ds_read_b128 v[190:193], v237 offset:5120
	ds_read_b128 v[194:197], v237 offset:6144
	ds_read_b128 v[198:201], v237 offset:7168
	global_load_lds_dwordx4 v[222:223], off
	v_lshl_add_u64 v[222:223], v[218:219], 0, s[68:69]
	s_add_i32 m0, s1, 0xe000
	s_nop 0
	global_load_lds_dwordx4 v[222:223], off
	s_waitcnt vmcnt(8)
	s_waitcnt lgkmcnt(0)
	s_barrier
	s_waitcnt lgkmcnt(0)
	v_mfma_f32_16x16x32_bf16 v[132:135], v[148:151], v[136:139], v[132:135]
	v_mfma_f32_16x16x32_bf16 v[128:131], v[166:169], v[136:139], v[128:131]
	v_mfma_f32_16x16x32_bf16 v[116:119], v[148:151], v[178:181], v[116:119]
	v_mfma_f32_16x16x32_bf16 v[112:115], v[166:169], v[178:181], v[112:115]
	v_mfma_f32_16x16x32_bf16 v[100:103], v[148:151], v[186:189], v[100:103]
	v_mfma_f32_16x16x32_bf16 v[96:99], v[166:169], v[186:189], v[96:99]
	v_mfma_f32_16x16x32_bf16 v[84:87], v[148:151], v[194:197], v[84:87]
	v_mfma_f32_16x16x32_bf16 v[80:83], v[166:169], v[194:197], v[80:83]
	v_mfma_f32_16x16x32_bf16 v[132:135], v[144:147], v[140:143], v[132:135]
	v_mfma_f32_16x16x32_bf16 v[128:131], v[162:165], v[140:143], v[128:131]
	v_mfma_f32_16x16x32_bf16 v[116:119], v[144:147], v[182:185], v[116:119]
	v_mfma_f32_16x16x32_bf16 v[112:115], v[162:165], v[182:185], v[112:115]
	v_mfma_f32_16x16x32_bf16 v[100:103], v[144:147], v[190:193], v[100:103]
	v_mfma_f32_16x16x32_bf16 v[96:99], v[162:165], v[190:193], v[96:99]
	v_mfma_f32_16x16x32_bf16 v[84:87], v[144:147], v[198:201], v[84:87]
	v_mfma_f32_16x16x32_bf16 v[80:83], v[162:165], v[198:201], v[80:83]
	v_mfma_f32_16x16x32_bf16 v[124:127], v[156:159], v[136:139], v[124:127]
	v_mfma_f32_16x16x32_bf16 v[120:123], v[174:177], v[136:139], v[120:123]
	v_mfma_f32_16x16x32_bf16 v[108:111], v[156:159], v[178:181], v[108:111]
	v_mfma_f32_16x16x32_bf16 v[104:107], v[174:177], v[178:181], v[104:107]
	v_mfma_f32_16x16x32_bf16 v[92:95], v[156:159], v[186:189], v[92:95]
	v_mfma_f32_16x16x32_bf16 v[88:91], v[174:177], v[186:189], v[88:91]
	v_mfma_f32_16x16x32_bf16 v[76:79], v[156:159], v[194:197], v[76:79]
	v_mfma_f32_16x16x32_bf16 v[72:75], v[174:177], v[194:197], v[72:75]
	v_mfma_f32_16x16x32_bf16 v[124:127], v[152:155], v[140:143], v[124:127]
	v_mfma_f32_16x16x32_bf16 v[120:123], v[170:173], v[140:143], v[120:123]
	v_mfma_f32_16x16x32_bf16 v[108:111], v[152:155], v[182:185], v[108:111]
	v_mfma_f32_16x16x32_bf16 v[104:107], v[170:173], v[182:185], v[104:107]
	v_mfma_f32_16x16x32_bf16 v[92:95], v[152:155], v[190:193], v[92:95]
	v_mfma_f32_16x16x32_bf16 v[88:91], v[170:173], v[190:193], v[88:91]
	v_mfma_f32_16x16x32_bf16 v[76:79], v[152:155], v[198:201], v[76:79]
	v_mfma_f32_16x16x32_bf16 v[72:75], v[170:173], v[198:201], v[72:75]
	s_barrier
; #define PG8_STAGE(bufoff, gbase, voff) do { _Pragma("unroll") for (int _i = 0; _i < 2; ++_i) \
;         __builtin_amdgcn_global_load_lds((const GAS unsigned*)((const GAS char*)(gbase) + (voff)[_i]), (PG8_LAS unsigned*)(lds + (bufoff) + ldsw + _i * 8192), 16, 0, 0); } while (0)
; #define PG8_LDA(dst, b, h) do { _Pragma("unroll") for (int m = 0; m < 4; ++m) _Pragma("unroll") for (int k = 0; k < 2; ++k) dst[m][k] = *(const PG8_LAS bf16x8*)(lds + PG8_SA(b, h) + aoff + m * 2048 + k * 1024); } while (0)
; #define PG8_MMA(ai, bj, At, Bt) do { __builtin_amdgcn_s_setprio(1); _Pragma("unroll") for (int m = 0; m < 4; ++m) _Pragma("unroll") for (int n = 0; n < 2; ++n) _Pragma("unroll") for (int k = 0; k < 2; ++k) \
;         acc[ai][bj][m][n] = __builtin_amdgcn_mfma_f32_16x16x32_bf16(Bt[n][k], At[m][k], acc[ai][bj][m][n], 0, 0, 0); __builtin_amdgcn_s_setprio(0); } while (0)
; #define PG8_WAIT_V(n) asm volatile("s_waitcnt vmcnt(" #n ")" ::: "memory")
; #define PG8_WAIT_L(n) asm volatile("s_waitcnt lgkmcnt(" #n ")" ::: "memory")
; #define PG8_BAR __builtin_amdgcn_s_barrier()
; #define PG8_SCHED __builtin_amdgcn_sched_barrier(0)
; #define PG8_STAGE(bufoff, gbase, voff) do { _Pragma("unroll") for (int _i = 0; _i < 2; ++_i) \
;         __builtin_amdgcn_global_load_lds((const GAS unsigned*)((const GAS char*)(gbase) + (voff)[_i]), (PG8_LAS unsigned*)(lds + (bufoff) + ldsw + _i * 8192), 16, 0, 0); } while (0)
; #define PG8_LDA(dst, b, h) do { _Pragma("unroll") for (int m = 0; m < 4; ++m) _Pragma("unroll") for (int k = 0; k < 2; ++k) dst[m][k] = *(const PG8_LAS bf16x8*)(lds + PG8_SA(b, h) + aoff + m * 2048 + k * 1024); } while (0)
; #define PG8_LDS_S(dst, boffs) do { dst[0] = *(const PG8_LAS bf16x8*)(slds + (boffs) + soff0); dst[1] = *(const PG8_LAS bf16x8*)(slds + (boffs) + (soff0 ^ 64)); } while (0)
; #define PG8_BAR __builtin_amdgcn_s_barrier()
; template <class Epi, class Sched>
; __device__ __forceinline__ void gemm_phase_strip(PG8_LAS unsigned char* lds, PG8_LAS unsigned char* slds, PG8_LAS unsigned char* pf, const Gemm g, const Sched& S, const Epi& E, int wv) {
;     ...
;             PG8_LDA(At, 0, 1); PG8_LDS_S(As, sq); PG8_STAGE(PG8_SB(0, 0), b2, voffB); PG8_STAGE(PG8_SB(0, 1), b2 + hstepB, voffB); PG8_STAGE(PG8_SA(0, 0), a2, voffA);
;             PG8_WAIT_V(8); PG8_WAIT_L(0); PG8_BAR; PG8_MMA(1, 0, At, B0); PG8_MMA(1, 1, At, B1); PG8_MMA_S(); PG8_BAR; PG8_SCHED;
	s_add_i32 s23, s34, 0
	s_add_i32 s23, s23, 0x21000
	v_add_u32_e32 v160, s23, v235
	v_add_u32_e32 v242, s23, v236
	s_add_i32 s23, s74, s79
	v_lshl_add_u64 v[222:223], s[72:73], 0, v[204:205]
	s_mov_b32 m0, s23
	ds_read_b128 v[136:139], v237 offset:16384
	ds_read_b128 v[140:143], v237 offset:17408
	ds_read_b128 v[186:189], v237 offset:18432
	ds_read_b128 v[190:193], v237 offset:19456
	ds_read_b128 v[194:197], v237 offset:20480
	ds_read_b128 v[198:201], v237 offset:21504
	ds_read_b128 v[244:247], v237 offset:22528
	ds_read_b128 v[248:251], v237 offset:23552
	ds_read_b128 v[182:185], v160
	ds_read_b128 v[178:181], v242
	global_load_lds_dwordx4 v[222:223], off
	s_add_i32 m0, s23, 0x2000
	s_add_u32 s24, s72, 0x80000
	v_lshl_add_u64 v[224:225], s[72:73], 0, v[208:209]
	s_addc_u32 s25, s73, 0
	s_add_i32 s23, s75, s79
	global_load_lds_dwordx4 v[224:225], off
	v_lshl_add_u64 v[226:227], s[24:25], 0, v[204:205]
	s_mov_b32 m0, s23
	v_lshl_add_u64 v[228:229], s[28:29], 0, v[206:207]
	global_load_lds_dwordx4 v[226:227], off
	v_lshl_add_u64 v[226:227], s[24:25], 0, v[208:209]
	s_add_i32 m0, s23, 0x2000
	s_nop 0
	global_load_lds_dwordx4 v[226:227], off
	v_lshl_add_u64 v[226:227], s[28:29], 0, v[202:203]
	s_mov_b32 m0, s1
	s_nop 0
	global_load_lds_dwordx4 v[226:227], off
	s_mov_b32 m0, s80
	s_nop 0
	global_load_lds_dwordx4 v[228:229], off
	s_waitcnt vmcnt(8)
	s_waitcnt lgkmcnt(0)
	s_barrier
	s_waitcnt lgkmcnt(0)
	v_mfma_f32_16x16x32_bf16 v[68:71], v[148:151], v[136:139], v[68:71]
	v_mfma_f32_16x16x32_bf16 v[64:67], v[166:169], v[136:139], v[64:67]
	v_mfma_f32_16x16x32_bf16 v[52:55], v[148:151], v[186:189], v[52:55]
	v_mfma_f32_16x16x32_bf16 v[48:51], v[166:169], v[186:189], v[48:51]
	v_mfma_f32_16x16x32_bf16 v[36:39], v[148:151], v[194:197], v[36:39]
	v_mfma_f32_16x16x32_bf16 v[32:35], v[166:169], v[194:197], v[32:35]
	v_mfma_f32_16x16x32_bf16 v[20:23], v[148:151], v[244:247], v[20:23]
	v_mfma_f32_16x16x32_bf16 v[16:19], v[166:169], v[244:247], v[16:19]
	v_mfma_f32_16x16x32_bf16 v[68:71], v[144:147], v[140:143], v[68:71]
	v_mfma_f32_16x16x32_bf16 v[64:67], v[162:165], v[140:143], v[64:67]
	v_mfma_f32_16x16x32_bf16 v[52:55], v[144:147], v[190:193], v[52:55]
	v_mfma_f32_16x16x32_bf16 v[48:51], v[162:165], v[190:193], v[48:51]
	v_mfma_f32_16x16x32_bf16 v[36:39], v[144:147], v[198:201], v[36:39]
	v_mfma_f32_16x16x32_bf16 v[32:35], v[162:165], v[198:201], v[32:35]
	v_mfma_f32_16x16x32_bf16 v[20:23], v[144:147], v[248:251], v[20:23]
	v_mfma_f32_16x16x32_bf16 v[16:19], v[162:165], v[248:251], v[16:19]
	v_mfma_f32_16x16x32_bf16 v[60:63], v[156:159], v[136:139], v[60:63]
	v_mfma_f32_16x16x32_bf16 v[56:59], v[174:177], v[136:139], v[56:59]
	v_mfma_f32_16x16x32_bf16 v[44:47], v[156:159], v[186:189], v[44:47]
	v_mfma_f32_16x16x32_bf16 v[40:43], v[174:177], v[186:189], v[40:43]
	v_mfma_f32_16x16x32_bf16 v[28:31], v[156:159], v[194:197], v[28:31]
	v_mfma_f32_16x16x32_bf16 v[24:27], v[174:177], v[194:197], v[24:27]
	v_mfma_f32_16x16x32_bf16 v[12:15], v[156:159], v[244:247], v[12:15]
	v_mfma_f32_16x16x32_bf16 v[8:11], v[174:177], v[244:247], v[8:11]
	v_mfma_f32_16x16x32_bf16 v[60:63], v[152:155], v[140:143], v[60:63]
	v_mfma_f32_16x16x32_bf16 v[56:59], v[170:173], v[140:143], v[56:59]
	v_mfma_f32_16x16x32_bf16 v[44:47], v[152:155], v[190:193], v[44:47]
	v_mfma_f32_16x16x32_bf16 v[40:43], v[170:173], v[190:193], v[40:43]
	v_mfma_f32_16x16x32_bf16 v[28:31], v[152:155], v[198:201], v[28:31]
	v_mfma_f32_16x16x32_bf16 v[24:27], v[170:173], v[198:201], v[24:27]
	v_mfma_f32_16x16x32_bf16 v[12:15], v[152:155], v[248:251], v[12:15]
	v_mfma_f32_16x16x32_bf16 v[8:11], v[170:173], v[248:251], v[8:11]
	v_cndmask_b32_e64 v136, 0, 1, s[42:43]
	v_cmp_ne_u32_e64 s[40:41], 1, v136
	s_andn2_b64 vcc, exec, s[42:43]
	s_mov_b64 s[74:75], -1
	s_cbranch_vccnz .LBB0_541
	v_mfma_f32_16x16x32_bf16 v[136:139], v[166:169], v[182:185], v[4:7]
	s_mov_b64 s[74:75], 0
	v_mfma_f32_16x16x32_bf16 v[140:143], v[174:177], v[182:185], v[0:3]
	v_mfma_f32_16x16x32_bf16 v[136:139], v[162:165], v[178:181], v[136:139]
	v_mfma_f32_16x16x32_bf16 v[140:143], v[170:173], v[178:181], v[140:143]

; #define PG8_STAGE(bufoff, gbase, voff) do { _Pragma("unroll") for (int _i = 0; _i < 2; ++_i) \
;         __builtin_amdgcn_global_load_lds((const GAS unsigned*)((const GAS char*)(gbase) + (voff)[_i]), (PG8_LAS unsigned*)(lds + (bufoff) + ldsw + _i * 8192), 16, 0, 0); } while (0)
; #define PG8_LDA(dst, b, h) do { _Pragma("unroll") for (int m = 0; m < 4; ++m) _Pragma("unroll") for (int k = 0; k < 2; ++k) dst[m][k] = *(const PG8_LAS bf16x8*)(lds + PG8_SA(b, h) + aoff + m * 2048 + k * 1024); } while (0)
; #define PG8_LDB(dst, b, h) do { _Pragma("unroll") for (int n = 0; n < 2; ++n) _Pragma("unroll") for (int k = 0; k < 2; ++k) dst[n][k] = *(const PG8_LAS bf16x8*)(lds + PG8_SB(b, h) + boff + n * 2048 + k * 1024); } while (0)
; #define PG8_MMA(ai, bj, At, Bt) do { __builtin_amdgcn_s_setprio(1); _Pragma("unroll") for (int m = 0; m < 4; ++m) _Pragma("unroll") for (int n = 0; n < 2; ++n) _Pragma("unroll") for (int k = 0; k < 2; ++k) \
;         acc[ai][bj][m][n] = __builtin_amdgcn_mfma_f32_16x16x32_bf16(Bt[n][k], At[m][k], acc[ai][bj][m][n], 0, 0, 0); __builtin_amdgcn_s_setprio(0); } while (0)
; #define PG8_WAIT_V(n) asm volatile("s_waitcnt vmcnt(" #n ")" ::: "memory")
; #define PG8_WAIT_L(n) asm volatile("s_waitcnt lgkmcnt(" #n ")" ::: "memory")
; #define PG8_BAR __builtin_amdgcn_s_barrier()
; #define PG8_SCHED __builtin_amdgcn_sched_barrier(0)
; #define PG8_STAGE(bufoff, gbase, voff) do { _Pragma("unroll") for (int _i = 0; _i < 2; ++_i) \
;         __builtin_amdgcn_global_load_lds((const GAS unsigned*)((const GAS char*)(gbase) + (voff)[_i]), (PG8_LAS unsigned*)(lds + (bufoff) + ldsw + _i * 8192), 16, 0, 0); } while (0)
; #define PG8_WAIT_V(n) asm volatile("s_waitcnt vmcnt(" #n ")" ::: "memory")
; #define PG8_BAR __builtin_amdgcn_s_barrier()
; template <class Epi, class Sched>
; __device__ __forceinline__ void gemm_phase_strip(PG8_LAS unsigned char* lds, PG8_LAS unsigned char* slds, PG8_LAS unsigned char* pf, const Gemm g, const Sched& S, const Epi& E, int wv) {
;     ...
;             PG8_WAIT_V(8); PG8_WAIT_L(0); PG8_BAR; PG8_MMA(1, 0, At, B0); PG8_MMA(1, 1, At, B1); PG8_MMA_S(); PG8_BAR; PG8_SCHED;
;             PG8_LDB(B0, 1, 0); PG8_LDB(B1, 1, 1); PG8_SCHED; PG8_LDA(At, 1, 0); PG8_STAGE(PG8_SA(0, 1), a2 + (Sched::SPLIT ? ((last && has_next) ? (nxt.kh > 0 ? -(long)hstepA : (long)hstepA) : hsA) : (long)hstepA), voffA); PG8_STAGE_S(sq ^ 4096u, s2);
.LBB0_543:
	s_barrier
	s_nop 3
	v_add_u32_e32 v0, 0, v234
	v_add_u32_e32 v1, 0x18000, v0
	v_add_u32_e32 v0, 0x1c000, v0
	ds_read_b128 v[148:151], v1
	ds_read_b128 v[144:147], v1 offset:1024
	ds_read_b128 v[166:169], v1 offset:2048
	ds_read_b128 v[162:165], v1 offset:3072
	ds_read_b128 v[156:159], v0
	ds_read_b128 v[152:155], v0 offset:1024
	ds_read_b128 v[174:177], v0 offset:2048
	ds_read_b128 v[170:173], v0 offset:3072
	s_add_u32 s24, s28, 0x80000
	s_addc_u32 s25, s29, 0
	s_mov_b32 m0, s81
	v_lshl_add_u64 v[244:245], s[24:25], 0, v[202:203]
	ds_read_b128 v[194:197], v237 offset:32768
	ds_read_b128 v[198:201], v237 offset:33792
	ds_read_b128 v[186:189], v237 offset:34816
	ds_read_b128 v[190:193], v237 offset:35840
	ds_read_b128 v[178:181], v237 offset:36864
	ds_read_b128 v[182:185], v237 offset:37888
	ds_read_b128 v[0:3], v237 offset:38912
	ds_read_b128 v[4:7], v237 offset:39936
	global_load_lds_dwordx4 v[244:245], off
	v_lshl_add_u64 v[244:245], s[24:25], 0, v[206:207]
	s_mov_b32 m0, s83
	v_mov_b32_e32 v243, v231
	global_load_lds_dwordx4 v[244:245], off
	s_and_saveexec_b64 s[28:29], s[36:37]
	s_cbranch_execz .LBB0_545
	s_add_u32 s23, s53, s68
	s_addc_u32 s24, s55, s69
	s_and_b64 s[2:3], s[2:3], exec
	s_cselect_b32 s3, s61, s24
	s_cselect_b32 s2, s60, s23
	s_xor_b32 s23, s34, 0x1000
	s_add_i32 m0, s91, s23
	s_nop 0
	global_load_lds_dwordx4 v243, s[2:3]
; #define PG8_STAGE(bufoff, gbase, voff) do { _Pragma("unroll") for (int _i = 0; _i < 2; ++_i) \
;         __builtin_amdgcn_global_load_lds((const GAS unsigned*)((const GAS char*)(gbase) + (voff)[_i]), (PG8_LAS unsigned*)(lds + (bufoff) + ldsw + _i * 8192), 16, 0, 0); } while (0)
; #define PG8_LDA(dst, b, h) do { _Pragma("unroll") for (int m = 0; m < 4; ++m) _Pragma("unroll") for (int k = 0; k < 2; ++k) dst[m][k] = *(const PG8_LAS bf16x8*)(lds + PG8_SA(b, h) + aoff + m * 2048 + k * 1024); } while (0)
; #define PG8_MMA(ai, bj, At, Bt) do { __builtin_amdgcn_s_setprio(1); _Pragma("unroll") for (int m = 0; m < 4; ++m) _Pragma("unroll") for (int n = 0; n < 2; ++n) _Pragma("unroll") for (int k = 0; k < 2; ++k) \
;         acc[ai][bj][m][n] = __builtin_amdgcn_mfma_f32_16x16x32_bf16(Bt[n][k], At[m][k], acc[ai][bj][m][n], 0, 0, 0); __builtin_amdgcn_s_setprio(0); } while (0)
; #define PG8_WAIT_V(n) asm volatile("s_waitcnt vmcnt(" #n ")" ::: "memory")
; #define PG8_WAIT_L(n) asm volatile("s_waitcnt lgkmcnt(" #n ")" ::: "memory")
; #define PG8_BAR __builtin_amdgcn_s_barrier()
; #define PG8_SCHED __builtin_amdgcn_sched_barrier(0)
; #define PG8_STAGE(bufoff, gbase, voff) do { _Pragma("unroll") for (int _i = 0; _i < 2; ++_i) \
;         __builtin_amdgcn_global_load_lds((const GAS unsigned*)((const GAS char*)(gbase) + (voff)[_i]), (PG8_LAS unsigned*)(lds + (bufoff) + ldsw + _i * 8192), 16, 0, 0); } while (0)
; #define PG8_LDA(dst, b, h) do { _Pragma("unroll") for (int m = 0; m < 4; ++m) _Pragma("unroll") for (int k = 0; k < 2; ++k) dst[m][k] = *(const PG8_LAS bf16x8*)(lds + PG8_SA(b, h) + aoff + m * 2048 + k * 1024); } while (0)
; #define PG8_WAIT_V(n) asm volatile("s_waitcnt vmcnt(" #n ")" ::: "memory")
; template <class Epi, class Sched>
; __device__ __forceinline__ void gemm_phase_strip(PG8_LAS unsigned char* lds, PG8_LAS unsigned char* slds, PG8_LAS unsigned char* pf, const Gemm g, const Sched& S, const Epi& E, int wv) {
;     ...
;             PG8_WAIT_V(9); PG8_WAIT_L(0); PG8_BAR; PG8_MMA(0, 0, At, B0); PG8_MMA(0, 1, At, B1); PG8_BAR; PG8_SCHED;
;             PG8_LDA(At, 1, 1); PG8_LDS_S(As, sq + 2048u); PG8_STAGE(PG8_SB(1, 0), b3, voffB); PG8_STAGE(PG8_SB(1, 1), b3 + hstepB, voffB); PG8_STAGE(PG8_SA(1, 0), a3, voffA);
;             PG8_WAIT_V(9); PG8_WAIT_L(0); PG8_BAR; PG8_MMA(1, 0, At, B0); PG8_MMA(1, 1, At, B1); PG8_MMA_S(); PG8_BAR; PG8_SCHED;
.LBB0_545:
	s_or_b64 exec, exec, s[28:29]
	s_waitcnt vmcnt(9)
	s_waitcnt lgkmcnt(0)
	s_barrier
	s_waitcnt lgkmcnt(0)
	v_mfma_f32_16x16x32_bf16 v[132:135], v[148:151], v[194:197], v[132:135]
	v_mfma_f32_16x16x32_bf16 v[128:131], v[166:169], v[194:197], v[128:131]
	v_mfma_f32_16x16x32_bf16 v[116:119], v[148:151], v[186:189], v[116:119]
	v_mfma_f32_16x16x32_bf16 v[112:115], v[166:169], v[186:189], v[112:115]
	v_mfma_f32_16x16x32_bf16 v[100:103], v[148:151], v[178:181], v[100:103]
	v_mfma_f32_16x16x32_bf16 v[96:99], v[166:169], v[178:181], v[96:99]
	v_mfma_f32_16x16x32_bf16 v[84:87], v[148:151], v[0:3], v[84:87]
	v_mfma_f32_16x16x32_bf16 v[80:83], v[166:169], v[0:3], v[80:83]
	v_mfma_f32_16x16x32_bf16 v[132:135], v[144:147], v[198:201], v[132:135]
	v_mfma_f32_16x16x32_bf16 v[128:131], v[162:165], v[198:201], v[128:131]
	v_mfma_f32_16x16x32_bf16 v[116:119], v[144:147], v[190:193], v[116:119]
	v_mfma_f32_16x16x32_bf16 v[112:115], v[162:165], v[190:193], v[112:115]
	v_mfma_f32_16x16x32_bf16 v[100:103], v[144:147], v[182:185], v[100:103]
	v_mfma_f32_16x16x32_bf16 v[96:99], v[162:165], v[182:185], v[96:99]
	v_mfma_f32_16x16x32_bf16 v[84:87], v[144:147], v[4:7], v[84:87]
	v_mfma_f32_16x16x32_bf16 v[80:83], v[162:165], v[4:7], v[80:83]
	v_mfma_f32_16x16x32_bf16 v[124:127], v[156:159], v[194:197], v[124:127]
	v_mfma_f32_16x16x32_bf16 v[120:123], v[174:177], v[194:197], v[120:123]
	v_mfma_f32_16x16x32_bf16 v[108:111], v[156:159], v[186:189], v[108:111]
	v_mfma_f32_16x16x32_bf16 v[104:107], v[174:177], v[186:189], v[104:107]
	v_mfma_f32_16x16x32_bf16 v[92:95], v[156:159], v[178:181], v[92:95]
	v_mfma_f32_16x16x32_bf16 v[88:91], v[174:177], v[178:181], v[88:91]
	v_mfma_f32_16x16x32_bf16 v[76:79], v[156:159], v[0:3], v[76:79]
	v_mfma_f32_16x16x32_bf16 v[0:3], v[174:177], v[0:3], v[72:75]
	v_mfma_f32_16x16x32_bf16 v[124:127], v[152:155], v[198:201], v[124:127]
	v_mfma_f32_16x16x32_bf16 v[120:123], v[170:173], v[198:201], v[120:123]
	v_mfma_f32_16x16x32_bf16 v[108:111], v[152:155], v[190:193], v[108:111]
	v_mfma_f32_16x16x32_bf16 v[104:107], v[170:173], v[190:193], v[104:107]
	v_mfma_f32_16x16x32_bf16 v[92:95], v[152:155], v[182:185], v[92:95]
	v_mfma_f32_16x16x32_bf16 v[88:91], v[170:173], v[182:185], v[88:91]
	v_mfma_f32_16x16x32_bf16 v[76:79], v[152:155], v[4:7], v[76:79]
	v_mfma_f32_16x16x32_bf16 v[72:75], v[170:173], v[4:7], v[0:3]
	s_barrier
	s_mov_b32 m0, s85
	v_lshl_add_u64 v[222:223], v[222:223], 0, s[16:17]
	s_add_u32 s2, s72, 0x80080
	ds_read_b128 v[0:3], v237 offset:49152
	ds_read_b128 v[4:7], v237 offset:50176
	ds_read_b128 v[186:189], v237 offset:51200
	ds_read_b128 v[190:193], v237 offset:52224
	ds_read_b128 v[194:197], v237 offset:53248
	ds_read_b128 v[198:201], v237 offset:54272
	ds_read_b128 v[244:247], v237 offset:55296
	ds_read_b128 v[248:251], v237 offset:56320
	ds_read_b128 v[182:185], v160 offset:2048
	ds_read_b128 v[178:181], v242 offset:2048
	global_load_lds_dwordx4 v[222:223], off
	v_lshl_add_u64 v[222:223], v[224:225], 0, s[16:17]
	s_mov_b32 m0, s86
	s_addc_u32 s3, s73, 0
	global_load_lds_dwordx4 v[222:223], off
	v_lshl_add_u64 v[222:223], s[2:3], 0, v[204:205]
	s_mov_b32 m0, s89
	s_nop 0
	global_load_lds_dwordx4 v[222:223], off
	v_lshl_add_u64 v[222:223], s[2:3], 0, v[208:209]
	s_mov_b32 m0, s90
	s_nop 0
	global_load_lds_dwordx4 v[222:223], off
	v_lshl_add_u64 v[222:223], v[226:227], 0, s[16:17]
	s_mov_b32 m0, s87
	s_nop 0
	global_load_lds_dwordx4 v[222:223], off
	v_lshl_add_u64 v[222:223], v[228:229], 0, s[16:17]
	s_mov_b32 m0, s88
	s_nop 0
	global_load_lds_dwordx4 v[222:223], off
	s_waitcnt vmcnt(9)
	s_waitcnt lgkmcnt(0)
	s_barrier
	s_waitcnt lgkmcnt(0)
	v_mfma_f32_16x16x32_bf16 v[68:71], v[148:151], v[0:3], v[68:71]
	v_mfma_f32_16x16x32_bf16 v[64:67], v[166:169], v[0:3], v[64:67]
	v_mfma_f32_16x16x32_bf16 v[52:55], v[148:151], v[186:189], v[52:55]
	v_mfma_f32_16x16x32_bf16 v[48:51], v[166:169], v[186:189], v[48:51]
	v_mfma_f32_16x16x32_bf16 v[36:39], v[148:151], v[194:197], v[36:39]
	v_mfma_f32_16x16x32_bf16 v[32:35], v[166:169], v[194:197], v[32:35]
	v_mfma_f32_16x16x32_bf16 v[20:23], v[148:151], v[244:247], v[20:23]
	v_mfma_f32_16x16x32_bf16 v[16:19], v[166:169], v[244:247], v[16:19]
	v_mfma_f32_16x16x32_bf16 v[68:71], v[144:147], v[4:7], v[68:71]
	v_mfma_f32_16x16x32_bf16 v[64:67], v[162:165], v[4:7], v[64:67]
	v_mfma_f32_16x16x32_bf16 v[52:55], v[144:147], v[190:193], v[52:55]
	v_mfma_f32_16x16x32_bf16 v[48:51], v[162:165], v[190:193], v[48:51]
	v_mfma_f32_16x16x32_bf16 v[36:39], v[144:147], v[198:201], v[36:39]
	v_mfma_f32_16x16x32_bf16 v[32:35], v[162:165], v[198:201], v[32:35]
	v_mfma_f32_16x16x32_bf16 v[20:23], v[144:147], v[248:251], v[20:23]
	v_mfma_f32_16x16x32_bf16 v[16:19], v[162:165], v[248:251], v[16:19]
	v_mfma_f32_16x16x32_bf16 v[60:63], v[156:159], v[0:3], v[60:63]
	v_mfma_f32_16x16x32_bf16 v[0:3], v[174:177], v[0:3], v[56:59]
	v_mfma_f32_16x16x32_bf16 v[56:59], v[170:173], v[4:7], v[0:3]
	v_mfma_f32_16x16x32_bf16 v[0:3], v[156:159], v[186:189], v[44:47]
	v_mfma_f32_16x16x32_bf16 v[44:47], v[152:155], v[190:193], v[0:3]
	v_mfma_f32_16x16x32_bf16 v[0:3], v[174:177], v[186:189], v[40:43]
	v_mfma_f32_16x16x32_bf16 v[40:43], v[170:173], v[190:193], v[0:3]
	v_mfma_f32_16x16x32_bf16 v[0:3], v[156:159], v[194:197], v[28:31]
	v_mfma_f32_16x16x32_bf16 v[28:31], v[152:155], v[198:201], v[0:3]
	v_mfma_f32_16x16x32_bf16 v[0:3], v[174:177], v[194:197], v[24:27]
	v_mfma_f32_16x16x32_bf16 v[24:27], v[170:173], v[198:201], v[0:3]
	v_mfma_f32_16x16x32_bf16 v[0:3], v[156:159], v[244:247], v[12:15]
	v_mfma_f32_16x16x32_bf16 v[12:15], v[152:155], v[248:251], v[0:3]
	v_mfma_f32_16x16x32_bf16 v[0:3], v[174:177], v[244:247], v[8:11]
	v_mfma_f32_16x16x32_bf16 v[60:63], v[152:155], v[4:7], v[60:63]
	v_mfma_f32_16x16x32_bf16 v[8:11], v[170:173], v[248:251], v[0:3]
	s_and_b64 vcc, exec, s[40:41]
	s_mov_b64 s[2:3], -1
	s_cbranch_vccnz .LBB0_547
	v_mfma_f32_16x16x32_bf16 v[0:3], v[166:169], v[182:185], v[136:139]
	s_mov_b64 s[2:3], 0
	v_mfma_f32_16x16x32_bf16 v[166:169], v[174:177], v[182:185], v[140:143]
	v_mfma_f32_16x16x32_bf16 v[4:7], v[162:165], v[178:181], v[0:3]
	v_mfma_f32_16x16x32_bf16 v[0:3], v[170:173], v[178:181], v[166:169]

; #define PG8_STAGE(bufoff, gbase, voff) do { _Pragma("unroll") for (int _i = 0; _i < 2; ++_i) \
;         __builtin_amdgcn_global_load_lds((const GAS unsigned*)((const GAS char*)(gbase) + (voff)[_i]), (PG8_LAS unsigned*)(lds + (bufoff) + ldsw + _i * 8192), 16, 0, 0); } while (0)
; #define PG8_LDA(dst, b, h) do { _Pragma("unroll") for (int m = 0; m < 4; ++m) _Pragma("unroll") for (int k = 0; k < 2; ++k) dst[m][k] = *(const PG8_LAS bf16x8*)(lds + PG8_SA(b, h) + aoff + m * 2048 + k * 1024); } while (0)
; #define PG8_LDB(dst, b, h) do { _Pragma("unroll") for (int n = 0; n < 2; ++n) _Pragma("unroll") for (int k = 0; k < 2; ++k) dst[n][k] = *(const PG8_LAS bf16x8*)(lds + PG8_SB(b, h) + boff + n * 2048 + k * 1024); } while (0)
; #define PG8_MMA(ai, bj, At, Bt) do { __builtin_amdgcn_s_setprio(1); _Pragma("unroll") for (int m = 0; m < 4; ++m) _Pragma("unroll") for (int n = 0; n < 2; ++n) _Pragma("unroll") for (int k = 0; k < 2; ++k) \
;         acc[ai][bj][m][n] = __builtin_amdgcn_mfma_f32_16x16x32_bf16(Bt[n][k], At[m][k], acc[ai][bj][m][n], 0, 0, 0); __builtin_amdgcn_s_setprio(0); } while (0)
; #define PG8_WAIT_V(n) asm volatile("s_waitcnt vmcnt(" #n ")" ::: "memory")
; #define PG8_WAIT_L(n) asm volatile("s_waitcnt lgkmcnt(" #n ")" ::: "memory")
; #define PG8_BAR __builtin_amdgcn_s_barrier()
; #define PG8_SCHED __builtin_amdgcn_sched_barrier(0)
; #define PG8_STAGE(bufoff, gbase, voff) do { _Pragma("unroll") for (int _i = 0; _i < 2; ++_i) \
;         __builtin_amdgcn_global_load_lds((const GAS unsigned*)((const GAS char*)(gbase) + (voff)[_i]), (PG8_LAS unsigned*)(lds + (bufoff) + ldsw + _i * 8192), 16, 0, 0); } while (0)
; #define PG8_LDA(dst, b, h) do { _Pragma("unroll") for (int m = 0; m < 4; ++m) _Pragma("unroll") for (int k = 0; k < 2; ++k) dst[m][k] = *(const PG8_LAS bf16x8*)(lds + PG8_SA(b, h) + aoff + m * 2048 + k * 1024); } while (0)
; #define PG8_BAR __builtin_amdgcn_s_barrier()
; template <class Epi, class Sched>
; __device__ __forceinline__ void gemm_phase_strip(PG8_LAS unsigned char* lds, PG8_LAS unsigned char* slds, PG8_LAS unsigned char* pf, const Gemm g, const Sched& S, const Epi& E, int wv) {
;     ...
;             PG8_LDB(B0, 0, 0); PG8_LDB(B1, 0, 1); PG8_SCHED; PG8_LDA(At, 0, 0); PG8_STAGE(PG8_SA(1, 1), a1 + PG8_HS, voffA);
;             PG8_WAIT_V(8); PG8_WAIT_L(0); PG8_BAR; PG8_MMA(0, 0, At, B0); PG8_MMA(0, 1, At, B1); PG8_BAR; PG8_SCHED;
.LBB0_1108:
	s_barrier
	s_xor_b32 s97, s97, 0x1000
	s_add_i32 s23, s23, 2
	s_add_u32 s14, s14, 0x100
	s_addc_u32 s15, s15, 0
	s_cmp_gt_u32 s23, 5
	s_cbranch_scc1 .LBB0_1119
.LBB0_1109:
	s_add_u32 s24, s12, s14
	s_addc_u32 s25, s13, s15
	s_add_u32 s28, s24, 0x100
	s_addc_u32 s29, s25, 0
	s_add_u32 s38, s21, s14
	s_addc_u32 s39, s22, s15
	s_add_i32 s41, 0, 0x10000
	s_add_i32 s43, 0, 0x14000
	v_add_u32_e32 v132, s41, v233
	ds_read_b128 v[148:151], v132
	ds_read_b128 v[144:147], v132 offset:1024
	ds_read_b128 v[166:169], v132 offset:2048
	ds_read_b128 v[162:165], v132 offset:3072
	v_add_u32_e32 v132, s43, v233
	ds_read_b128 v[156:159], v132
	ds_read_b128 v[152:155], v132 offset:1024
	ds_read_b128 v[174:177], v132 offset:2048
	ds_read_b128 v[170:173], v132 offset:3072
	s_cmpk_eq_i32 s14, 0x300
	s_cselect_b64 s[58:59], -1, 0
	s_and_b64 s[24:25], s[58:59], exec
	s_cselect_b32 s29, s51, s29
	s_cselect_b32 s28, s50, s28
	s_cselect_b32 s57, s1, s39
	s_cselect_b32 s56, s5, s38
	v_lshl_add_u64 v[222:223], v[220:221], 0, s[14:15]
	s_add_i32 m0, s19, 0xc000
	ds_read_b128 v[132:135], v236
	ds_read_b128 v[140:143], v236 offset:1024
	ds_read_b128 v[178:181], v236 offset:2048
	ds_read_b128 v[182:185], v236 offset:3072
	ds_read_b128 v[186:189], v236 offset:4096
	ds_read_b128 v[190:193], v236 offset:5120
	ds_read_b128 v[194:197], v236 offset:6144
	ds_read_b128 v[198:201], v236 offset:7168
	global_load_lds_dwordx4 v[222:223], off
	v_lshl_add_u64 v[222:223], v[218:219], 0, s[14:15]
	s_add_i32 m0, s19, 0xe000
	s_nop 0
	global_load_lds_dwordx4 v[222:223], off
	s_waitcnt vmcnt(8)
	s_waitcnt lgkmcnt(0)
	s_barrier
	s_waitcnt lgkmcnt(0)
	v_mfma_f32_16x16x32_bf16 v[136:139], v[148:151], v[132:135], v[136:139]
	v_mfma_f32_16x16x32_bf16 v[128:131], v[166:169], v[132:135], v[128:131]
	v_mfma_f32_16x16x32_bf16 v[124:127], v[148:151], v[178:181], v[124:127]
	v_mfma_f32_16x16x32_bf16 v[120:123], v[166:169], v[178:181], v[120:123]
	v_mfma_f32_16x16x32_bf16 v[116:119], v[148:151], v[186:189], v[116:119]
	v_mfma_f32_16x16x32_bf16 v[112:115], v[166:169], v[186:189], v[112:115]
	v_mfma_f32_16x16x32_bf16 v[108:111], v[148:151], v[194:197], v[108:111]
	v_mfma_f32_16x16x32_bf16 v[104:107], v[166:169], v[194:197], v[104:107]
	v_mfma_f32_16x16x32_bf16 v[136:139], v[144:147], v[140:143], v[136:139]
	v_mfma_f32_16x16x32_bf16 v[128:131], v[162:165], v[140:143], v[128:131]
	v_mfma_f32_16x16x32_bf16 v[124:127], v[144:147], v[182:185], v[124:127]
	v_mfma_f32_16x16x32_bf16 v[120:123], v[162:165], v[182:185], v[120:123]
	v_mfma_f32_16x16x32_bf16 v[116:119], v[144:147], v[190:193], v[116:119]
	v_mfma_f32_16x16x32_bf16 v[112:115], v[162:165], v[190:193], v[112:115]
	v_mfma_f32_16x16x32_bf16 v[108:111], v[144:147], v[198:201], v[108:111]
	v_mfma_f32_16x16x32_bf16 v[104:107], v[162:165], v[198:201], v[104:107]
	v_mfma_f32_16x16x32_bf16 v[68:71], v[156:159], v[132:135], v[68:71]
	v_mfma_f32_16x16x32_bf16 v[64:67], v[174:177], v[132:135], v[64:67]
	v_mfma_f32_16x16x32_bf16 v[60:63], v[156:159], v[178:181], v[60:63]
	v_mfma_f32_16x16x32_bf16 v[56:59], v[174:177], v[178:181], v[56:59]
	v_mfma_f32_16x16x32_bf16 v[52:55], v[156:159], v[186:189], v[52:55]
	v_mfma_f32_16x16x32_bf16 v[48:51], v[174:177], v[186:189], v[48:51]
	v_mfma_f32_16x16x32_bf16 v[44:47], v[156:159], v[194:197], v[44:47]
	v_mfma_f32_16x16x32_bf16 v[40:43], v[174:177], v[194:197], v[40:43]
	v_mfma_f32_16x16x32_bf16 v[68:71], v[152:155], v[140:143], v[68:71]
	v_mfma_f32_16x16x32_bf16 v[64:67], v[170:173], v[140:143], v[64:67]
	v_mfma_f32_16x16x32_bf16 v[60:63], v[152:155], v[182:185], v[60:63]
	v_mfma_f32_16x16x32_bf16 v[56:59], v[170:173], v[182:185], v[56:59]
	v_mfma_f32_16x16x32_bf16 v[52:55], v[152:155], v[190:193], v[52:55]
	v_mfma_f32_16x16x32_bf16 v[48:51], v[170:173], v[190:193], v[48:51]
	v_mfma_f32_16x16x32_bf16 v[44:47], v[152:155], v[198:201], v[44:47]
	v_mfma_f32_16x16x32_bf16 v[40:43], v[170:173], v[198:201], v[40:43]
	s_barrier
; #define PG8_STAGE(bufoff, gbase, voff) do { _Pragma("unroll") for (int _i = 0; _i < 2; ++_i) \
;         __builtin_amdgcn_global_load_lds((const GAS unsigned*)((const GAS char*)(gbase) + (voff)[_i]), (PG8_LAS unsigned*)(lds + (bufoff) + ldsw + _i * 8192), 16, 0, 0); } while (0)
; #define PG8_LDA(dst, b, h) do { _Pragma("unroll") for (int m = 0; m < 4; ++m) _Pragma("unroll") for (int k = 0; k < 2; ++k) dst[m][k] = *(const PG8_LAS bf16x8*)(lds + PG8_SA(b, h) + aoff + m * 2048 + k * 1024); } while (0)
; #define PG8_MMA(ai, bj, At, Bt) do { __builtin_amdgcn_s_setprio(1); _Pragma("unroll") for (int m = 0; m < 4; ++m) _Pragma("unroll") for (int n = 0; n < 2; ++n) _Pragma("unroll") for (int k = 0; k < 2; ++k) \
;         acc[ai][bj][m][n] = __builtin_amdgcn_mfma_f32_16x16x32_bf16(Bt[n][k], At[m][k], acc[ai][bj][m][n], 0, 0, 0); __builtin_amdgcn_s_setprio(0); } while (0)
; #define PG8_WAIT_V(n) asm volatile("s_waitcnt vmcnt(" #n ")" ::: "memory")
; #define PG8_WAIT_L(n) asm volatile("s_waitcnt lgkmcnt(" #n ")" ::: "memory")
; #define PG8_BAR __builtin_amdgcn_s_barrier()
; #define PG8_SCHED __builtin_amdgcn_sched_barrier(0)
; #define PG8_STAGE(bufoff, gbase, voff) do { _Pragma("unroll") for (int _i = 0; _i < 2; ++_i) \
;         __builtin_amdgcn_global_load_lds((const GAS unsigned*)((const GAS char*)(gbase) + (voff)[_i]), (PG8_LAS unsigned*)(lds + (bufoff) + ldsw + _i * 8192), 16, 0, 0); } while (0)
; #define PG8_LDA(dst, b, h) do { _Pragma("unroll") for (int m = 0; m < 4; ++m) _Pragma("unroll") for (int k = 0; k < 2; ++k) dst[m][k] = *(const PG8_LAS bf16x8*)(lds + PG8_SA(b, h) + aoff + m * 2048 + k * 1024); } while (0)
; #define PG8_LDS_S(dst, boffs) do { dst[0] = *(const PG8_LAS bf16x8*)(slds + (boffs) + soff0); dst[1] = *(const PG8_LAS bf16x8*)(slds + (boffs) + (soff0 ^ 64)); } while (0)
; #define PG8_BAR __builtin_amdgcn_s_barrier()
; template <class Epi, class Sched>
; __device__ __forceinline__ void gemm_phase_strip(PG8_LAS unsigned char* lds, PG8_LAS unsigned char* slds, PG8_LAS unsigned char* pf, const Gemm g, const Sched& S, const Epi& E, int wv) {
;     ...
;             PG8_LDA(At, 0, 1); PG8_LDS_S(As, sq); PG8_STAGE(PG8_SB(0, 0), b2, voffB); PG8_STAGE(PG8_SB(0, 1), b2 + hstepB, voffB); PG8_STAGE(PG8_SA(0, 0), a2, voffA);
;             PG8_WAIT_V(8); PG8_WAIT_L(0); PG8_BAR; PG8_MMA(1, 0, At, B0); PG8_MMA(1, 1, At, B1); PG8_MMA_S(); PG8_BAR; PG8_SCHED;
	s_add_i32 s24, s97, 0
	s_add_i32 s24, s24, 0x21000
	v_add_u32_e32 v160, s24, v234
	v_add_u32_e32 v237, s24, v235
	s_add_i32 s24, s41, s81
	v_lshl_add_u64 v[222:223], s[56:57], 0, v[204:205]
	s_mov_b32 m0, s24
	ds_read_b128 v[132:135], v236 offset:16384
	ds_read_b128 v[140:143], v236 offset:17408
	ds_read_b128 v[186:189], v236 offset:18432
	ds_read_b128 v[190:193], v236 offset:19456
	ds_read_b128 v[194:197], v236 offset:20480
	ds_read_b128 v[198:201], v236 offset:21504
	ds_read_b128 v[242:245], v236 offset:22528
	ds_read_b128 v[246:249], v236 offset:23552
	ds_read_b128 v[182:185], v160
	ds_read_b128 v[178:181], v237
	global_load_lds_dwordx4 v[222:223], off
	s_add_i32 m0, s24, 0x2000
	s_add_u32 s24, s56, 0x20000
	v_lshl_add_u64 v[224:225], s[56:57], 0, v[208:209]
	s_addc_u32 s25, s57, 0
	s_add_i32 s38, s43, s81
	global_load_lds_dwordx4 v[224:225], off
	v_lshl_add_u64 v[226:227], s[24:25], 0, v[204:205]
	s_mov_b32 m0, s38
	v_lshl_add_u64 v[228:229], s[28:29], 0, v[206:207]
	global_load_lds_dwordx4 v[226:227], off
	v_lshl_add_u64 v[226:227], s[24:25], 0, v[208:209]
	s_add_i32 m0, s38, 0x2000
	s_nop 0
	global_load_lds_dwordx4 v[226:227], off
	v_lshl_add_u64 v[226:227], s[28:29], 0, v[202:203]
	s_mov_b32 m0, s19
	s_nop 0
	global_load_lds_dwordx4 v[226:227], off
	s_mov_b32 m0, s27
	s_nop 0
	global_load_lds_dwordx4 v[228:229], off
	s_waitcnt vmcnt(8)
	s_waitcnt lgkmcnt(0)
	s_barrier
	s_waitcnt lgkmcnt(0)
	v_mfma_f32_16x16x32_bf16 v[100:103], v[148:151], v[132:135], v[100:103]
	v_mfma_f32_16x16x32_bf16 v[96:99], v[166:169], v[132:135], v[96:99]
	v_mfma_f32_16x16x32_bf16 v[92:95], v[148:151], v[186:189], v[92:95]
	v_mfma_f32_16x16x32_bf16 v[88:91], v[166:169], v[186:189], v[88:91]
	v_mfma_f32_16x16x32_bf16 v[84:87], v[148:151], v[194:197], v[84:87]
	v_mfma_f32_16x16x32_bf16 v[80:83], v[166:169], v[194:197], v[80:83]
	v_mfma_f32_16x16x32_bf16 v[76:79], v[148:151], v[242:245], v[76:79]
	v_mfma_f32_16x16x32_bf16 v[72:75], v[166:169], v[242:245], v[72:75]
	v_mfma_f32_16x16x32_bf16 v[100:103], v[144:147], v[140:143], v[100:103]
	v_mfma_f32_16x16x32_bf16 v[96:99], v[162:165], v[140:143], v[96:99]
	v_mfma_f32_16x16x32_bf16 v[92:95], v[144:147], v[190:193], v[92:95]
	v_mfma_f32_16x16x32_bf16 v[88:91], v[162:165], v[190:193], v[88:91]
	v_mfma_f32_16x16x32_bf16 v[84:87], v[144:147], v[198:201], v[84:87]
	v_mfma_f32_16x16x32_bf16 v[80:83], v[162:165], v[198:201], v[80:83]
	v_mfma_f32_16x16x32_bf16 v[76:79], v[144:147], v[246:249], v[76:79]
	v_mfma_f32_16x16x32_bf16 v[72:75], v[162:165], v[246:249], v[72:75]
	v_mfma_f32_16x16x32_bf16 v[36:39], v[156:159], v[132:135], v[36:39]
	v_mfma_f32_16x16x32_bf16 v[32:35], v[174:177], v[132:135], v[32:35]
	v_mfma_f32_16x16x32_bf16 v[28:31], v[156:159], v[186:189], v[28:31]
	v_mfma_f32_16x16x32_bf16 v[24:27], v[174:177], v[186:189], v[24:27]
	v_mfma_f32_16x16x32_bf16 v[20:23], v[156:159], v[194:197], v[20:23]
	v_mfma_f32_16x16x32_bf16 v[16:19], v[174:177], v[194:197], v[16:19]
	v_mfma_f32_16x16x32_bf16 v[12:15], v[156:159], v[242:245], v[12:15]
	v_mfma_f32_16x16x32_bf16 v[8:11], v[174:177], v[242:245], v[8:11]
	v_mfma_f32_16x16x32_bf16 v[36:39], v[152:155], v[140:143], v[36:39]
	v_mfma_f32_16x16x32_bf16 v[32:35], v[170:173], v[140:143], v[32:35]
	v_mfma_f32_16x16x32_bf16 v[28:31], v[152:155], v[190:193], v[28:31]
	v_mfma_f32_16x16x32_bf16 v[24:27], v[170:173], v[190:193], v[24:27]
	v_mfma_f32_16x16x32_bf16 v[20:23], v[152:155], v[198:201], v[20:23]
	v_mfma_f32_16x16x32_bf16 v[16:19], v[170:173], v[198:201], v[16:19]
	v_mfma_f32_16x16x32_bf16 v[12:15], v[152:155], v[246:249], v[12:15]
	v_mfma_f32_16x16x32_bf16 v[8:11], v[170:173], v[246:249], v[8:11]
	v_cndmask_b32_e64 v132, 0, 1, s[8:9]
	v_cmp_ne_u32_e64 s[38:39], 1, v132
	s_andn2_b64 vcc, exec, s[8:9]
	s_mov_b64 s[60:61], -1
	s_cbranch_vccnz .LBB0_1111
	v_mfma_f32_16x16x32_bf16 v[132:135], v[166:169], v[182:185], v[4:7]
	s_mov_b64 s[60:61], 0
	v_mfma_f32_16x16x32_bf16 v[140:143], v[174:177], v[182:185], v[0:3]
	v_mfma_f32_16x16x32_bf16 v[132:135], v[162:165], v[178:181], v[132:135]
	v_mfma_f32_16x16x32_bf16 v[140:143], v[170:173], v[178:181], v[140:143]

; #define PG8_STAGE(bufoff, gbase, voff) do { _Pragma("unroll") for (int _i = 0; _i < 2; ++_i) \
;         __builtin_amdgcn_global_load_lds((const GAS unsigned*)((const GAS char*)(gbase) + (voff)[_i]), (PG8_LAS unsigned*)(lds + (bufoff) + ldsw + _i * 8192), 16, 0, 0); } while (0)
; #define PG8_LDA(dst, b, h) do { _Pragma("unroll") for (int m = 0; m < 4; ++m) _Pragma("unroll") for (int k = 0; k < 2; ++k) dst[m][k] = *(const PG8_LAS bf16x8*)(lds + PG8_SA(b, h) + aoff + m * 2048 + k * 1024); } while (0)
; #define PG8_LDB(dst, b, h) do { _Pragma("unroll") for (int n = 0; n < 2; ++n) _Pragma("unroll") for (int k = 0; k < 2; ++k) dst[n][k] = *(const PG8_LAS bf16x8*)(lds + PG8_SB(b, h) + boff + n * 2048 + k * 1024); } while (0)
; #define PG8_MMA(ai, bj, At, Bt) do { __builtin_amdgcn_s_setprio(1); _Pragma("unroll") for (int m = 0; m < 4; ++m) _Pragma("unroll") for (int n = 0; n < 2; ++n) _Pragma("unroll") for (int k = 0; k < 2; ++k) \
;         acc[ai][bj][m][n] = __builtin_amdgcn_mfma_f32_16x16x32_bf16(Bt[n][k], At[m][k], acc[ai][bj][m][n], 0, 0, 0); __builtin_amdgcn_s_setprio(0); } while (0)
; #define PG8_WAIT_V(n) asm volatile("s_waitcnt vmcnt(" #n ")" ::: "memory")
; #define PG8_WAIT_L(n) asm volatile("s_waitcnt lgkmcnt(" #n ")" ::: "memory")
; #define PG8_BAR __builtin_amdgcn_s_barrier()
; #define PG8_SCHED __builtin_amdgcn_sched_barrier(0)
; #define PG8_STAGE(bufoff, gbase, voff) do { _Pragma("unroll") for (int _i = 0; _i < 2; ++_i) \
;         __builtin_amdgcn_global_load_lds((const GAS unsigned*)((const GAS char*)(gbase) + (voff)[_i]), (PG8_LAS unsigned*)(lds + (bufoff) + ldsw + _i * 8192), 16, 0, 0); } while (0)
; #define PG8_WAIT_V(n) asm volatile("s_waitcnt vmcnt(" #n ")" ::: "memory")
; #define PG8_BAR __builtin_amdgcn_s_barrier()
; template <class Epi, class Sched>
; __device__ __forceinline__ void gemm_phase_strip(PG8_LAS unsigned char* lds, PG8_LAS unsigned char* slds, PG8_LAS unsigned char* pf, const Gemm g, const Sched& S, const Epi& E, int wv) {
;     ...
;             PG8_WAIT_V(8); PG8_WAIT_L(0); PG8_BAR; PG8_MMA(1, 0, At, B0); PG8_MMA(1, 1, At, B1); PG8_MMA_S(); PG8_BAR; PG8_SCHED;
;             PG8_LDB(B0, 1, 0); PG8_LDB(B1, 1, 1); PG8_SCHED; PG8_LDA(At, 1, 0); PG8_STAGE(PG8_SA(0, 1), a2 + (Sched::SPLIT ? ((last && has_next) ? (nxt.kh > 0 ? -(long)hstepA : (long)hstepA) : hsA) : (long)hstepA), voffA); PG8_STAGE_S(sq ^ 4096u, s2);
.LBB0_1113:
	s_barrier
	s_nop 3
	v_add_u32_e32 v0, 0, v233
	v_add_u32_e32 v1, 0x18000, v0
	v_add_u32_e32 v0, 0x1c000, v0
	ds_read_b128 v[148:151], v1
	ds_read_b128 v[144:147], v1 offset:1024
	ds_read_b128 v[166:169], v1 offset:2048
	ds_read_b128 v[162:165], v1 offset:3072
	ds_read_b128 v[156:159], v0
	ds_read_b128 v[152:155], v0 offset:1024
	ds_read_b128 v[174:177], v0 offset:2048
	ds_read_b128 v[170:173], v0 offset:3072
	s_add_u32 s24, s28, 0x80000
	s_addc_u32 s25, s29, 0
	s_mov_b32 m0, s78
	v_lshl_add_u64 v[242:243], s[24:25], 0, v[202:203]
	ds_read_b128 v[194:197], v236 offset:32768
	ds_read_b128 v[198:201], v236 offset:33792
	ds_read_b128 v[186:189], v236 offset:34816
	ds_read_b128 v[190:193], v236 offset:35840
	ds_read_b128 v[178:181], v236 offset:36864
	ds_read_b128 v[182:185], v236 offset:37888
	ds_read_b128 v[0:3], v236 offset:38912
	ds_read_b128 v[4:7], v236 offset:39936
	global_load_lds_dwordx4 v[242:243], off
	v_lshl_add_u64 v[242:243], s[24:25], 0, v[206:207]
	s_mov_b32 m0, s79
	s_nop 0
	global_load_lds_dwordx4 v[242:243], off
	v_mov_b32_e32 v242, v230
	s_and_saveexec_b64 s[28:29], s[34:35]
	s_cbranch_execz .LBB0_1115
	s_add_u32 s41, s11, s14
	s_addc_u32 s43, s20, s15
	s_and_b64 s[24:25], s[58:59], exec
	s_cselect_b32 s25, s53, s43
	s_cselect_b32 s24, s52, s41
	s_xor_b32 s41, s97, 0x1000
	s_add_i32 m0, s89, s41
	s_nop 0
	global_load_lds_dwordx4 v242, s[24:25]
; #define PG8_STAGE(bufoff, gbase, voff) do { _Pragma("unroll") for (int _i = 0; _i < 2; ++_i) \
;         __builtin_amdgcn_global_load_lds((const GAS unsigned*)((const GAS char*)(gbase) + (voff)[_i]), (PG8_LAS unsigned*)(lds + (bufoff) + ldsw + _i * 8192), 16, 0, 0); } while (0)
; #define PG8_LDA(dst, b, h) do { _Pragma("unroll") for (int m = 0; m < 4; ++m) _Pragma("unroll") for (int k = 0; k < 2; ++k) dst[m][k] = *(const PG8_LAS bf16x8*)(lds + PG8_SA(b, h) + aoff + m * 2048 + k * 1024); } while (0)
; #define PG8_MMA(ai, bj, At, Bt) do { __builtin_amdgcn_s_setprio(1); _Pragma("unroll") for (int m = 0; m < 4; ++m) _Pragma("unroll") for (int n = 0; n < 2; ++n) _Pragma("unroll") for (int k = 0; k < 2; ++k) \
;         acc[ai][bj][m][n] = __builtin_amdgcn_mfma_f32_16x16x32_bf16(Bt[n][k], At[m][k], acc[ai][bj][m][n], 0, 0, 0); __builtin_amdgcn_s_setprio(0); } while (0)
; #define PG8_WAIT_V(n) asm volatile("s_waitcnt vmcnt(" #n ")" ::: "memory")
; #define PG8_WAIT_L(n) asm volatile("s_waitcnt lgkmcnt(" #n ")" ::: "memory")
; #define PG8_BAR __builtin_amdgcn_s_barrier()
; #define PG8_SCHED __builtin_amdgcn_sched_barrier(0)
; #define PG8_STAGE(bufoff, gbase, voff) do { _Pragma("unroll") for (int _i = 0; _i < 2; ++_i) \
;         __builtin_amdgcn_global_load_lds((const GAS unsigned*)((const GAS char*)(gbase) + (voff)[_i]), (PG8_LAS unsigned*)(lds + (bufoff) + ldsw + _i * 8192), 16, 0, 0); } while (0)
; #define PG8_LDA(dst, b, h) do { _Pragma("unroll") for (int m = 0; m < 4; ++m) _Pragma("unroll") for (int k = 0; k < 2; ++k) dst[m][k] = *(const PG8_LAS bf16x8*)(lds + PG8_SA(b, h) + aoff + m * 2048 + k * 1024); } while (0)
; #define PG8_WAIT_V(n) asm volatile("s_waitcnt vmcnt(" #n ")" ::: "memory")
; template <class Epi, class Sched>
; __device__ __forceinline__ void gemm_phase_strip(PG8_LAS unsigned char* lds, PG8_LAS unsigned char* slds, PG8_LAS unsigned char* pf, const Gemm g, const Sched& S, const Epi& E, int wv) {
;     ...
;             PG8_WAIT_V(9); PG8_WAIT_L(0); PG8_BAR; PG8_MMA(0, 0, At, B0); PG8_MMA(0, 1, At, B1); PG8_BAR; PG8_SCHED;
;             PG8_LDA(At, 1, 1); PG8_LDS_S(As, sq + 2048u); PG8_STAGE(PG8_SB(1, 0), b3, voffB); PG8_STAGE(PG8_SB(1, 1), b3 + hstepB, voffB); PG8_STAGE(PG8_SA(1, 0), a3, voffA);
;             PG8_WAIT_V(9); PG8_WAIT_L(0); PG8_BAR; PG8_MMA(1, 0, At, B0); PG8_MMA(1, 1, At, B1); PG8_MMA_S(); PG8_BAR; PG8_SCHED;
.LBB0_1115:
	s_or_b64 exec, exec, s[28:29]
	s_waitcnt vmcnt(9)
	s_waitcnt lgkmcnt(0)
	s_barrier
	s_waitcnt lgkmcnt(0)
	v_mfma_f32_16x16x32_bf16 v[136:139], v[148:151], v[194:197], v[136:139]
	v_mfma_f32_16x16x32_bf16 v[128:131], v[166:169], v[194:197], v[128:131]
	v_mfma_f32_16x16x32_bf16 v[124:127], v[148:151], v[186:189], v[124:127]
	v_mfma_f32_16x16x32_bf16 v[120:123], v[166:169], v[186:189], v[120:123]
	v_mfma_f32_16x16x32_bf16 v[116:119], v[148:151], v[178:181], v[116:119]
	v_mfma_f32_16x16x32_bf16 v[112:115], v[166:169], v[178:181], v[112:115]
	v_mfma_f32_16x16x32_bf16 v[108:111], v[148:151], v[0:3], v[108:111]
	v_mfma_f32_16x16x32_bf16 v[104:107], v[166:169], v[0:3], v[104:107]
	v_mfma_f32_16x16x32_bf16 v[136:139], v[144:147], v[198:201], v[136:139]
	v_mfma_f32_16x16x32_bf16 v[128:131], v[162:165], v[198:201], v[128:131]
	v_mfma_f32_16x16x32_bf16 v[124:127], v[144:147], v[190:193], v[124:127]
	v_mfma_f32_16x16x32_bf16 v[120:123], v[162:165], v[190:193], v[120:123]
	v_mfma_f32_16x16x32_bf16 v[116:119], v[144:147], v[182:185], v[116:119]
	v_mfma_f32_16x16x32_bf16 v[112:115], v[162:165], v[182:185], v[112:115]
	v_mfma_f32_16x16x32_bf16 v[108:111], v[144:147], v[4:7], v[108:111]
	v_mfma_f32_16x16x32_bf16 v[104:107], v[162:165], v[4:7], v[104:107]
	v_mfma_f32_16x16x32_bf16 v[68:71], v[156:159], v[194:197], v[68:71]
	v_mfma_f32_16x16x32_bf16 v[64:67], v[174:177], v[194:197], v[64:67]
	v_mfma_f32_16x16x32_bf16 v[60:63], v[156:159], v[186:189], v[60:63]
	v_mfma_f32_16x16x32_bf16 v[56:59], v[174:177], v[186:189], v[56:59]
	v_mfma_f32_16x16x32_bf16 v[52:55], v[156:159], v[178:181], v[52:55]
	v_mfma_f32_16x16x32_bf16 v[48:51], v[174:177], v[178:181], v[48:51]
	v_mfma_f32_16x16x32_bf16 v[44:47], v[156:159], v[0:3], v[44:47]
	v_mfma_f32_16x16x32_bf16 v[0:3], v[174:177], v[0:3], v[40:43]
	v_mfma_f32_16x16x32_bf16 v[68:71], v[152:155], v[198:201], v[68:71]
	v_mfma_f32_16x16x32_bf16 v[64:67], v[170:173], v[198:201], v[64:67]
	v_mfma_f32_16x16x32_bf16 v[60:63], v[152:155], v[190:193], v[60:63]
	v_mfma_f32_16x16x32_bf16 v[56:59], v[170:173], v[190:193], v[56:59]
	v_mfma_f32_16x16x32_bf16 v[52:55], v[152:155], v[182:185], v[52:55]
	v_mfma_f32_16x16x32_bf16 v[48:51], v[170:173], v[182:185], v[48:51]
	v_mfma_f32_16x16x32_bf16 v[44:47], v[152:155], v[4:7], v[44:47]
	v_mfma_f32_16x16x32_bf16 v[40:43], v[170:173], v[4:7], v[0:3]
	s_barrier
	s_mov_b32 m0, s83
	v_lshl_add_u64 v[222:223], v[222:223], 0, s[16:17]
	s_add_u32 s24, s56, 0x20080
	ds_read_b128 v[0:3], v236 offset:49152
	ds_read_b128 v[4:7], v236 offset:50176
	ds_read_b128 v[186:189], v236 offset:51200
	ds_read_b128 v[190:193], v236 offset:52224
	ds_read_b128 v[194:197], v236 offset:53248
	ds_read_b128 v[198:201], v236 offset:54272
	ds_read_b128 v[242:245], v236 offset:55296
	ds_read_b128 v[246:249], v236 offset:56320
	ds_read_b128 v[182:185], v160 offset:2048
	ds_read_b128 v[178:181], v237 offset:2048
	global_load_lds_dwordx4 v[222:223], off
	v_lshl_add_u64 v[222:223], v[224:225], 0, s[16:17]
	s_mov_b32 m0, s84
	s_addc_u32 s25, s57, 0
	global_load_lds_dwordx4 v[222:223], off
	v_lshl_add_u64 v[222:223], s[24:25], 0, v[204:205]
	s_mov_b32 m0, s87
	s_nop 0
	global_load_lds_dwordx4 v[222:223], off
	v_lshl_add_u64 v[222:223], s[24:25], 0, v[208:209]
	s_mov_b32 m0, s88
	s_nop 0
	global_load_lds_dwordx4 v[222:223], off
	v_lshl_add_u64 v[222:223], v[226:227], 0, s[16:17]
	s_mov_b32 m0, s85
	s_nop 0
	global_load_lds_dwordx4 v[222:223], off
	v_lshl_add_u64 v[222:223], v[228:229], 0, s[16:17]
	s_mov_b32 m0, s86
	s_nop 0
	global_load_lds_dwordx4 v[222:223], off
	s_waitcnt vmcnt(9)
	s_waitcnt lgkmcnt(0)
	s_barrier
	s_waitcnt lgkmcnt(0)
	v_mfma_f32_16x16x32_bf16 v[100:103], v[148:151], v[0:3], v[100:103]
	v_mfma_f32_16x16x32_bf16 v[96:99], v[166:169], v[0:3], v[96:99]
	v_mfma_f32_16x16x32_bf16 v[92:95], v[148:151], v[186:189], v[92:95]
	v_mfma_f32_16x16x32_bf16 v[88:91], v[166:169], v[186:189], v[88:91]
	v_mfma_f32_16x16x32_bf16 v[84:87], v[148:151], v[194:197], v[84:87]
	v_mfma_f32_16x16x32_bf16 v[80:83], v[166:169], v[194:197], v[80:83]
	v_mfma_f32_16x16x32_bf16 v[76:79], v[148:151], v[242:245], v[76:79]
	v_mfma_f32_16x16x32_bf16 v[72:75], v[166:169], v[242:245], v[72:75]
	v_mfma_f32_16x16x32_bf16 v[100:103], v[144:147], v[4:7], v[100:103]
	v_mfma_f32_16x16x32_bf16 v[96:99], v[162:165], v[4:7], v[96:99]
	v_mfma_f32_16x16x32_bf16 v[92:95], v[144:147], v[190:193], v[92:95]
	v_mfma_f32_16x16x32_bf16 v[88:91], v[162:165], v[190:193], v[88:91]
	v_mfma_f32_16x16x32_bf16 v[84:87], v[144:147], v[198:201], v[84:87]
	v_mfma_f32_16x16x32_bf16 v[80:83], v[162:165], v[198:201], v[80:83]
	v_mfma_f32_16x16x32_bf16 v[76:79], v[144:147], v[246:249], v[76:79]
	v_mfma_f32_16x16x32_bf16 v[72:75], v[162:165], v[246:249], v[72:75]
	v_mfma_f32_16x16x32_bf16 v[36:39], v[156:159], v[0:3], v[36:39]
	v_mfma_f32_16x16x32_bf16 v[0:3], v[174:177], v[0:3], v[32:35]
	v_mfma_f32_16x16x32_bf16 v[32:35], v[170:173], v[4:7], v[0:3]
	v_mfma_f32_16x16x32_bf16 v[0:3], v[156:159], v[186:189], v[28:31]
	v_mfma_f32_16x16x32_bf16 v[28:31], v[152:155], v[190:193], v[0:3]
	v_mfma_f32_16x16x32_bf16 v[0:3], v[174:177], v[186:189], v[24:27]
	v_mfma_f32_16x16x32_bf16 v[24:27], v[170:173], v[190:193], v[0:3]
	v_mfma_f32_16x16x32_bf16 v[0:3], v[156:159], v[194:197], v[20:23]
	v_mfma_f32_16x16x32_bf16 v[20:23], v[152:155], v[198:201], v[0:3]
	v_mfma_f32_16x16x32_bf16 v[0:3], v[174:177], v[194:197], v[16:19]
	v_mfma_f32_16x16x32_bf16 v[16:19], v[170:173], v[198:201], v[0:3]
	v_mfma_f32_16x16x32_bf16 v[0:3], v[156:159], v[242:245], v[12:15]
	v_mfma_f32_16x16x32_bf16 v[12:15], v[152:155], v[246:249], v[0:3]
	v_mfma_f32_16x16x32_bf16 v[0:3], v[174:177], v[242:245], v[8:11]
	v_mfma_f32_16x16x32_bf16 v[36:39], v[152:155], v[4:7], v[36:39]
	v_mfma_f32_16x16x32_bf16 v[8:11], v[170:173], v[246:249], v[0:3]
	s_and_b64 vcc, exec, s[38:39]
	s_mov_b64 s[28:29], -1
	s_cbranch_vccnz .LBB0_1117
	v_mfma_f32_16x16x32_bf16 v[0:3], v[166:169], v[182:185], v[132:135]
	s_mov_b64 s[28:29], 0
	v_mfma_f32_16x16x32_bf16 v[166:169], v[174:177], v[182:185], v[140:143]
	v_mfma_f32_16x16x32_bf16 v[4:7], v[162:165], v[178:181], v[0:3]
	v_mfma_f32_16x16x32_bf16 v[0:3], v[170:173], v[178:181], v[166:169]

; #define PG8_STAGE(bufoff, gbase, voff) do { _Pragma("unroll") for (int _i = 0; _i < 2; ++_i) \
;         __builtin_amdgcn_global_load_lds((const GAS unsigned*)((const GAS char*)(gbase) + (voff)[_i]), (PG8_LAS unsigned*)(lds + (bufoff) + ldsw + _i * 8192), 16, 0, 0); } while (0)
; #define PG8_LDA(dst, b, h) do { _Pragma("unroll") for (int m = 0; m < 4; ++m) _Pragma("unroll") for (int k = 0; k < 2; ++k) dst[m][k] = *(const PG8_LAS bf16x8*)(lds + PG8_SA(b, h) + aoff + m * 2048 + k * 1024); } while (0)
; #define PG8_LDB(dst, b, h) do { _Pragma("unroll") for (int n = 0; n < 2; ++n) _Pragma("unroll") for (int k = 0; k < 2; ++k) dst[n][k] = *(const PG8_LAS bf16x8*)(lds + PG8_SB(b, h) + boff + n * 2048 + k * 1024); } while (0)
; #define PG8_MMA(ai, bj, At, Bt) do { __builtin_amdgcn_s_setprio(1); _Pragma("unroll") for (int m = 0; m < 4; ++m) _Pragma("unroll") for (int n = 0; n < 2; ++n) _Pragma("unroll") for (int k = 0; k < 2; ++k) \
;         acc[ai][bj][m][n] = __builtin_amdgcn_mfma_f32_16x16x32_bf16(Bt[n][k], At[m][k], acc[ai][bj][m][n], 0, 0, 0); __builtin_amdgcn_s_setprio(0); } while (0)
; #define PG8_WAIT_V(n) asm volatile("s_waitcnt vmcnt(" #n ")" ::: "memory")
; #define PG8_WAIT_L(n) asm volatile("s_waitcnt lgkmcnt(" #n ")" ::: "memory")
; #define PG8_BAR __builtin_amdgcn_s_barrier()
; #define PG8_SCHED __builtin_amdgcn_sched_barrier(0)
; #define PG8_LDA(dst, b, h) do { _Pragma("unroll") for (int m = 0; m < 4; ++m) _Pragma("unroll") for (int k = 0; k < 2; ++k) dst[m][k] = *(const PG8_LAS bf16x8*)(lds + PG8_SA(b, h) + aoff + m * 2048 + k * 1024); } while (0)
; template <class Epi, class Sched, bool ALIGN_EPI = false, bool SP2 = false>
; __device__ __forceinline__ void gemm_phase(PG8_LAS unsigned char* lds, PG8_LAS unsigned char* pf, const Gemm g, const Sched& S, const Epi& E, int wv) {
;     ...
;             PG8_LDB(B0, 0, 0); PG8_LDB(B1, 0, 1); PG8_SCHED; PG8_LDA(At, 0, 0); PG8_STAGE(PG8_SA(1, 1), a1 + (Sched::SPLIT ? hsA : (long)hstepA), voffA);
;             PG8_WAIT_V(8); PG8_WAIT_L(0); PG8_BAR; PG8_MMA(0, 0, At, B0); PG8_MMA(0, 1, At, B1); PG8_BAR; PG8_SCHED;
;             PG8_LDA(At, 0, 1); PG8_STAGE(PG8_SB(0, 0), b2, voffB); PG8_STAGE(PG8_SB(0, 1), b2 + hstepB, voffB); PG8_STAGE(PG8_SA(0, 0), a2, voffA);
;             PG8_WAIT_V(8); PG8_WAIT_L(0); PG8_BAR; PG8_MMA(1, 0, At, B0); PG8_MMA(1, 1, At, B1); PG8_BAR; PG8_SCHED;
.LBB0_1186:
	s_add_u32 s22, s14, 0xfff80080
	s_addc_u32 s23, s15, -1
	s_add_i32 s24, 0, 0x10000
	s_cmp_eq_u32 s21, 4
	s_cselect_b32 s29, s39, s23
	s_cselect_b32 s28, s38, s22
	s_cselect_b32 s37, s5, s20
	s_cselect_b32 s36, s11, s13
	s_add_i32 s25, 0, 0x14000
	v_add_u32_e32 v140, s24, v204
	v_add_u32_e32 v156, s25, v204
	ds_read_b128 v[120:123], v140
	ds_read_b128 v[124:127], v140 offset:1024
	ds_read_b128 v[136:139], v140 offset:2048
	ds_read_b128 v[140:143], v140 offset:3072
	ds_read_b128 v[144:147], v156
	ds_read_b128 v[148:151], v156 offset:1024
	ds_read_b128 v[152:155], v156 offset:2048
	ds_read_b128 v[156:159], v156 offset:3072
	v_lshl_add_u64 v[214:215], s[14:15], 0, v[172:173]
	s_add_i32 m0, s18, 0xc000
	ds_read_b128 v[174:177], v205
	ds_read_b128 v[178:181], v205 offset:1024
	ds_read_b128 v[182:185], v205 offset:2048
	ds_read_b128 v[186:189], v205 offset:3072
	ds_read_b128 v[190:193], v205 offset:4096
	ds_read_b128 v[194:197], v205 offset:5120
	ds_read_b128 v[198:201], v205 offset:6144
	ds_read_b128 v[206:209], v205 offset:7168
	global_load_lds_dwordx4 v[214:215], off
	v_lshl_add_u64 v[214:215], s[14:15], 0, v[170:171]
	s_add_i32 m0, s18, 0xe000
	s_nop 0
	global_load_lds_dwordx4 v[214:215], off
	s_waitcnt vmcnt(8)
	s_waitcnt lgkmcnt(0)
	s_barrier
	s_waitcnt lgkmcnt(0)
	v_mfma_f32_16x16x32_bf16 v[132:135], v[120:123], v[174:177], v[132:135]
	v_mfma_f32_16x16x32_bf16 v[128:131], v[136:139], v[174:177], v[128:131]
	v_mfma_f32_16x16x32_bf16 v[116:119], v[120:123], v[182:185], v[116:119]
	v_mfma_f32_16x16x32_bf16 v[112:115], v[136:139], v[182:185], v[112:115]
	v_mfma_f32_16x16x32_bf16 v[108:111], v[120:123], v[190:193], v[108:111]
	v_mfma_f32_16x16x32_bf16 v[104:107], v[136:139], v[190:193], v[104:107]
	v_mfma_f32_16x16x32_bf16 v[100:103], v[120:123], v[198:201], v[100:103]
	v_mfma_f32_16x16x32_bf16 v[96:99], v[136:139], v[198:201], v[96:99]
	v_mfma_f32_16x16x32_bf16 v[132:135], v[124:127], v[178:181], v[132:135]
	v_mfma_f32_16x16x32_bf16 v[128:131], v[140:143], v[178:181], v[128:131]
	v_mfma_f32_16x16x32_bf16 v[116:119], v[124:127], v[186:189], v[116:119]
	v_mfma_f32_16x16x32_bf16 v[112:115], v[140:143], v[186:189], v[112:115]
	v_mfma_f32_16x16x32_bf16 v[108:111], v[124:127], v[194:197], v[108:111]
	v_mfma_f32_16x16x32_bf16 v[104:107], v[140:143], v[194:197], v[104:107]
	v_mfma_f32_16x16x32_bf16 v[100:103], v[124:127], v[206:209], v[100:103]
	v_mfma_f32_16x16x32_bf16 v[96:99], v[140:143], v[206:209], v[96:99]
	v_mfma_f32_16x16x32_bf16 v[60:63], v[144:147], v[174:177], v[60:63]
	v_mfma_f32_16x16x32_bf16 v[56:59], v[152:155], v[174:177], v[56:59]
	v_mfma_f32_16x16x32_bf16 v[52:55], v[144:147], v[182:185], v[52:55]
	v_mfma_f32_16x16x32_bf16 v[48:51], v[152:155], v[182:185], v[48:51]
	v_mfma_f32_16x16x32_bf16 v[44:47], v[144:147], v[190:193], v[44:47]
	v_mfma_f32_16x16x32_bf16 v[40:43], v[152:155], v[190:193], v[40:43]
	v_mfma_f32_16x16x32_bf16 v[36:39], v[144:147], v[198:201], v[36:39]
	v_mfma_f32_16x16x32_bf16 v[32:35], v[152:155], v[198:201], v[32:35]
	v_mfma_f32_16x16x32_bf16 v[60:63], v[148:151], v[178:181], v[60:63]
	v_mfma_f32_16x16x32_bf16 v[56:59], v[156:159], v[178:181], v[56:59]
	v_mfma_f32_16x16x32_bf16 v[52:55], v[148:151], v[186:189], v[52:55]
	v_mfma_f32_16x16x32_bf16 v[48:51], v[156:159], v[186:189], v[48:51]
	v_mfma_f32_16x16x32_bf16 v[44:47], v[148:151], v[194:197], v[44:47]
	v_mfma_f32_16x16x32_bf16 v[40:43], v[156:159], v[194:197], v[40:43]
	v_mfma_f32_16x16x32_bf16 v[36:39], v[148:151], v[206:209], v[36:39]
	v_mfma_f32_16x16x32_bf16 v[32:35], v[156:159], v[206:209], v[32:35]
	s_barrier
	s_add_i32 s22, s24, s81
	v_lshl_add_u64 v[214:215], s[36:37], 0, v[164:165]
	s_mov_b32 m0, s22
	ds_read_b128 v[174:177], v205 offset:16384
	ds_read_b128 v[178:181], v205 offset:17408
	ds_read_b128 v[182:185], v205 offset:18432
	ds_read_b128 v[186:189], v205 offset:19456
	ds_read_b128 v[190:193], v205 offset:20480
	ds_read_b128 v[194:197], v205 offset:21504
	ds_read_b128 v[198:201], v205 offset:22528
	ds_read_b128 v[206:209], v205 offset:23552
	global_load_lds_dwordx4 v[214:215], off
	s_add_i32 m0, s22, 0x2000
	s_add_u32 s22, s36, 0x20000
	v_lshl_add_u64 v[216:217], s[36:37], 0, v[168:169]
	s_addc_u32 s23, s37, 0
	s_add_i32 s24, s25, s81
	global_load_lds_dwordx4 v[216:217], off
	v_lshl_add_u64 v[218:219], s[22:23], 0, v[164:165]
	s_mov_b32 m0, s24
	v_lshl_add_u64 v[220:221], s[28:29], 0, v[166:167]
	global_load_lds_dwordx4 v[218:219], off
	v_lshl_add_u64 v[218:219], s[22:23], 0, v[168:169]
	s_add_i32 m0, s24, 0x2000
	s_nop 0
	global_load_lds_dwordx4 v[218:219], off
	v_lshl_add_u64 v[218:219], s[28:29], 0, v[162:163]
	s_mov_b32 m0, s18
	s_nop 0
	global_load_lds_dwordx4 v[218:219], off
	s_mov_b32 m0, s19
	s_nop 0
	global_load_lds_dwordx4 v[220:221], off
	s_waitcnt vmcnt(8)
	s_waitcnt lgkmcnt(0)
	s_barrier
; #define PG8_STAGE(bufoff, gbase, voff) do { _Pragma("unroll") for (int _i = 0; _i < 2; ++_i) \
;         __builtin_amdgcn_global_load_lds((const GAS unsigned*)((const GAS char*)(gbase) + (voff)[_i]), (PG8_LAS unsigned*)(lds + (bufoff) + ldsw + _i * 8192), 16, 0, 0); } while (0)
; #define PG8_LDA(dst, b, h) do { _Pragma("unroll") for (int m = 0; m < 4; ++m) _Pragma("unroll") for (int k = 0; k < 2; ++k) dst[m][k] = *(const PG8_LAS bf16x8*)(lds + PG8_SA(b, h) + aoff + m * 2048 + k * 1024); } while (0)
; #define PG8_LDB(dst, b, h) do { _Pragma("unroll") for (int n = 0; n < 2; ++n) _Pragma("unroll") for (int k = 0; k < 2; ++k) dst[n][k] = *(const PG8_LAS bf16x8*)(lds + PG8_SB(b, h) + boff + n * 2048 + k * 1024); } while (0)
; #define PG8_MMA(ai, bj, At, Bt) do { __builtin_amdgcn_s_setprio(1); _Pragma("unroll") for (int m = 0; m < 4; ++m) _Pragma("unroll") for (int n = 0; n < 2; ++n) _Pragma("unroll") for (int k = 0; k < 2; ++k) \
;         acc[ai][bj][m][n] = __builtin_amdgcn_mfma_f32_16x16x32_bf16(Bt[n][k], At[m][k], acc[ai][bj][m][n], 0, 0, 0); __builtin_amdgcn_s_setprio(0); } while (0)
; #define PG8_WAIT_V(n) asm volatile("s_waitcnt vmcnt(" #n ")" ::: "memory")
; #define PG8_WAIT_L(n) asm volatile("s_waitcnt lgkmcnt(" #n ")" ::: "memory")
; #define PG8_BAR __builtin_amdgcn_s_barrier()
; #define PG8_SCHED __builtin_amdgcn_sched_barrier(0)
; #define PG8_STAGE(bufoff, gbase, voff) do { _Pragma("unroll") for (int _i = 0; _i < 2; ++_i) \
;         __builtin_amdgcn_global_load_lds((const GAS unsigned*)((const GAS char*)(gbase) + (voff)[_i]), (PG8_LAS unsigned*)(lds + (bufoff) + ldsw + _i * 8192), 16, 0, 0); } while (0)
; #define PG8_BAR __builtin_amdgcn_s_barrier()
; template <class Epi, class Sched, bool ALIGN_EPI = false, bool SP2 = false>
; __device__ __forceinline__ void gemm_phase(PG8_LAS unsigned char* lds, PG8_LAS unsigned char* pf, const Gemm g, const Sched& S, const Epi& E, int wv) {
;     ...
;             PG8_WAIT_V(8); PG8_WAIT_L(0); PG8_BAR; PG8_MMA(1, 0, At, B0); PG8_MMA(1, 1, At, B1); PG8_BAR; PG8_SCHED;
;             PG8_LDB(B0, 1, 0); PG8_LDB(B1, 1, 1); PG8_SCHED; PG8_LDA(At, 1, 0); PG8_STAGE(PG8_SA(0, 1), a2 + (Sched::SPLIT ? ((last && has_next) ? (nxt.kh > 0 ? -(long)hstepA : (long)hstepA) : hsA) : (long)hstepA), voffA);
;             PG8_WAIT_V(8); PG8_WAIT_L(0); PG8_BAR; PG8_MMA(0, 0, At, B0); PG8_MMA(0, 1, At, B1); PG8_BAR; PG8_SCHED;
	s_waitcnt lgkmcnt(0)
	v_mfma_f32_16x16x32_bf16 v[92:95], v[120:123], v[174:177], v[92:95]
	v_mfma_f32_16x16x32_bf16 v[88:91], v[136:139], v[174:177], v[88:91]
	v_mfma_f32_16x16x32_bf16 v[84:87], v[120:123], v[182:185], v[84:87]
	v_mfma_f32_16x16x32_bf16 v[80:83], v[136:139], v[182:185], v[80:83]
	v_mfma_f32_16x16x32_bf16 v[76:79], v[120:123], v[190:193], v[76:79]
	v_mfma_f32_16x16x32_bf16 v[72:75], v[136:139], v[190:193], v[72:75]
	v_mfma_f32_16x16x32_bf16 v[68:71], v[120:123], v[198:201], v[68:71]
	v_mfma_f32_16x16x32_bf16 v[64:67], v[136:139], v[198:201], v[64:67]
	v_mfma_f32_16x16x32_bf16 v[92:95], v[124:127], v[178:181], v[92:95]
	v_mfma_f32_16x16x32_bf16 v[88:91], v[140:143], v[178:181], v[88:91]
	v_mfma_f32_16x16x32_bf16 v[84:87], v[124:127], v[186:189], v[84:87]
	v_mfma_f32_16x16x32_bf16 v[80:83], v[140:143], v[186:189], v[80:83]
	v_mfma_f32_16x16x32_bf16 v[76:79], v[124:127], v[194:197], v[76:79]
	v_mfma_f32_16x16x32_bf16 v[72:75], v[140:143], v[194:197], v[72:75]
	v_mfma_f32_16x16x32_bf16 v[68:71], v[124:127], v[206:209], v[68:71]
	v_mfma_f32_16x16x32_bf16 v[64:67], v[140:143], v[206:209], v[64:67]
	v_mfma_f32_16x16x32_bf16 v[28:31], v[144:147], v[174:177], v[28:31]
	v_mfma_f32_16x16x32_bf16 v[24:27], v[152:155], v[174:177], v[24:27]
	v_mfma_f32_16x16x32_bf16 v[20:23], v[144:147], v[182:185], v[20:23]
	v_mfma_f32_16x16x32_bf16 v[16:19], v[152:155], v[182:185], v[16:19]
	v_mfma_f32_16x16x32_bf16 v[12:15], v[144:147], v[190:193], v[12:15]
	v_mfma_f32_16x16x32_bf16 v[8:11], v[152:155], v[190:193], v[8:11]
	v_mfma_f32_16x16x32_bf16 v[4:7], v[144:147], v[198:201], v[4:7]
	v_mfma_f32_16x16x32_bf16 v[0:3], v[152:155], v[198:201], v[0:3]
	v_mfma_f32_16x16x32_bf16 v[28:31], v[148:151], v[178:181], v[28:31]
	v_mfma_f32_16x16x32_bf16 v[24:27], v[156:159], v[178:181], v[24:27]
	v_mfma_f32_16x16x32_bf16 v[20:23], v[148:151], v[186:189], v[20:23]
	v_mfma_f32_16x16x32_bf16 v[16:19], v[156:159], v[186:189], v[16:19]
	v_mfma_f32_16x16x32_bf16 v[12:15], v[148:151], v[194:197], v[12:15]
	v_mfma_f32_16x16x32_bf16 v[8:11], v[156:159], v[194:197], v[8:11]
	v_mfma_f32_16x16x32_bf16 v[4:7], v[148:151], v[206:209], v[4:7]
	v_mfma_f32_16x16x32_bf16 v[0:3], v[156:159], v[206:209], v[0:3]
	s_barrier
	s_add_i32 s24, 0, 0x18000
	s_add_i32 s25, 0, 0x1c000
	v_add_u32_e32 v140, s24, v204
	v_add_u32_e32 v156, s25, v204
	ds_read_b128 v[120:123], v140
	ds_read_b128 v[124:127], v140 offset:1024
	ds_read_b128 v[136:139], v140 offset:2048
	ds_read_b128 v[140:143], v140 offset:3072
	ds_read_b128 v[144:147], v156
	ds_read_b128 v[148:151], v156 offset:1024
	ds_read_b128 v[152:155], v156 offset:2048
	ds_read_b128 v[156:159], v156 offset:3072
	s_add_u32 s22, s28, 0x80000
	s_addc_u32 s23, s29, 0
	s_mov_b32 m0, s27
	v_lshl_add_u64 v[222:223], s[22:23], 0, v[162:163]
	ds_read_b128 v[174:177], v205 offset:32768
	ds_read_b128 v[178:181], v205 offset:33792
	ds_read_b128 v[182:185], v205 offset:34816
	ds_read_b128 v[186:189], v205 offset:35840
	ds_read_b128 v[190:193], v205 offset:36864
	ds_read_b128 v[194:197], v205 offset:37888
	ds_read_b128 v[198:201], v205 offset:38912
	ds_read_b128 v[206:209], v205 offset:39936
	global_load_lds_dwordx4 v[222:223], off
	v_lshl_add_u64 v[222:223], s[22:23], 0, v[166:167]
	s_mov_b32 m0, s52
	s_nop 0
	global_load_lds_dwordx4 v[222:223], off
	s_waitcnt vmcnt(8)
	s_waitcnt lgkmcnt(0)
	s_barrier
	s_waitcnt lgkmcnt(0)
	v_mfma_f32_16x16x32_bf16 v[132:135], v[120:123], v[174:177], v[132:135]
	v_mfma_f32_16x16x32_bf16 v[128:131], v[136:139], v[174:177], v[128:131]
	v_mfma_f32_16x16x32_bf16 v[116:119], v[120:123], v[182:185], v[116:119]
	v_mfma_f32_16x16x32_bf16 v[112:115], v[136:139], v[182:185], v[112:115]
	v_mfma_f32_16x16x32_bf16 v[108:111], v[120:123], v[190:193], v[108:111]
	v_mfma_f32_16x16x32_bf16 v[104:107], v[136:139], v[190:193], v[104:107]
	v_mfma_f32_16x16x32_bf16 v[100:103], v[120:123], v[198:201], v[100:103]
	v_mfma_f32_16x16x32_bf16 v[96:99], v[136:139], v[198:201], v[96:99]
	v_mfma_f32_16x16x32_bf16 v[132:135], v[124:127], v[178:181], v[132:135]
	v_mfma_f32_16x16x32_bf16 v[128:131], v[140:143], v[178:181], v[128:131]
	v_mfma_f32_16x16x32_bf16 v[116:119], v[124:127], v[186:189], v[116:119]
	v_mfma_f32_16x16x32_bf16 v[112:115], v[140:143], v[186:189], v[112:115]
	v_mfma_f32_16x16x32_bf16 v[108:111], v[124:127], v[194:197], v[108:111]
	v_mfma_f32_16x16x32_bf16 v[104:107], v[140:143], v[194:197], v[104:107]
	v_mfma_f32_16x16x32_bf16 v[100:103], v[124:127], v[206:209], v[100:103]
	v_mfma_f32_16x16x32_bf16 v[96:99], v[140:143], v[206:209], v[96:99]
	v_mfma_f32_16x16x32_bf16 v[60:63], v[144:147], v[174:177], v[60:63]
	v_mfma_f32_16x16x32_bf16 v[56:59], v[152:155], v[174:177], v[56:59]
	v_mfma_f32_16x16x32_bf16 v[52:55], v[144:147], v[182:185], v[52:55]
	v_mfma_f32_16x16x32_bf16 v[48:51], v[152:155], v[182:185], v[48:51]
	v_mfma_f32_16x16x32_bf16 v[44:47], v[144:147], v[190:193], v[44:47]
	v_mfma_f32_16x16x32_bf16 v[40:43], v[152:155], v[190:193], v[40:43]
	v_mfma_f32_16x16x32_bf16 v[36:39], v[144:147], v[198:201], v[36:39]
	v_mfma_f32_16x16x32_bf16 v[32:35], v[152:155], v[198:201], v[32:35]
	v_mfma_f32_16x16x32_bf16 v[60:63], v[148:151], v[178:181], v[60:63]
	v_mfma_f32_16x16x32_bf16 v[56:59], v[156:159], v[178:181], v[56:59]
	v_mfma_f32_16x16x32_bf16 v[52:55], v[148:151], v[186:189], v[52:55]
	v_mfma_f32_16x16x32_bf16 v[48:51], v[156:159], v[186:189], v[48:51]
	v_mfma_f32_16x16x32_bf16 v[44:47], v[148:151], v[194:197], v[44:47]
	v_mfma_f32_16x16x32_bf16 v[40:43], v[156:159], v[194:197], v[40:43]
	v_mfma_f32_16x16x32_bf16 v[36:39], v[148:151], v[206:209], v[36:39]
	v_mfma_f32_16x16x32_bf16 v[32:35], v[156:159], v[206:209], v[32:35]
	s_barrier
; #define PG8_STAGE(bufoff, gbase, voff) do { _Pragma("unroll") for (int _i = 0; _i < 2; ++_i) \
;         __builtin_amdgcn_global_load_lds((const GAS unsigned*)((const GAS char*)(gbase) + (voff)[_i]), (PG8_LAS unsigned*)(lds + (bufoff) + ldsw + _i * 8192), 16, 0, 0); } while (0)
; #define PG8_LDA(dst, b, h) do { _Pragma("unroll") for (int m = 0; m < 4; ++m) _Pragma("unroll") for (int k = 0; k < 2; ++k) dst[m][k] = *(const PG8_LAS bf16x8*)(lds + PG8_SA(b, h) + aoff + m * 2048 + k * 1024); } while (0)
; #define PG8_MMA(ai, bj, At, Bt) do { __builtin_amdgcn_s_setprio(1); _Pragma("unroll") for (int m = 0; m < 4; ++m) _Pragma("unroll") for (int n = 0; n < 2; ++n) _Pragma("unroll") for (int k = 0; k < 2; ++k) \
;         acc[ai][bj][m][n] = __builtin_amdgcn_mfma_f32_16x16x32_bf16(Bt[n][k], At[m][k], acc[ai][bj][m][n], 0, 0, 0); __builtin_amdgcn_s_setprio(0); } while (0)
; #define PG8_WAIT_V(n) asm volatile("s_waitcnt vmcnt(" #n ")" ::: "memory")
; #define PG8_WAIT_L(n) asm volatile("s_waitcnt lgkmcnt(" #n ")" ::: "memory")
; #define PG8_BAR __builtin_amdgcn_s_barrier()
; #define PG8_SCHED __builtin_amdgcn_sched_barrier(0)
; #define PG8_STAGE(bufoff, gbase, voff) do { _Pragma("unroll") for (int _i = 0; _i < 2; ++_i) \
;         __builtin_amdgcn_global_load_lds((const GAS unsigned*)((const GAS char*)(gbase) + (voff)[_i]), (PG8_LAS unsigned*)(lds + (bufoff) + ldsw + _i * 8192), 16, 0, 0); } while (0)
; #define PG8_LDA(dst, b, h) do { _Pragma("unroll") for (int m = 0; m < 4; ++m) _Pragma("unroll") for (int k = 0; k < 2; ++k) dst[m][k] = *(const PG8_LAS bf16x8*)(lds + PG8_SA(b, h) + aoff + m * 2048 + k * 1024); } while (0)
; #define PG8_WAIT_V(n) asm volatile("s_waitcnt vmcnt(" #n ")" ::: "memory")
; #define PG8_WAIT_L(n) asm volatile("s_waitcnt lgkmcnt(" #n ")" ::: "memory")
; #define PG8_BAR __builtin_amdgcn_s_barrier()
; #define PG8_SCHED __builtin_amdgcn_sched_barrier(0)
; template <class Epi, class Sched, bool ALIGN_EPI = false, bool SP2 = false>
; __device__ __forceinline__ void gemm_phase(PG8_LAS unsigned char* lds, PG8_LAS unsigned char* pf, const Gemm g, const Sched& S, const Epi& E, int wv) {
;     ...
;             PG8_LDA(At, 1, 1); PG8_STAGE(PG8_SB(1, 0), b3, voffB); PG8_STAGE(PG8_SB(1, 1), b3 + hstepB, voffB); PG8_STAGE(PG8_SA(1, 0), a3, voffA);
;             PG8_WAIT_V(8); PG8_WAIT_L(0); PG8_BAR; PG8_MMA(1, 0, At, B0); PG8_MMA(1, 1, At, B1); PG8_BAR; PG8_SCHED;
	s_add_i32 s22, s24, s81
	v_lshl_add_u64 v[214:215], v[214:215], 0, s[16:17]
	s_mov_b32 m0, s22
	ds_read_b128 v[174:177], v205 offset:49152
	ds_read_b128 v[178:181], v205 offset:50176
	ds_read_b128 v[182:185], v205 offset:51200
	ds_read_b128 v[186:189], v205 offset:52224
	ds_read_b128 v[190:193], v205 offset:53248
	ds_read_b128 v[194:197], v205 offset:54272
	ds_read_b128 v[198:201], v205 offset:55296
	ds_read_b128 v[206:209], v205 offset:56320
	global_load_lds_dwordx4 v[214:215], off
	s_add_i32 m0, s22, 0x2000
	s_add_u32 s22, s36, 0x20080
	v_lshl_add_u64 v[214:215], v[216:217], 0, s[16:17]
	s_addc_u32 s23, s37, 0
	s_add_i32 s24, s25, s81
	global_load_lds_dwordx4 v[214:215], off
	v_lshl_add_u64 v[214:215], s[22:23], 0, v[164:165]
	s_mov_b32 m0, s24
	s_nop 0
	global_load_lds_dwordx4 v[214:215], off
	v_lshl_add_u64 v[214:215], s[22:23], 0, v[168:169]
	s_add_i32 m0, s24, 0x2000
	s_nop 0
	global_load_lds_dwordx4 v[214:215], off
	v_lshl_add_u64 v[214:215], v[218:219], 0, s[16:17]
	s_mov_b32 m0, s55
	s_nop 0
	global_load_lds_dwordx4 v[214:215], off
	v_lshl_add_u64 v[214:215], v[220:221], 0, s[16:17]
	s_mov_b32 m0, s56
	s_nop 0
	global_load_lds_dwordx4 v[214:215], off
	s_waitcnt vmcnt(8)
	s_waitcnt lgkmcnt(0)
	s_barrier
	s_waitcnt lgkmcnt(0)
	v_mfma_f32_16x16x32_bf16 v[92:95], v[120:123], v[174:177], v[92:95]
	v_mfma_f32_16x16x32_bf16 v[88:91], v[136:139], v[174:177], v[88:91]
	v_mfma_f32_16x16x32_bf16 v[84:87], v[120:123], v[182:185], v[84:87]
	v_mfma_f32_16x16x32_bf16 v[80:83], v[136:139], v[182:185], v[80:83]
	v_mfma_f32_16x16x32_bf16 v[76:79], v[120:123], v[190:193], v[76:79]
	v_mfma_f32_16x16x32_bf16 v[72:75], v[136:139], v[190:193], v[72:75]
	v_mfma_f32_16x16x32_bf16 v[68:71], v[120:123], v[198:201], v[68:71]
	v_mfma_f32_16x16x32_bf16 v[64:67], v[136:139], v[198:201], v[64:67]
	v_mfma_f32_16x16x32_bf16 v[92:95], v[124:127], v[178:181], v[92:95]
	v_mfma_f32_16x16x32_bf16 v[88:91], v[140:143], v[178:181], v[88:91]
	v_mfma_f32_16x16x32_bf16 v[84:87], v[124:127], v[186:189], v[84:87]
	v_mfma_f32_16x16x32_bf16 v[80:83], v[140:143], v[186:189], v[80:83]
	v_mfma_f32_16x16x32_bf16 v[76:79], v[124:127], v[194:197], v[76:79]
	v_mfma_f32_16x16x32_bf16 v[72:75], v[140:143], v[194:197], v[72:75]
	v_mfma_f32_16x16x32_bf16 v[68:71], v[124:127], v[206:209], v[68:71]
	v_mfma_f32_16x16x32_bf16 v[64:67], v[140:143], v[206:209], v[64:67]
	v_mfma_f32_16x16x32_bf16 v[28:31], v[144:147], v[174:177], v[28:31]
	v_mfma_f32_16x16x32_bf16 v[24:27], v[152:155], v[174:177], v[24:27]
	v_mfma_f32_16x16x32_bf16 v[20:23], v[144:147], v[182:185], v[20:23]
	v_mfma_f32_16x16x32_bf16 v[16:19], v[152:155], v[182:185], v[16:19]
	v_mfma_f32_16x16x32_bf16 v[12:15], v[144:147], v[190:193], v[12:15]
	v_mfma_f32_16x16x32_bf16 v[8:11], v[152:155], v[190:193], v[8:11]
	v_mfma_f32_16x16x32_bf16 v[4:7], v[144:147], v[198:201], v[4:7]
	v_mfma_f32_16x16x32_bf16 v[0:3], v[152:155], v[198:201], v[0:3]
	v_mfma_f32_16x16x32_bf16 v[28:31], v[148:151], v[178:181], v[28:31]
	v_mfma_f32_16x16x32_bf16 v[24:27], v[156:159], v[178:181], v[24:27]
	v_mfma_f32_16x16x32_bf16 v[20:23], v[148:151], v[186:189], v[20:23]
	v_mfma_f32_16x16x32_bf16 v[16:19], v[156:159], v[186:189], v[16:19]
	v_mfma_f32_16x16x32_bf16 v[12:15], v[148:151], v[194:197], v[12:15]
	v_mfma_f32_16x16x32_bf16 v[8:11], v[156:159], v[194:197], v[8:11]
	v_mfma_f32_16x16x32_bf16 v[4:7], v[148:151], v[206:209], v[4:7]
	v_mfma_f32_16x16x32_bf16 v[0:3], v[156:159], v[206:209], v[0:3]
	s_barrier
	s_add_i32 s21, s21, 2
	s_add_u32 s13, s13, 0x100
	s_addc_u32 s20, s20, 0
	s_add_u32 s14, s14, 0x100
	s_addc_u32 s15, s15, 0
	s_cmp_gt_u32 s21, 5
	s_cbranch_scc0 .LBB0_1186
	s_and_b64 vcc, exec, s[6:7]
	s_cbranch_vccz .LBB0_1189
	s_barrier

; #define PG8_STAGE(bufoff, gbase, voff) do { _Pragma("unroll") for (int _i = 0; _i < 2; ++_i) \
;         __builtin_amdgcn_global_load_lds((const GAS unsigned*)((const GAS char*)(gbase) + (voff)[_i]), (PG8_LAS unsigned*)(lds + (bufoff) + ldsw + _i * 8192), 16, 0, 0); } while (0)
; #define PG8_LDA(dst, b, h) do { _Pragma("unroll") for (int m = 0; m < 4; ++m) _Pragma("unroll") for (int k = 0; k < 2; ++k) dst[m][k] = *(const PG8_LAS bf16x8*)(lds + PG8_SA(b, h) + aoff + m * 2048 + k * 1024); } while (0)
; #define PG8_LDB(dst, b, h) do { _Pragma("unroll") for (int n = 0; n < 2; ++n) _Pragma("unroll") for (int k = 0; k < 2; ++k) dst[n][k] = *(const PG8_LAS bf16x8*)(lds + PG8_SB(b, h) + boff + n * 2048 + k * 1024); } while (0)
; #define PG8_MMA(ai, bj, At, Bt) do { __builtin_amdgcn_s_setprio(1); _Pragma("unroll") for (int m = 0; m < 4; ++m) _Pragma("unroll") for (int n = 0; n < 2; ++n) _Pragma("unroll") for (int k = 0; k < 2; ++k) \
;         acc[ai][bj][m][n] = __builtin_amdgcn_mfma_f32_16x16x32_bf16(Bt[n][k], At[m][k], acc[ai][bj][m][n], 0, 0, 0); __builtin_amdgcn_s_setprio(0); } while (0)
; #define PG8_WAIT_V(n) asm volatile("s_waitcnt vmcnt(" #n ")" ::: "memory")
; #define PG8_WAIT_L(n) asm volatile("s_waitcnt lgkmcnt(" #n ")" ::: "memory")
; #define PG8_BAR __builtin_amdgcn_s_barrier()
; #define PG8_SCHED __builtin_amdgcn_sched_barrier(0)
; #define PG8_STAGE(bufoff, gbase, voff) do { _Pragma("unroll") for (int _i = 0; _i < 2; ++_i) \
;         __builtin_amdgcn_global_load_lds((const GAS unsigned*)((const GAS char*)(gbase) + (voff)[_i]), (PG8_LAS unsigned*)(lds + (bufoff) + ldsw + _i * 8192), 16, 0, 0); } while (0)
; #define PG8_LDA(dst, b, h) do { _Pragma("unroll") for (int m = 0; m < 4; ++m) _Pragma("unroll") for (int k = 0; k < 2; ++k) dst[m][k] = *(const PG8_LAS bf16x8*)(lds + PG8_SA(b, h) + aoff + m * 2048 + k * 1024); } while (0)
; #define PG8_BAR __builtin_amdgcn_s_barrier()
; template <class Epi, class Sched>
; __device__ __forceinline__ void gemm_phase_strip(PG8_LAS unsigned char* lds, PG8_LAS unsigned char* slds, PG8_LAS unsigned char* pf, const Gemm g, const Sched& S, const Epi& E, int wv) {
;     ...
;             PG8_LDB(B0, 0, 0); PG8_LDB(B1, 0, 1); PG8_SCHED; PG8_LDA(At, 0, 0); PG8_STAGE(PG8_SA(1, 1), a1 + PG8_HS, voffA);
;             PG8_WAIT_V(8); PG8_WAIT_L(0); PG8_BAR; PG8_MMA(0, 0, At, B0); PG8_MMA(0, 1, At, B1); PG8_BAR; PG8_SCHED;
.LBB0_1304:
	s_barrier
	s_xor_b32 s91, s91, 0x1000
	s_add_i32 s22, s22, 2
	s_add_u32 s52, s52, 0x100
	s_addc_u32 s53, s53, 0
	s_cmp_gt_u32 s22, 29
	s_cbranch_scc1 .LBB0_1315
.LBB0_1305:
	s_add_u32 s23, s14, s52
	s_addc_u32 s24, s15, s53
	s_add_u32 s23, s23, 0x100
	s_addc_u32 s28, s24, 0
	s_add_u32 s31, s20, s52
	s_addc_u32 s38, s21, s53
	s_add_i32 s39, 0, 0x10000
	s_add_i32 s41, 0, 0x14000
	v_add_u32_e32 v128, s39, v233
	ds_read_b128 v[148:151], v128
	ds_read_b128 v[144:147], v128 offset:1024
	ds_read_b128 v[166:169], v128 offset:2048
	ds_read_b128 v[162:165], v128 offset:3072
	v_add_u32_e32 v128, s41, v233
	ds_read_b128 v[156:159], v128
	ds_read_b128 v[152:155], v128 offset:1024
	ds_read_b128 v[174:177], v128 offset:2048
	ds_read_b128 v[170:173], v128 offset:3072
	s_cmpk_eq_i32 s52, 0xf00
	s_cselect_b64 s[56:57], -1, 0
	s_and_b64 s[24:25], s[56:57], exec
	s_cselect_b32 s29, s43, s28
	s_cselect_b32 s28, s42, s23
	s_cselect_b32 s55, s1, s38
	s_cselect_b32 s54, s5, s31
	v_lshl_add_u64 v[222:223], v[220:221], 0, s[52:53]
	s_add_i32 m0, s64, 0xc000
	ds_read_b128 v[128:131], v236
	ds_read_b128 v[136:139], v236 offset:1024
	ds_read_b128 v[178:181], v236 offset:2048
	ds_read_b128 v[182:185], v236 offset:3072
	ds_read_b128 v[186:189], v236 offset:4096
	ds_read_b128 v[190:193], v236 offset:5120
	ds_read_b128 v[194:197], v236 offset:6144
	ds_read_b128 v[198:201], v236 offset:7168
	global_load_lds_dwordx4 v[222:223], off
	v_lshl_add_u64 v[222:223], v[218:219], 0, s[52:53]
	s_add_i32 m0, s64, 0xe000
	s_nop 0
	global_load_lds_dwordx4 v[222:223], off
	s_waitcnt vmcnt(8)
	s_waitcnt lgkmcnt(0)
	s_barrier
	s_waitcnt lgkmcnt(0)
	v_mfma_f32_16x16x32_bf16 v[140:143], v[148:151], v[128:131], v[140:143]
	v_mfma_f32_16x16x32_bf16 v[132:135], v[166:169], v[128:131], v[132:135]
	v_mfma_f32_16x16x32_bf16 v[124:127], v[148:151], v[178:181], v[124:127]
	v_mfma_f32_16x16x32_bf16 v[120:123], v[166:169], v[178:181], v[120:123]
	v_mfma_f32_16x16x32_bf16 v[116:119], v[148:151], v[186:189], v[116:119]
	v_mfma_f32_16x16x32_bf16 v[112:115], v[166:169], v[186:189], v[112:115]
	v_mfma_f32_16x16x32_bf16 v[108:111], v[148:151], v[194:197], v[108:111]
	v_mfma_f32_16x16x32_bf16 v[104:107], v[166:169], v[194:197], v[104:107]
	v_mfma_f32_16x16x32_bf16 v[140:143], v[144:147], v[136:139], v[140:143]
	v_mfma_f32_16x16x32_bf16 v[132:135], v[162:165], v[136:139], v[132:135]
	v_mfma_f32_16x16x32_bf16 v[124:127], v[144:147], v[182:185], v[124:127]
	v_mfma_f32_16x16x32_bf16 v[120:123], v[162:165], v[182:185], v[120:123]
	v_mfma_f32_16x16x32_bf16 v[116:119], v[144:147], v[190:193], v[116:119]
	v_mfma_f32_16x16x32_bf16 v[112:115], v[162:165], v[190:193], v[112:115]
	v_mfma_f32_16x16x32_bf16 v[108:111], v[144:147], v[198:201], v[108:111]
	v_mfma_f32_16x16x32_bf16 v[104:107], v[162:165], v[198:201], v[104:107]
	v_mfma_f32_16x16x32_bf16 v[68:71], v[156:159], v[128:131], v[68:71]
	v_mfma_f32_16x16x32_bf16 v[64:67], v[174:177], v[128:131], v[64:67]
	v_mfma_f32_16x16x32_bf16 v[60:63], v[156:159], v[178:181], v[60:63]
	v_mfma_f32_16x16x32_bf16 v[56:59], v[174:177], v[178:181], v[56:59]
	v_mfma_f32_16x16x32_bf16 v[52:55], v[156:159], v[186:189], v[52:55]
	v_mfma_f32_16x16x32_bf16 v[48:51], v[174:177], v[186:189], v[48:51]
	v_mfma_f32_16x16x32_bf16 v[44:47], v[156:159], v[194:197], v[44:47]
	v_mfma_f32_16x16x32_bf16 v[40:43], v[174:177], v[194:197], v[40:43]
	v_mfma_f32_16x16x32_bf16 v[68:71], v[152:155], v[136:139], v[68:71]
	v_mfma_f32_16x16x32_bf16 v[64:67], v[170:173], v[136:139], v[64:67]
	v_mfma_f32_16x16x32_bf16 v[60:63], v[152:155], v[182:185], v[60:63]
	v_mfma_f32_16x16x32_bf16 v[56:59], v[170:173], v[182:185], v[56:59]
	v_mfma_f32_16x16x32_bf16 v[52:55], v[152:155], v[190:193], v[52:55]
	v_mfma_f32_16x16x32_bf16 v[48:51], v[170:173], v[190:193], v[48:51]
	v_mfma_f32_16x16x32_bf16 v[44:47], v[152:155], v[198:201], v[44:47]
	v_mfma_f32_16x16x32_bf16 v[40:43], v[170:173], v[198:201], v[40:43]
	s_barrier
; #define PG8_STAGE(bufoff, gbase, voff) do { _Pragma("unroll") for (int _i = 0; _i < 2; ++_i) \
;         __builtin_amdgcn_global_load_lds((const GAS unsigned*)((const GAS char*)(gbase) + (voff)[_i]), (PG8_LAS unsigned*)(lds + (bufoff) + ldsw + _i * 8192), 16, 0, 0); } while (0)
; #define PG8_LDA(dst, b, h) do { _Pragma("unroll") for (int m = 0; m < 4; ++m) _Pragma("unroll") for (int k = 0; k < 2; ++k) dst[m][k] = *(const PG8_LAS bf16x8*)(lds + PG8_SA(b, h) + aoff + m * 2048 + k * 1024); } while (0)
; #define PG8_MMA(ai, bj, At, Bt) do { __builtin_amdgcn_s_setprio(1); _Pragma("unroll") for (int m = 0; m < 4; ++m) _Pragma("unroll") for (int n = 0; n < 2; ++n) _Pragma("unroll") for (int k = 0; k < 2; ++k) \
;         acc[ai][bj][m][n] = __builtin_amdgcn_mfma_f32_16x16x32_bf16(Bt[n][k], At[m][k], acc[ai][bj][m][n], 0, 0, 0); __builtin_amdgcn_s_setprio(0); } while (0)
; #define PG8_WAIT_V(n) asm volatile("s_waitcnt vmcnt(" #n ")" ::: "memory")
; #define PG8_WAIT_L(n) asm volatile("s_waitcnt lgkmcnt(" #n ")" ::: "memory")
; #define PG8_BAR __builtin_amdgcn_s_barrier()
; #define PG8_SCHED __builtin_amdgcn_sched_barrier(0)
; #define PG8_STAGE(bufoff, gbase, voff) do { _Pragma("unroll") for (int _i = 0; _i < 2; ++_i) \
;         __builtin_amdgcn_global_load_lds((const GAS unsigned*)((const GAS char*)(gbase) + (voff)[_i]), (PG8_LAS unsigned*)(lds + (bufoff) + ldsw + _i * 8192), 16, 0, 0); } while (0)
; #define PG8_LDA(dst, b, h) do { _Pragma("unroll") for (int m = 0; m < 4; ++m) _Pragma("unroll") for (int k = 0; k < 2; ++k) dst[m][k] = *(const PG8_LAS bf16x8*)(lds + PG8_SA(b, h) + aoff + m * 2048 + k * 1024); } while (0)
; #define PG8_LDS_S(dst, boffs) do { dst[0] = *(const PG8_LAS bf16x8*)(slds + (boffs) + soff0); dst[1] = *(const PG8_LAS bf16x8*)(slds + (boffs) + (soff0 ^ 64)); } while (0)
; #define PG8_BAR __builtin_amdgcn_s_barrier()
; template <class Epi, class Sched>
; __device__ __forceinline__ void gemm_phase_strip(PG8_LAS unsigned char* lds, PG8_LAS unsigned char* slds, PG8_LAS unsigned char* pf, const Gemm g, const Sched& S, const Epi& E, int wv) {
;     ...
;             PG8_LDA(At, 0, 1); PG8_LDS_S(As, sq); PG8_STAGE(PG8_SB(0, 0), b2, voffB); PG8_STAGE(PG8_SB(0, 1), b2 + hstepB, voffB); PG8_STAGE(PG8_SA(0, 0), a2, voffA);
;             PG8_WAIT_V(8); PG8_WAIT_L(0); PG8_BAR; PG8_MMA(1, 0, At, B0); PG8_MMA(1, 1, At, B1); PG8_MMA_S(); PG8_BAR; PG8_SCHED;
	s_add_i32 s23, s91, 0
	s_add_i32 s23, s23, 0x21000
	v_add_u32_e32 v160, s23, v234
	v_add_u32_e32 v237, s23, v235
	s_add_i32 s23, s39, s62
	v_lshl_add_u64 v[222:223], s[54:55], 0, v[204:205]
	s_mov_b32 m0, s23
	ds_read_b128 v[128:131], v236 offset:16384
	ds_read_b128 v[136:139], v236 offset:17408
	ds_read_b128 v[186:189], v236 offset:18432
	ds_read_b128 v[190:193], v236 offset:19456
	ds_read_b128 v[194:197], v236 offset:20480
	ds_read_b128 v[198:201], v236 offset:21504
	ds_read_b128 v[242:245], v236 offset:22528
	ds_read_b128 v[246:249], v236 offset:23552
	ds_read_b128 v[182:185], v160
	ds_read_b128 v[178:181], v237
	global_load_lds_dwordx4 v[222:223], off
	s_add_i32 m0, s23, 0x2000
	s_add_u32 s24, s54, 0x80000
	v_lshl_add_u64 v[224:225], s[54:55], 0, v[208:209]
	s_addc_u32 s25, s55, 0
	s_add_i32 s23, s41, s62
	global_load_lds_dwordx4 v[224:225], off
	v_lshl_add_u64 v[226:227], s[24:25], 0, v[204:205]
	s_mov_b32 m0, s23
	v_lshl_add_u64 v[228:229], s[28:29], 0, v[206:207]
	global_load_lds_dwordx4 v[226:227], off
	v_lshl_add_u64 v[226:227], s[24:25], 0, v[208:209]
	s_add_i32 m0, s23, 0x2000
	s_nop 0
	global_load_lds_dwordx4 v[226:227], off
	v_lshl_add_u64 v[226:227], s[28:29], 0, v[202:203]
	s_mov_b32 m0, s64
	s_nop 0
	global_load_lds_dwordx4 v[226:227], off
	s_mov_b32 m0, s65
	s_nop 0
	global_load_lds_dwordx4 v[228:229], off
	s_waitcnt vmcnt(8)
	s_waitcnt lgkmcnt(0)
	s_barrier
	s_waitcnt lgkmcnt(0)
	v_mfma_f32_16x16x32_bf16 v[100:103], v[148:151], v[128:131], v[100:103]
	v_mfma_f32_16x16x32_bf16 v[96:99], v[166:169], v[128:131], v[96:99]
	v_mfma_f32_16x16x32_bf16 v[92:95], v[148:151], v[186:189], v[92:95]
	v_mfma_f32_16x16x32_bf16 v[88:91], v[166:169], v[186:189], v[88:91]
	v_mfma_f32_16x16x32_bf16 v[84:87], v[148:151], v[194:197], v[84:87]
	v_mfma_f32_16x16x32_bf16 v[80:83], v[166:169], v[194:197], v[80:83]
	v_mfma_f32_16x16x32_bf16 v[76:79], v[148:151], v[242:245], v[76:79]
	v_mfma_f32_16x16x32_bf16 v[72:75], v[166:169], v[242:245], v[72:75]
	v_mfma_f32_16x16x32_bf16 v[100:103], v[144:147], v[136:139], v[100:103]
	v_mfma_f32_16x16x32_bf16 v[96:99], v[162:165], v[136:139], v[96:99]
	v_mfma_f32_16x16x32_bf16 v[92:95], v[144:147], v[190:193], v[92:95]
	v_mfma_f32_16x16x32_bf16 v[88:91], v[162:165], v[190:193], v[88:91]
	v_mfma_f32_16x16x32_bf16 v[84:87], v[144:147], v[198:201], v[84:87]
	v_mfma_f32_16x16x32_bf16 v[80:83], v[162:165], v[198:201], v[80:83]
	v_mfma_f32_16x16x32_bf16 v[76:79], v[144:147], v[246:249], v[76:79]
	v_mfma_f32_16x16x32_bf16 v[72:75], v[162:165], v[246:249], v[72:75]
	v_mfma_f32_16x16x32_bf16 v[36:39], v[156:159], v[128:131], v[36:39]
	v_mfma_f32_16x16x32_bf16 v[32:35], v[174:177], v[128:131], v[32:35]
	v_mfma_f32_16x16x32_bf16 v[28:31], v[156:159], v[186:189], v[28:31]
	v_mfma_f32_16x16x32_bf16 v[24:27], v[174:177], v[186:189], v[24:27]
	v_mfma_f32_16x16x32_bf16 v[20:23], v[156:159], v[194:197], v[20:23]
	v_mfma_f32_16x16x32_bf16 v[16:19], v[174:177], v[194:197], v[16:19]
	v_mfma_f32_16x16x32_bf16 v[12:15], v[156:159], v[242:245], v[12:15]
	v_mfma_f32_16x16x32_bf16 v[8:11], v[174:177], v[242:245], v[8:11]
	v_mfma_f32_16x16x32_bf16 v[36:39], v[152:155], v[136:139], v[36:39]
	v_mfma_f32_16x16x32_bf16 v[32:35], v[170:173], v[136:139], v[32:35]
	v_mfma_f32_16x16x32_bf16 v[28:31], v[152:155], v[190:193], v[28:31]
	v_mfma_f32_16x16x32_bf16 v[24:27], v[170:173], v[190:193], v[24:27]
	v_mfma_f32_16x16x32_bf16 v[20:23], v[152:155], v[198:201], v[20:23]
	v_mfma_f32_16x16x32_bf16 v[16:19], v[170:173], v[198:201], v[16:19]
	v_mfma_f32_16x16x32_bf16 v[12:15], v[152:155], v[246:249], v[12:15]
	v_mfma_f32_16x16x32_bf16 v[8:11], v[170:173], v[246:249], v[8:11]
	v_cndmask_b32_e64 v128, 0, 1, s[8:9]
	v_cmp_ne_u32_e64 s[38:39], 1, v128
	s_andn2_b64 vcc, exec, s[8:9]
	s_mov_b64 s[58:59], -1
	s_cbranch_vccnz .LBB0_1307
	v_mfma_f32_16x16x32_bf16 v[128:131], v[166:169], v[182:185], v[4:7]
	s_mov_b64 s[58:59], 0
	v_mfma_f32_16x16x32_bf16 v[136:139], v[174:177], v[182:185], v[0:3]
	v_mfma_f32_16x16x32_bf16 v[128:131], v[162:165], v[178:181], v[128:131]
	v_mfma_f32_16x16x32_bf16 v[136:139], v[170:173], v[178:181], v[136:139]

; #define PG8_STAGE(bufoff, gbase, voff) do { _Pragma("unroll") for (int _i = 0; _i < 2; ++_i) \
;         __builtin_amdgcn_global_load_lds((const GAS unsigned*)((const GAS char*)(gbase) + (voff)[_i]), (PG8_LAS unsigned*)(lds + (bufoff) + ldsw + _i * 8192), 16, 0, 0); } while (0)
; #define PG8_LDA(dst, b, h) do { _Pragma("unroll") for (int m = 0; m < 4; ++m) _Pragma("unroll") for (int k = 0; k < 2; ++k) dst[m][k] = *(const PG8_LAS bf16x8*)(lds + PG8_SA(b, h) + aoff + m * 2048 + k * 1024); } while (0)
; #define PG8_LDB(dst, b, h) do { _Pragma("unroll") for (int n = 0; n < 2; ++n) _Pragma("unroll") for (int k = 0; k < 2; ++k) dst[n][k] = *(const PG8_LAS bf16x8*)(lds + PG8_SB(b, h) + boff + n * 2048 + k * 1024); } while (0)
; #define PG8_MMA(ai, bj, At, Bt) do { __builtin_amdgcn_s_setprio(1); _Pragma("unroll") for (int m = 0; m < 4; ++m) _Pragma("unroll") for (int n = 0; n < 2; ++n) _Pragma("unroll") for (int k = 0; k < 2; ++k) \
;         acc[ai][bj][m][n] = __builtin_amdgcn_mfma_f32_16x16x32_bf16(Bt[n][k], At[m][k], acc[ai][bj][m][n], 0, 0, 0); __builtin_amdgcn_s_setprio(0); } while (0)
; #define PG8_WAIT_V(n) asm volatile("s_waitcnt vmcnt(" #n ")" ::: "memory")
; #define PG8_WAIT_L(n) asm volatile("s_waitcnt lgkmcnt(" #n ")" ::: "memory")
; #define PG8_BAR __builtin_amdgcn_s_barrier()
; #define PG8_SCHED __builtin_amdgcn_sched_barrier(0)
; #define PG8_STAGE(bufoff, gbase, voff) do { _Pragma("unroll") for (int _i = 0; _i < 2; ++_i) \
;         __builtin_amdgcn_global_load_lds((const GAS unsigned*)((const GAS char*)(gbase) + (voff)[_i]), (PG8_LAS unsigned*)(lds + (bufoff) + ldsw + _i * 8192), 16, 0, 0); } while (0)
; #define PG8_WAIT_V(n) asm volatile("s_waitcnt vmcnt(" #n ")" ::: "memory")
; #define PG8_BAR __builtin_amdgcn_s_barrier()
; template <class Epi, class Sched>
; __device__ __forceinline__ void gemm_phase_strip(PG8_LAS unsigned char* lds, PG8_LAS unsigned char* slds, PG8_LAS unsigned char* pf, const Gemm g, const Sched& S, const Epi& E, int wv) {
;     ...
;             PG8_WAIT_V(8); PG8_WAIT_L(0); PG8_BAR; PG8_MMA(1, 0, At, B0); PG8_MMA(1, 1, At, B1); PG8_MMA_S(); PG8_BAR; PG8_SCHED;
;             PG8_LDB(B0, 1, 0); PG8_LDB(B1, 1, 1); PG8_SCHED; PG8_LDA(At, 1, 0); PG8_STAGE(PG8_SA(0, 1), a2 + (Sched::SPLIT ? ((last && has_next) ? (nxt.kh > 0 ? -(long)hstepA : (long)hstepA) : hsA) : (long)hstepA), voffA); PG8_STAGE_S(sq ^ 4096u, s2);
.LBB0_1309:
	s_barrier
	s_nop 3
	v_add_u32_e32 v0, 0, v233
	v_add_u32_e32 v1, 0x18000, v0
	v_add_u32_e32 v0, 0x1c000, v0
	ds_read_b128 v[148:151], v1
	ds_read_b128 v[144:147], v1 offset:1024
	ds_read_b128 v[166:169], v1 offset:2048
	ds_read_b128 v[162:165], v1 offset:3072
	ds_read_b128 v[156:159], v0
	ds_read_b128 v[152:155], v0 offset:1024
	ds_read_b128 v[174:177], v0 offset:2048
	ds_read_b128 v[170:173], v0 offset:3072
	s_add_u32 s24, s28, 0x80000
	s_addc_u32 s25, s29, 0
	s_mov_b32 m0, s66
	v_lshl_add_u64 v[242:243], s[24:25], 0, v[202:203]
	ds_read_b128 v[194:197], v236 offset:32768
	ds_read_b128 v[198:201], v236 offset:33792
	ds_read_b128 v[186:189], v236 offset:34816
	ds_read_b128 v[190:193], v236 offset:35840
	ds_read_b128 v[178:181], v236 offset:36864
	ds_read_b128 v[182:185], v236 offset:37888
	ds_read_b128 v[0:3], v236 offset:38912
	ds_read_b128 v[4:7], v236 offset:39936
	global_load_lds_dwordx4 v[242:243], off
	v_lshl_add_u64 v[242:243], s[24:25], 0, v[206:207]
	s_mov_b32 m0, s67
	s_nop 0
	global_load_lds_dwordx4 v[242:243], off
	v_mov_b32_e32 v242, v230
	s_and_saveexec_b64 s[28:29], s[34:35]
	s_cbranch_execz .LBB0_1311
	s_add_u32 s23, s11, s52
	s_addc_u32 s31, s13, s53
	s_and_b64 s[24:25], s[56:57], exec
	s_cselect_b32 s25, s45, s31
	s_cselect_b32 s24, s44, s23
	s_xor_b32 s23, s91, 0x1000
	s_add_i32 m0, s83, s23
	s_nop 0
	global_load_lds_dwordx4 v242, s[24:25]
; #define PG8_STAGE(bufoff, gbase, voff) do { _Pragma("unroll") for (int _i = 0; _i < 2; ++_i) \
;         __builtin_amdgcn_global_load_lds((const GAS unsigned*)((const GAS char*)(gbase) + (voff)[_i]), (PG8_LAS unsigned*)(lds + (bufoff) + ldsw + _i * 8192), 16, 0, 0); } while (0)
; #define PG8_LDA(dst, b, h) do { _Pragma("unroll") for (int m = 0; m < 4; ++m) _Pragma("unroll") for (int k = 0; k < 2; ++k) dst[m][k] = *(const PG8_LAS bf16x8*)(lds + PG8_SA(b, h) + aoff + m * 2048 + k * 1024); } while (0)
; #define PG8_MMA(ai, bj, At, Bt) do { __builtin_amdgcn_s_setprio(1); _Pragma("unroll") for (int m = 0; m < 4; ++m) _Pragma("unroll") for (int n = 0; n < 2; ++n) _Pragma("unroll") for (int k = 0; k < 2; ++k) \
;         acc[ai][bj][m][n] = __builtin_amdgcn_mfma_f32_16x16x32_bf16(Bt[n][k], At[m][k], acc[ai][bj][m][n], 0, 0, 0); __builtin_amdgcn_s_setprio(0); } while (0)
; #define PG8_WAIT_V(n) asm volatile("s_waitcnt vmcnt(" #n ")" ::: "memory")
; #define PG8_WAIT_L(n) asm volatile("s_waitcnt lgkmcnt(" #n ")" ::: "memory")
; #define PG8_BAR __builtin_amdgcn_s_barrier()
; #define PG8_SCHED __builtin_amdgcn_sched_barrier(0)
; #define PG8_STAGE(bufoff, gbase, voff) do { _Pragma("unroll") for (int _i = 0; _i < 2; ++_i) \
;         __builtin_amdgcn_global_load_lds((const GAS unsigned*)((const GAS char*)(gbase) + (voff)[_i]), (PG8_LAS unsigned*)(lds + (bufoff) + ldsw + _i * 8192), 16, 0, 0); } while (0)
; #define PG8_LDA(dst, b, h) do { _Pragma("unroll") for (int m = 0; m < 4; ++m) _Pragma("unroll") for (int k = 0; k < 2; ++k) dst[m][k] = *(const PG8_LAS bf16x8*)(lds + PG8_SA(b, h) + aoff + m * 2048 + k * 1024); } while (0)
; #define PG8_WAIT_V(n) asm volatile("s_waitcnt vmcnt(" #n ")" ::: "memory")
; template <class Epi, class Sched>
; __device__ __forceinline__ void gemm_phase_strip(PG8_LAS unsigned char* lds, PG8_LAS unsigned char* slds, PG8_LAS unsigned char* pf, const Gemm g, const Sched& S, const Epi& E, int wv) {
;     ...
;             PG8_WAIT_V(9); PG8_WAIT_L(0); PG8_BAR; PG8_MMA(0, 0, At, B0); PG8_MMA(0, 1, At, B1); PG8_BAR; PG8_SCHED;
;             PG8_LDA(At, 1, 1); PG8_LDS_S(As, sq + 2048u); PG8_STAGE(PG8_SB(1, 0), b3, voffB); PG8_STAGE(PG8_SB(1, 1), b3 + hstepB, voffB); PG8_STAGE(PG8_SA(1, 0), a3, voffA);
;             PG8_WAIT_V(9); PG8_WAIT_L(0); PG8_BAR; PG8_MMA(1, 0, At, B0); PG8_MMA(1, 1, At, B1); PG8_MMA_S(); PG8_BAR; PG8_SCHED;
.LBB0_1311:
	s_or_b64 exec, exec, s[28:29]
	s_waitcnt vmcnt(9)
	s_waitcnt lgkmcnt(0)
	s_barrier
	s_waitcnt lgkmcnt(0)
	v_mfma_f32_16x16x32_bf16 v[140:143], v[148:151], v[194:197], v[140:143]
	v_mfma_f32_16x16x32_bf16 v[132:135], v[166:169], v[194:197], v[132:135]
	v_mfma_f32_16x16x32_bf16 v[124:127], v[148:151], v[186:189], v[124:127]
	v_mfma_f32_16x16x32_bf16 v[120:123], v[166:169], v[186:189], v[120:123]
	v_mfma_f32_16x16x32_bf16 v[116:119], v[148:151], v[178:181], v[116:119]
	v_mfma_f32_16x16x32_bf16 v[112:115], v[166:169], v[178:181], v[112:115]
	v_mfma_f32_16x16x32_bf16 v[108:111], v[148:151], v[0:3], v[108:111]
	v_mfma_f32_16x16x32_bf16 v[104:107], v[166:169], v[0:3], v[104:107]
	v_mfma_f32_16x16x32_bf16 v[140:143], v[144:147], v[198:201], v[140:143]
	v_mfma_f32_16x16x32_bf16 v[132:135], v[162:165], v[198:201], v[132:135]
	v_mfma_f32_16x16x32_bf16 v[124:127], v[144:147], v[190:193], v[124:127]
	v_mfma_f32_16x16x32_bf16 v[120:123], v[162:165], v[190:193], v[120:123]
	v_mfma_f32_16x16x32_bf16 v[116:119], v[144:147], v[182:185], v[116:119]
	v_mfma_f32_16x16x32_bf16 v[112:115], v[162:165], v[182:185], v[112:115]
	v_mfma_f32_16x16x32_bf16 v[108:111], v[144:147], v[4:7], v[108:111]
	v_mfma_f32_16x16x32_bf16 v[104:107], v[162:165], v[4:7], v[104:107]
	v_mfma_f32_16x16x32_bf16 v[68:71], v[156:159], v[194:197], v[68:71]
	v_mfma_f32_16x16x32_bf16 v[64:67], v[174:177], v[194:197], v[64:67]
	v_mfma_f32_16x16x32_bf16 v[60:63], v[156:159], v[186:189], v[60:63]
	v_mfma_f32_16x16x32_bf16 v[56:59], v[174:177], v[186:189], v[56:59]
	v_mfma_f32_16x16x32_bf16 v[52:55], v[156:159], v[178:181], v[52:55]
	v_mfma_f32_16x16x32_bf16 v[48:51], v[174:177], v[178:181], v[48:51]
	v_mfma_f32_16x16x32_bf16 v[44:47], v[156:159], v[0:3], v[44:47]
	v_mfma_f32_16x16x32_bf16 v[0:3], v[174:177], v[0:3], v[40:43]
	v_mfma_f32_16x16x32_bf16 v[68:71], v[152:155], v[198:201], v[68:71]
	v_mfma_f32_16x16x32_bf16 v[64:67], v[170:173], v[198:201], v[64:67]
	v_mfma_f32_16x16x32_bf16 v[60:63], v[152:155], v[190:193], v[60:63]
	v_mfma_f32_16x16x32_bf16 v[56:59], v[170:173], v[190:193], v[56:59]
	v_mfma_f32_16x16x32_bf16 v[52:55], v[152:155], v[182:185], v[52:55]
	v_mfma_f32_16x16x32_bf16 v[48:51], v[170:173], v[182:185], v[48:51]
	v_mfma_f32_16x16x32_bf16 v[44:47], v[152:155], v[4:7], v[44:47]
	v_mfma_f32_16x16x32_bf16 v[40:43], v[170:173], v[4:7], v[0:3]
	s_barrier
	s_mov_b32 m0, s76
	v_lshl_add_u64 v[222:223], v[222:223], 0, s[16:17]
	s_add_u32 s24, s54, 0x80080
	ds_read_b128 v[0:3], v236 offset:49152
	ds_read_b128 v[4:7], v236 offset:50176
	ds_read_b128 v[186:189], v236 offset:51200
	ds_read_b128 v[190:193], v236 offset:52224
	ds_read_b128 v[194:197], v236 offset:53248
	ds_read_b128 v[198:201], v236 offset:54272
	ds_read_b128 v[242:245], v236 offset:55296
	ds_read_b128 v[246:249], v236 offset:56320
	ds_read_b128 v[182:185], v160 offset:2048
	ds_read_b128 v[178:181], v237 offset:2048
	global_load_lds_dwordx4 v[222:223], off
	v_lshl_add_u64 v[222:223], v[224:225], 0, s[16:17]
	s_mov_b32 m0, s77
	s_addc_u32 s25, s55, 0
	global_load_lds_dwordx4 v[222:223], off
	v_lshl_add_u64 v[222:223], s[24:25], 0, v[204:205]
	s_mov_b32 m0, s80
	s_nop 0
	global_load_lds_dwordx4 v[222:223], off
	v_lshl_add_u64 v[222:223], s[24:25], 0, v[208:209]
	s_mov_b32 m0, s81
	s_nop 0
	global_load_lds_dwordx4 v[222:223], off
	v_lshl_add_u64 v[222:223], v[226:227], 0, s[16:17]
	s_mov_b32 m0, s78
	s_nop 0
	global_load_lds_dwordx4 v[222:223], off
	v_lshl_add_u64 v[222:223], v[228:229], 0, s[16:17]
	s_mov_b32 m0, s79
	s_nop 0
	global_load_lds_dwordx4 v[222:223], off
	s_waitcnt vmcnt(9)
	s_waitcnt lgkmcnt(0)
	s_barrier
	s_waitcnt lgkmcnt(0)
	v_mfma_f32_16x16x32_bf16 v[100:103], v[148:151], v[0:3], v[100:103]
	v_mfma_f32_16x16x32_bf16 v[96:99], v[166:169], v[0:3], v[96:99]
	v_mfma_f32_16x16x32_bf16 v[92:95], v[148:151], v[186:189], v[92:95]
	v_mfma_f32_16x16x32_bf16 v[88:91], v[166:169], v[186:189], v[88:91]
	v_mfma_f32_16x16x32_bf16 v[84:87], v[148:151], v[194:197], v[84:87]
	v_mfma_f32_16x16x32_bf16 v[80:83], v[166:169], v[194:197], v[80:83]
	v_mfma_f32_16x16x32_bf16 v[76:79], v[148:151], v[242:245], v[76:79]
	v_mfma_f32_16x16x32_bf16 v[72:75], v[166:169], v[242:245], v[72:75]
	v_mfma_f32_16x16x32_bf16 v[100:103], v[144:147], v[4:7], v[100:103]
	v_mfma_f32_16x16x32_bf16 v[96:99], v[162:165], v[4:7], v[96:99]
	v_mfma_f32_16x16x32_bf16 v[92:95], v[144:147], v[190:193], v[92:95]
	v_mfma_f32_16x16x32_bf16 v[88:91], v[162:165], v[190:193], v[88:91]
	v_mfma_f32_16x16x32_bf16 v[84:87], v[144:147], v[198:201], v[84:87]
	v_mfma_f32_16x16x32_bf16 v[80:83], v[162:165], v[198:201], v[80:83]
	v_mfma_f32_16x16x32_bf16 v[76:79], v[144:147], v[246:249], v[76:79]
	v_mfma_f32_16x16x32_bf16 v[72:75], v[162:165], v[246:249], v[72:75]
	v_mfma_f32_16x16x32_bf16 v[36:39], v[156:159], v[0:3], v[36:39]
	v_mfma_f32_16x16x32_bf16 v[0:3], v[174:177], v[0:3], v[32:35]
	v_mfma_f32_16x16x32_bf16 v[32:35], v[170:173], v[4:7], v[0:3]
	v_mfma_f32_16x16x32_bf16 v[0:3], v[156:159], v[186:189], v[28:31]
	v_mfma_f32_16x16x32_bf16 v[28:31], v[152:155], v[190:193], v[0:3]
	v_mfma_f32_16x16x32_bf16 v[0:3], v[174:177], v[186:189], v[24:27]
	v_mfma_f32_16x16x32_bf16 v[24:27], v[170:173], v[190:193], v[0:3]
	v_mfma_f32_16x16x32_bf16 v[0:3], v[156:159], v[194:197], v[20:23]
	v_mfma_f32_16x16x32_bf16 v[20:23], v[152:155], v[198:201], v[0:3]
	v_mfma_f32_16x16x32_bf16 v[0:3], v[174:177], v[194:197], v[16:19]
	v_mfma_f32_16x16x32_bf16 v[16:19], v[170:173], v[198:201], v[0:3]
	v_mfma_f32_16x16x32_bf16 v[0:3], v[156:159], v[242:245], v[12:15]
	v_mfma_f32_16x16x32_bf16 v[12:15], v[152:155], v[246:249], v[0:3]
	v_mfma_f32_16x16x32_bf16 v[0:3], v[174:177], v[242:245], v[8:11]
	v_mfma_f32_16x16x32_bf16 v[36:39], v[152:155], v[4:7], v[36:39]
	v_mfma_f32_16x16x32_bf16 v[8:11], v[170:173], v[246:249], v[0:3]
	s_and_b64 vcc, exec, s[38:39]
	s_mov_b64 s[28:29], -1
	s_cbranch_vccnz .LBB0_1313
	v_mfma_f32_16x16x32_bf16 v[0:3], v[166:169], v[182:185], v[128:131]
	s_mov_b64 s[28:29], 0
	v_mfma_f32_16x16x32_bf16 v[166:169], v[174:177], v[182:185], v[136:139]
	v_mfma_f32_16x16x32_bf16 v[4:7], v[162:165], v[178:181], v[0:3]
	v_mfma_f32_16x16x32_bf16 v[0:3], v[170:173], v[178:181], v[166:169]

; #define PG8_STAGE(bufoff, gbase, voff) do { _Pragma("unroll") for (int _i = 0; _i < 2; ++_i) \
;         __builtin_amdgcn_global_load_lds((const GAS unsigned*)((const GAS char*)(gbase) + (voff)[_i]), (PG8_LAS unsigned*)(lds + (bufoff) + ldsw + _i * 8192), 16, 0, 0); } while (0)
; #define PG8_LDA(dst, b, h) do { _Pragma("unroll") for (int m = 0; m < 4; ++m) _Pragma("unroll") for (int k = 0; k < 2; ++k) dst[m][k] = *(const PG8_LAS bf16x8*)(lds + PG8_SA(b, h) + aoff + m * 2048 + k * 1024); } while (0)
; #define PG8_LDB(dst, b, h) do { _Pragma("unroll") for (int n = 0; n < 2; ++n) _Pragma("unroll") for (int k = 0; k < 2; ++k) dst[n][k] = *(const PG8_LAS bf16x8*)(lds + PG8_SB(b, h) + boff + n * 2048 + k * 1024); } while (0)
; #define PG8_MMA(ai, bj, At, Bt) do { __builtin_amdgcn_s_setprio(1); _Pragma("unroll") for (int m = 0; m < 4; ++m) _Pragma("unroll") for (int n = 0; n < 2; ++n) _Pragma("unroll") for (int k = 0; k < 2; ++k) \
;         acc[ai][bj][m][n] = __builtin_amdgcn_mfma_f32_16x16x32_bf16(Bt[n][k], At[m][k], acc[ai][bj][m][n], 0, 0, 0); __builtin_amdgcn_s_setprio(0); } while (0)
; #define PG8_WAIT_V(n) asm volatile("s_waitcnt vmcnt(" #n ")" ::: "memory")
; #define PG8_WAIT_L(n) asm volatile("s_waitcnt lgkmcnt(" #n ")" ::: "memory")
; #define PG8_BAR __builtin_amdgcn_s_barrier()
; #define PG8_SCHED __builtin_amdgcn_sched_barrier(0)
; #define PG8_LDA(dst, b, h) do { _Pragma("unroll") for (int m = 0; m < 4; ++m) _Pragma("unroll") for (int k = 0; k < 2; ++k) dst[m][k] = *(const PG8_LAS bf16x8*)(lds + PG8_SA(b, h) + aoff + m * 2048 + k * 1024); } while (0)
; template <class Epi, class Sched, bool ALIGN_EPI = false, bool SP2 = false>
; __device__ __forceinline__ void gemm_phase(PG8_LAS unsigned char* lds, PG8_LAS unsigned char* pf, const Gemm g, const Sched& S, const Epi& E, int wv) {
;     ...
;             PG8_LDB(B0, 0, 0); PG8_LDB(B1, 0, 1); PG8_SCHED; PG8_LDA(At, 0, 0); PG8_STAGE(PG8_SA(1, 1), a1 + (Sched::SPLIT ? hsA : (long)hstepA), voffA);
;             PG8_WAIT_V(8); PG8_WAIT_L(0); PG8_BAR; PG8_MMA(0, 0, At, B0); PG8_MMA(0, 1, At, B1); PG8_BAR; PG8_SCHED;
;             PG8_LDA(At, 0, 1); PG8_STAGE(PG8_SB(0, 0), b2, voffB); PG8_STAGE(PG8_SB(0, 1), b2 + hstepB, voffB); PG8_STAGE(PG8_SA(0, 0), a2, voffA);
;             PG8_WAIT_V(8); PG8_WAIT_L(0); PG8_BAR; PG8_MMA(1, 0, At, B0); PG8_MMA(1, 1, At, B1); PG8_BAR; PG8_SCHED;
.LBB0_1414:
	s_add_u32 s25, s36, 0xfff80080
	s_addc_u32 s28, s37, -1
	s_add_i32 s42, 0, 0x10000
	s_cmp_eq_u32 s24, 28
	s_cselect_b32 s29, s13, s28
	s_cselect_b32 s28, s12, s25
	s_cselect_b32 s41, s9, s23
	s_cselect_b32 s40, s11, s22
	s_add_i32 s25, 0, 0x14000
	v_add_u32_e32 v132, s42, v159
	v_add_u32_e32 v160, s25, v159
	ds_read_b128 v[120:123], v132
	ds_read_b128 v[124:127], v132 offset:1024
	ds_read_b128 v[128:131], v132 offset:2048
	ds_read_b128 v[132:135], v132 offset:3072
	ds_read_b128 v[164:167], v160
	ds_read_b128 v[168:171], v160 offset:1024
	ds_read_b128 v[172:175], v160 offset:2048
	ds_read_b128 v[176:179], v160 offset:3072
	v_lshl_add_u64 v[208:209], s[36:37], 0, v[154:155]
	s_add_i32 m0, s1, 0xc000
	ds_read_b128 v[180:183], v162
	ds_read_b128 v[184:187], v162 offset:1024
	ds_read_b128 v[188:191], v162 offset:2048
	ds_read_b128 v[192:195], v162 offset:3072
	ds_read_b128 v[196:199], v162 offset:4096
	ds_read_b128 v[200:203], v162 offset:5120
	ds_read_b128 v[204:207], v162 offset:6144
	ds_read_b128 v[214:217], v162 offset:7168
	global_load_lds_dwordx4 v[208:209], off
	v_lshl_add_u64 v[208:209], s[36:37], 0, v[152:153]
	s_add_i32 m0, s1, 0xe000
	s_nop 0
	global_load_lds_dwordx4 v[208:209], off
	s_waitcnt vmcnt(8)
	s_waitcnt lgkmcnt(0)
	s_barrier
	s_waitcnt lgkmcnt(0)
	v_mfma_f32_16x16x32_bf16 v[140:143], v[120:123], v[180:183], v[140:143]
	v_mfma_f32_16x16x32_bf16 v[136:139], v[128:131], v[180:183], v[136:139]
	v_mfma_f32_16x16x32_bf16 v[108:111], v[120:123], v[188:191], v[108:111]
	v_mfma_f32_16x16x32_bf16 v[104:107], v[128:131], v[188:191], v[104:107]
	v_mfma_f32_16x16x32_bf16 v[92:95], v[120:123], v[196:199], v[92:95]
	v_mfma_f32_16x16x32_bf16 v[88:91], v[128:131], v[196:199], v[88:91]
	v_mfma_f32_16x16x32_bf16 v[76:79], v[120:123], v[204:207], v[76:79]
	v_mfma_f32_16x16x32_bf16 v[72:75], v[128:131], v[204:207], v[72:75]
	v_mfma_f32_16x16x32_bf16 v[140:143], v[124:127], v[184:187], v[140:143]
	v_mfma_f32_16x16x32_bf16 v[136:139], v[132:135], v[184:187], v[136:139]
	v_mfma_f32_16x16x32_bf16 v[108:111], v[124:127], v[192:195], v[108:111]
	v_mfma_f32_16x16x32_bf16 v[104:107], v[132:135], v[192:195], v[104:107]
	v_mfma_f32_16x16x32_bf16 v[92:95], v[124:127], v[200:203], v[92:95]
	v_mfma_f32_16x16x32_bf16 v[88:91], v[132:135], v[200:203], v[88:91]
	v_mfma_f32_16x16x32_bf16 v[76:79], v[124:127], v[214:217], v[76:79]
	v_mfma_f32_16x16x32_bf16 v[72:75], v[132:135], v[214:217], v[72:75]
	v_mfma_f32_16x16x32_bf16 v[116:119], v[164:167], v[180:183], v[116:119]
	v_mfma_f32_16x16x32_bf16 v[112:115], v[172:175], v[180:183], v[112:115]
	v_mfma_f32_16x16x32_bf16 v[100:103], v[164:167], v[188:191], v[100:103]
	v_mfma_f32_16x16x32_bf16 v[96:99], v[172:175], v[188:191], v[96:99]
	v_mfma_f32_16x16x32_bf16 v[84:87], v[164:167], v[196:199], v[84:87]
	v_mfma_f32_16x16x32_bf16 v[80:83], v[172:175], v[196:199], v[80:83]
	v_mfma_f32_16x16x32_bf16 v[68:71], v[164:167], v[204:207], v[68:71]
	v_mfma_f32_16x16x32_bf16 v[64:67], v[172:175], v[204:207], v[64:67]
	v_mfma_f32_16x16x32_bf16 v[116:119], v[168:171], v[184:187], v[116:119]
	v_mfma_f32_16x16x32_bf16 v[112:115], v[176:179], v[184:187], v[112:115]
	v_mfma_f32_16x16x32_bf16 v[100:103], v[168:171], v[192:195], v[100:103]
	v_mfma_f32_16x16x32_bf16 v[96:99], v[176:179], v[192:195], v[96:99]
	v_mfma_f32_16x16x32_bf16 v[84:87], v[168:171], v[200:203], v[84:87]
	v_mfma_f32_16x16x32_bf16 v[80:83], v[176:179], v[200:203], v[80:83]
	v_mfma_f32_16x16x32_bf16 v[68:71], v[168:171], v[214:217], v[68:71]
	v_mfma_f32_16x16x32_bf16 v[64:67], v[176:179], v[214:217], v[64:67]
	s_barrier
	s_add_i32 s42, s42, s27
	v_lshl_add_u64 v[208:209], s[40:41], 0, v[146:147]
	s_mov_b32 m0, s42
	ds_read_b128 v[180:183], v162 offset:16384
	ds_read_b128 v[184:187], v162 offset:17408
	ds_read_b128 v[188:191], v162 offset:18432
	ds_read_b128 v[192:195], v162 offset:19456
	ds_read_b128 v[196:199], v162 offset:20480
	ds_read_b128 v[200:203], v162 offset:21504
	ds_read_b128 v[204:207], v162 offset:22528
	ds_read_b128 v[214:217], v162 offset:23552
	global_load_lds_dwordx4 v[208:209], off
	s_add_i32 m0, s42, 0x2000
	s_add_u32 s42, s40, 0x80000
	v_lshl_add_u64 v[218:219], s[40:41], 0, v[150:151]
	s_addc_u32 s43, s41, 0
	s_add_i32 s25, s25, s27
	global_load_lds_dwordx4 v[218:219], off
	v_lshl_add_u64 v[220:221], s[42:43], 0, v[146:147]
	s_mov_b32 m0, s25
	v_lshl_add_u64 v[222:223], s[28:29], 0, v[148:149]
	global_load_lds_dwordx4 v[220:221], off
	v_lshl_add_u64 v[220:221], s[42:43], 0, v[150:151]
	s_add_i32 m0, s25, 0x2000
	s_nop 0
	global_load_lds_dwordx4 v[220:221], off
	v_lshl_add_u64 v[220:221], s[28:29], 0, v[144:145]
	s_mov_b32 m0, s1
	s_nop 0
	global_load_lds_dwordx4 v[220:221], off
	s_mov_b32 m0, s39
	s_nop 0
	global_load_lds_dwordx4 v[222:223], off
	s_waitcnt vmcnt(8)
	s_waitcnt lgkmcnt(0)
	s_barrier
; #define PG8_STAGE(bufoff, gbase, voff) do { _Pragma("unroll") for (int _i = 0; _i < 2; ++_i) \
;         __builtin_amdgcn_global_load_lds((const GAS unsigned*)((const GAS char*)(gbase) + (voff)[_i]), (PG8_LAS unsigned*)(lds + (bufoff) + ldsw + _i * 8192), 16, 0, 0); } while (0)
; #define PG8_LDA(dst, b, h) do { _Pragma("unroll") for (int m = 0; m < 4; ++m) _Pragma("unroll") for (int k = 0; k < 2; ++k) dst[m][k] = *(const PG8_LAS bf16x8*)(lds + PG8_SA(b, h) + aoff + m * 2048 + k * 1024); } while (0)
; #define PG8_LDB(dst, b, h) do { _Pragma("unroll") for (int n = 0; n < 2; ++n) _Pragma("unroll") for (int k = 0; k < 2; ++k) dst[n][k] = *(const PG8_LAS bf16x8*)(lds + PG8_SB(b, h) + boff + n * 2048 + k * 1024); } while (0)
; #define PG8_MMA(ai, bj, At, Bt) do { __builtin_amdgcn_s_setprio(1); _Pragma("unroll") for (int m = 0; m < 4; ++m) _Pragma("unroll") for (int n = 0; n < 2; ++n) _Pragma("unroll") for (int k = 0; k < 2; ++k) \
;         acc[ai][bj][m][n] = __builtin_amdgcn_mfma_f32_16x16x32_bf16(Bt[n][k], At[m][k], acc[ai][bj][m][n], 0, 0, 0); __builtin_amdgcn_s_setprio(0); } while (0)
; #define PG8_WAIT_V(n) asm volatile("s_waitcnt vmcnt(" #n ")" ::: "memory")
; #define PG8_WAIT_L(n) asm volatile("s_waitcnt lgkmcnt(" #n ")" ::: "memory")
; #define PG8_BAR __builtin_amdgcn_s_barrier()
; #define PG8_SCHED __builtin_amdgcn_sched_barrier(0)
; #define PG8_STAGE(bufoff, gbase, voff) do { _Pragma("unroll") for (int _i = 0; _i < 2; ++_i) \
;         __builtin_amdgcn_global_load_lds((const GAS unsigned*)((const GAS char*)(gbase) + (voff)[_i]), (PG8_LAS unsigned*)(lds + (bufoff) + ldsw + _i * 8192), 16, 0, 0); } while (0)
; #define PG8_BAR __builtin_amdgcn_s_barrier()
; template <class Epi, class Sched, bool ALIGN_EPI = false, bool SP2 = false>
; __device__ __forceinline__ void gemm_phase(PG8_LAS unsigned char* lds, PG8_LAS unsigned char* pf, const Gemm g, const Sched& S, const Epi& E, int wv) {
;     ...
;             PG8_WAIT_V(8); PG8_WAIT_L(0); PG8_BAR; PG8_MMA(1, 0, At, B0); PG8_MMA(1, 1, At, B1); PG8_BAR; PG8_SCHED;
;             PG8_LDB(B0, 1, 0); PG8_LDB(B1, 1, 1); PG8_SCHED; PG8_LDA(At, 1, 0); PG8_STAGE(PG8_SA(0, 1), a2 + (Sched::SPLIT ? ((last && has_next) ? (nxt.kh > 0 ? -(long)hstepA : (long)hstepA) : hsA) : (long)hstepA), voffA);
;             PG8_WAIT_V(8); PG8_WAIT_L(0); PG8_BAR; PG8_MMA(0, 0, At, B0); PG8_MMA(0, 1, At, B1); PG8_BAR; PG8_SCHED;
	s_waitcnt lgkmcnt(0)
	v_mfma_f32_16x16x32_bf16 v[60:63], v[120:123], v[180:183], v[60:63]
	v_mfma_f32_16x16x32_bf16 v[56:59], v[128:131], v[180:183], v[56:59]
	v_mfma_f32_16x16x32_bf16 v[44:47], v[120:123], v[188:191], v[44:47]
	v_mfma_f32_16x16x32_bf16 v[40:43], v[128:131], v[188:191], v[40:43]
	v_mfma_f32_16x16x32_bf16 v[28:31], v[120:123], v[196:199], v[28:31]
	v_mfma_f32_16x16x32_bf16 v[24:27], v[128:131], v[196:199], v[24:27]
	v_mfma_f32_16x16x32_bf16 v[12:15], v[120:123], v[204:207], v[12:15]
	v_mfma_f32_16x16x32_bf16 v[8:11], v[128:131], v[204:207], v[8:11]
	v_mfma_f32_16x16x32_bf16 v[60:63], v[124:127], v[184:187], v[60:63]
	v_mfma_f32_16x16x32_bf16 v[56:59], v[132:135], v[184:187], v[56:59]
	v_mfma_f32_16x16x32_bf16 v[44:47], v[124:127], v[192:195], v[44:47]
	v_mfma_f32_16x16x32_bf16 v[40:43], v[132:135], v[192:195], v[40:43]
	v_mfma_f32_16x16x32_bf16 v[28:31], v[124:127], v[200:203], v[28:31]
	v_mfma_f32_16x16x32_bf16 v[24:27], v[132:135], v[200:203], v[24:27]
	v_mfma_f32_16x16x32_bf16 v[12:15], v[124:127], v[214:217], v[12:15]
	v_mfma_f32_16x16x32_bf16 v[8:11], v[132:135], v[214:217], v[8:11]
	v_mfma_f32_16x16x32_bf16 v[52:55], v[164:167], v[180:183], v[52:55]
	v_mfma_f32_16x16x32_bf16 v[48:51], v[172:175], v[180:183], v[48:51]
	v_mfma_f32_16x16x32_bf16 v[36:39], v[164:167], v[188:191], v[36:39]
	v_mfma_f32_16x16x32_bf16 v[32:35], v[172:175], v[188:191], v[32:35]
	v_mfma_f32_16x16x32_bf16 v[20:23], v[164:167], v[196:199], v[20:23]
	v_mfma_f32_16x16x32_bf16 v[16:19], v[172:175], v[196:199], v[16:19]
	v_mfma_f32_16x16x32_bf16 v[4:7], v[164:167], v[204:207], v[4:7]
	v_mfma_f32_16x16x32_bf16 v[0:3], v[172:175], v[204:207], v[0:3]
	v_mfma_f32_16x16x32_bf16 v[52:55], v[168:171], v[184:187], v[52:55]
	v_mfma_f32_16x16x32_bf16 v[48:51], v[176:179], v[184:187], v[48:51]
	v_mfma_f32_16x16x32_bf16 v[36:39], v[168:171], v[192:195], v[36:39]
	v_mfma_f32_16x16x32_bf16 v[32:35], v[176:179], v[192:195], v[32:35]
	v_mfma_f32_16x16x32_bf16 v[20:23], v[168:171], v[200:203], v[20:23]
	v_mfma_f32_16x16x32_bf16 v[16:19], v[176:179], v[200:203], v[16:19]
	v_mfma_f32_16x16x32_bf16 v[4:7], v[168:171], v[214:217], v[4:7]
	v_mfma_f32_16x16x32_bf16 v[0:3], v[176:179], v[214:217], v[0:3]
	s_barrier
	s_add_i32 s25, 0, 0x18000
	s_add_i32 s42, 0, 0x1c000
	v_add_u32_e32 v132, s25, v159
	v_add_u32_e32 v160, s42, v159
	ds_read_b128 v[120:123], v132
	ds_read_b128 v[124:127], v132 offset:1024
	ds_read_b128 v[128:131], v132 offset:2048
	ds_read_b128 v[132:135], v132 offset:3072
	ds_read_b128 v[164:167], v160
	ds_read_b128 v[168:171], v160 offset:1024
	ds_read_b128 v[172:175], v160 offset:2048
	ds_read_b128 v[176:179], v160 offset:3072
	s_add_u32 s28, s28, 0x80000
	s_addc_u32 s29, s29, 0
	s_mov_b32 m0, s44
	v_lshl_add_u64 v[224:225], s[28:29], 0, v[144:145]
	ds_read_b128 v[180:183], v162 offset:32768
	ds_read_b128 v[184:187], v162 offset:33792
	ds_read_b128 v[188:191], v162 offset:34816
	ds_read_b128 v[192:195], v162 offset:35840
	ds_read_b128 v[196:199], v162 offset:36864
	ds_read_b128 v[200:203], v162 offset:37888
	ds_read_b128 v[204:207], v162 offset:38912
	ds_read_b128 v[214:217], v162 offset:39936
	global_load_lds_dwordx4 v[224:225], off
	v_lshl_add_u64 v[224:225], s[28:29], 0, v[148:149]
	s_mov_b32 m0, s45
	s_nop 0
	global_load_lds_dwordx4 v[224:225], off
	s_waitcnt vmcnt(8)
	s_waitcnt lgkmcnt(0)
	s_barrier
	s_waitcnt lgkmcnt(0)
	v_mfma_f32_16x16x32_bf16 v[140:143], v[120:123], v[180:183], v[140:143]
	v_mfma_f32_16x16x32_bf16 v[136:139], v[128:131], v[180:183], v[136:139]
	v_mfma_f32_16x16x32_bf16 v[108:111], v[120:123], v[188:191], v[108:111]
	v_mfma_f32_16x16x32_bf16 v[104:107], v[128:131], v[188:191], v[104:107]
	v_mfma_f32_16x16x32_bf16 v[92:95], v[120:123], v[196:199], v[92:95]
	v_mfma_f32_16x16x32_bf16 v[88:91], v[128:131], v[196:199], v[88:91]
	v_mfma_f32_16x16x32_bf16 v[76:79], v[120:123], v[204:207], v[76:79]
	v_mfma_f32_16x16x32_bf16 v[72:75], v[128:131], v[204:207], v[72:75]
	v_mfma_f32_16x16x32_bf16 v[140:143], v[124:127], v[184:187], v[140:143]
	v_mfma_f32_16x16x32_bf16 v[136:139], v[132:135], v[184:187], v[136:139]
	v_mfma_f32_16x16x32_bf16 v[108:111], v[124:127], v[192:195], v[108:111]
	v_mfma_f32_16x16x32_bf16 v[104:107], v[132:135], v[192:195], v[104:107]
	v_mfma_f32_16x16x32_bf16 v[92:95], v[124:127], v[200:203], v[92:95]
	v_mfma_f32_16x16x32_bf16 v[88:91], v[132:135], v[200:203], v[88:91]
	v_mfma_f32_16x16x32_bf16 v[76:79], v[124:127], v[214:217], v[76:79]
	v_mfma_f32_16x16x32_bf16 v[72:75], v[132:135], v[214:217], v[72:75]
	v_mfma_f32_16x16x32_bf16 v[116:119], v[164:167], v[180:183], v[116:119]
	v_mfma_f32_16x16x32_bf16 v[112:115], v[172:175], v[180:183], v[112:115]
	v_mfma_f32_16x16x32_bf16 v[100:103], v[164:167], v[188:191], v[100:103]
	v_mfma_f32_16x16x32_bf16 v[96:99], v[172:175], v[188:191], v[96:99]
	v_mfma_f32_16x16x32_bf16 v[84:87], v[164:167], v[196:199], v[84:87]
	v_mfma_f32_16x16x32_bf16 v[80:83], v[172:175], v[196:199], v[80:83]
	v_mfma_f32_16x16x32_bf16 v[68:71], v[164:167], v[204:207], v[68:71]
	v_mfma_f32_16x16x32_bf16 v[64:67], v[172:175], v[204:207], v[64:67]
	v_mfma_f32_16x16x32_bf16 v[116:119], v[168:171], v[184:187], v[116:119]
	v_mfma_f32_16x16x32_bf16 v[112:115], v[176:179], v[184:187], v[112:115]
	v_mfma_f32_16x16x32_bf16 v[100:103], v[168:171], v[192:195], v[100:103]
	v_mfma_f32_16x16x32_bf16 v[96:99], v[176:179], v[192:195], v[96:99]
	v_mfma_f32_16x16x32_bf16 v[84:87], v[168:171], v[200:203], v[84:87]
	v_mfma_f32_16x16x32_bf16 v[80:83], v[176:179], v[200:203], v[80:83]
	v_mfma_f32_16x16x32_bf16 v[68:71], v[168:171], v[214:217], v[68:71]
	v_mfma_f32_16x16x32_bf16 v[64:67], v[176:179], v[214:217], v[64:67]
	s_barrier
; #define PG8_STAGE(bufoff, gbase, voff) do { _Pragma("unroll") for (int _i = 0; _i < 2; ++_i) \
;         __builtin_amdgcn_global_load_lds((const GAS unsigned*)((const GAS char*)(gbase) + (voff)[_i]), (PG8_LAS unsigned*)(lds + (bufoff) + ldsw + _i * 8192), 16, 0, 0); } while (0)
; #define PG8_LDA(dst, b, h) do { _Pragma("unroll") for (int m = 0; m < 4; ++m) _Pragma("unroll") for (int k = 0; k < 2; ++k) dst[m][k] = *(const PG8_LAS bf16x8*)(lds + PG8_SA(b, h) + aoff + m * 2048 + k * 1024); } while (0)
; #define PG8_MMA(ai, bj, At, Bt) do { __builtin_amdgcn_s_setprio(1); _Pragma("unroll") for (int m = 0; m < 4; ++m) _Pragma("unroll") for (int n = 0; n < 2; ++n) _Pragma("unroll") for (int k = 0; k < 2; ++k) \
;         acc[ai][bj][m][n] = __builtin_amdgcn_mfma_f32_16x16x32_bf16(Bt[n][k], At[m][k], acc[ai][bj][m][n], 0, 0, 0); __builtin_amdgcn_s_setprio(0); } while (0)
; #define PG8_WAIT_V(n) asm volatile("s_waitcnt vmcnt(" #n ")" ::: "memory")
; #define PG8_WAIT_L(n) asm volatile("s_waitcnt lgkmcnt(" #n ")" ::: "memory")
; #define PG8_BAR __builtin_amdgcn_s_barrier()
; #define PG8_SCHED __builtin_amdgcn_sched_barrier(0)
; #define PG8_STAGE(bufoff, gbase, voff) do { _Pragma("unroll") for (int _i = 0; _i < 2; ++_i) \
;         __builtin_amdgcn_global_load_lds((const GAS unsigned*)((const GAS char*)(gbase) + (voff)[_i]), (PG8_LAS unsigned*)(lds + (bufoff) + ldsw + _i * 8192), 16, 0, 0); } while (0)
; #define PG8_LDA(dst, b, h) do { _Pragma("unroll") for (int m = 0; m < 4; ++m) _Pragma("unroll") for (int k = 0; k < 2; ++k) dst[m][k] = *(const PG8_LAS bf16x8*)(lds + PG8_SA(b, h) + aoff + m * 2048 + k * 1024); } while (0)
; #define PG8_WAIT_V(n) asm volatile("s_waitcnt vmcnt(" #n ")" ::: "memory")
; #define PG8_WAIT_L(n) asm volatile("s_waitcnt lgkmcnt(" #n ")" ::: "memory")
; #define PG8_BAR __builtin_amdgcn_s_barrier()
; #define PG8_SCHED __builtin_amdgcn_sched_barrier(0)
; template <class Epi, class Sched, bool ALIGN_EPI = false, bool SP2 = false>
; __device__ __forceinline__ void gemm_phase(PG8_LAS unsigned char* lds, PG8_LAS unsigned char* pf, const Gemm g, const Sched& S, const Epi& E, int wv) {
;     ...
;             PG8_LDA(At, 1, 1); PG8_STAGE(PG8_SB(1, 0), b3, voffB); PG8_STAGE(PG8_SB(1, 1), b3 + hstepB, voffB); PG8_STAGE(PG8_SA(1, 0), a3, voffA);
;             PG8_WAIT_V(8); PG8_WAIT_L(0); PG8_BAR; PG8_MMA(1, 0, At, B0); PG8_MMA(1, 1, At, B1); PG8_BAR; PG8_SCHED;
	s_add_i32 s25, s25, s27
	v_lshl_add_u64 v[208:209], v[208:209], 0, s[16:17]
	s_mov_b32 m0, s25
	ds_read_b128 v[180:183], v162 offset:49152
	ds_read_b128 v[184:187], v162 offset:50176
	ds_read_b128 v[188:191], v162 offset:51200
	ds_read_b128 v[192:195], v162 offset:52224
	ds_read_b128 v[196:199], v162 offset:53248
	ds_read_b128 v[200:203], v162 offset:54272
	ds_read_b128 v[204:207], v162 offset:55296
	ds_read_b128 v[214:217], v162 offset:56320
	global_load_lds_dwordx4 v[208:209], off
	s_add_i32 m0, s25, 0x2000
	s_add_u32 s28, s40, 0x80080
	v_lshl_add_u64 v[208:209], v[218:219], 0, s[16:17]
	s_addc_u32 s29, s41, 0
	s_add_i32 s25, s42, s27
	global_load_lds_dwordx4 v[208:209], off
	v_lshl_add_u64 v[208:209], s[28:29], 0, v[146:147]
	s_mov_b32 m0, s25
	s_nop 0
	global_load_lds_dwordx4 v[208:209], off
	v_lshl_add_u64 v[208:209], s[28:29], 0, v[150:151]
	s_add_i32 m0, s25, 0x2000
	s_nop 0
	global_load_lds_dwordx4 v[208:209], off
	v_lshl_add_u64 v[208:209], v[220:221], 0, s[16:17]
	s_mov_b32 m0, s20
	s_nop 0
	global_load_lds_dwordx4 v[208:209], off
	v_lshl_add_u64 v[208:209], v[222:223], 0, s[16:17]
	s_mov_b32 m0, s21
	s_nop 0
	global_load_lds_dwordx4 v[208:209], off
	s_waitcnt vmcnt(8)
	s_waitcnt lgkmcnt(0)
	s_barrier
	s_waitcnt lgkmcnt(0)
	v_mfma_f32_16x16x32_bf16 v[60:63], v[120:123], v[180:183], v[60:63]
	v_mfma_f32_16x16x32_bf16 v[56:59], v[128:131], v[180:183], v[56:59]
	v_mfma_f32_16x16x32_bf16 v[44:47], v[120:123], v[188:191], v[44:47]
	v_mfma_f32_16x16x32_bf16 v[40:43], v[128:131], v[188:191], v[40:43]
	v_mfma_f32_16x16x32_bf16 v[28:31], v[120:123], v[196:199], v[28:31]
	v_mfma_f32_16x16x32_bf16 v[24:27], v[128:131], v[196:199], v[24:27]
	v_mfma_f32_16x16x32_bf16 v[12:15], v[120:123], v[204:207], v[12:15]
	v_mfma_f32_16x16x32_bf16 v[8:11], v[128:131], v[204:207], v[8:11]
	v_mfma_f32_16x16x32_bf16 v[60:63], v[124:127], v[184:187], v[60:63]
	v_mfma_f32_16x16x32_bf16 v[56:59], v[132:135], v[184:187], v[56:59]
	v_mfma_f32_16x16x32_bf16 v[44:47], v[124:127], v[192:195], v[44:47]
	v_mfma_f32_16x16x32_bf16 v[40:43], v[132:135], v[192:195], v[40:43]
	v_mfma_f32_16x16x32_bf16 v[28:31], v[124:127], v[200:203], v[28:31]
	v_mfma_f32_16x16x32_bf16 v[24:27], v[132:135], v[200:203], v[24:27]
	v_mfma_f32_16x16x32_bf16 v[12:15], v[124:127], v[214:217], v[12:15]
	v_mfma_f32_16x16x32_bf16 v[8:11], v[132:135], v[214:217], v[8:11]
	v_mfma_f32_16x16x32_bf16 v[52:55], v[164:167], v[180:183], v[52:55]
	v_mfma_f32_16x16x32_bf16 v[48:51], v[172:175], v[180:183], v[48:51]
	v_mfma_f32_16x16x32_bf16 v[36:39], v[164:167], v[188:191], v[36:39]
	v_mfma_f32_16x16x32_bf16 v[32:35], v[172:175], v[188:191], v[32:35]
	v_mfma_f32_16x16x32_bf16 v[20:23], v[164:167], v[196:199], v[20:23]
	v_mfma_f32_16x16x32_bf16 v[16:19], v[172:175], v[196:199], v[16:19]
	v_mfma_f32_16x16x32_bf16 v[4:7], v[164:167], v[204:207], v[4:7]
	v_mfma_f32_16x16x32_bf16 v[0:3], v[172:175], v[204:207], v[0:3]
	v_mfma_f32_16x16x32_bf16 v[52:55], v[168:171], v[184:187], v[52:55]
	v_mfma_f32_16x16x32_bf16 v[48:51], v[176:179], v[184:187], v[48:51]
	v_mfma_f32_16x16x32_bf16 v[36:39], v[168:171], v[192:195], v[36:39]
	v_mfma_f32_16x16x32_bf16 v[32:35], v[176:179], v[192:195], v[32:35]
	v_mfma_f32_16x16x32_bf16 v[20:23], v[168:171], v[200:203], v[20:23]
	v_mfma_f32_16x16x32_bf16 v[16:19], v[176:179], v[200:203], v[16:19]
	v_mfma_f32_16x16x32_bf16 v[4:7], v[168:171], v[214:217], v[4:7]
	v_mfma_f32_16x16x32_bf16 v[0:3], v[176:179], v[214:217], v[0:3]
	s_barrier
	s_add_i32 s24, s24, 2
	s_add_u32 s22, s22, 0x100
	s_addc_u32 s23, s23, 0
	s_add_u32 s36, s36, 0x100
	s_addc_u32 s37, s37, 0
	s_cmp_gt_u32 s24, 29
	s_cbranch_scc0 .LBB0_1414
	s_and_b64 vcc, exec, s[6:7]
	s_cbranch_vccz .LBB0_1417
	s_barrier

; #define PG8_STAGE(bufoff, gbase, voff) do { _Pragma("unroll") for (int _i = 0; _i < 2; ++_i) \
;         __builtin_amdgcn_global_load_lds((const GAS unsigned*)((const GAS char*)(gbase) + (voff)[_i]), (PG8_LAS unsigned*)(lds + (bufoff) + ldsw + _i * 8192), 16, 0, 0); } while (0)
; #define PG8_LDA(dst, b, h) do { _Pragma("unroll") for (int m = 0; m < 4; ++m) _Pragma("unroll") for (int k = 0; k < 2; ++k) dst[m][k] = *(const PG8_LAS bf16x8*)(lds + PG8_SA(b, h) + aoff + m * 2048 + k * 1024); } while (0)
; #define PG8_LDB(dst, b, h) do { _Pragma("unroll") for (int n = 0; n < 2; ++n) _Pragma("unroll") for (int k = 0; k < 2; ++k) dst[n][k] = *(const PG8_LAS bf16x8*)(lds + PG8_SB(b, h) + boff + n * 2048 + k * 1024); } while (0)
; #define PG8_MMA(ai, bj, At, Bt) do { __builtin_amdgcn_s_setprio(1); _Pragma("unroll") for (int m = 0; m < 4; ++m) _Pragma("unroll") for (int n = 0; n < 2; ++n) _Pragma("unroll") for (int k = 0; k < 2; ++k) \
;         acc[ai][bj][m][n] = __builtin_amdgcn_mfma_f32_16x16x32_bf16(Bt[n][k], At[m][k], acc[ai][bj][m][n], 0, 0, 0); __builtin_amdgcn_s_setprio(0); } while (0)
; #define PG8_WAIT_V(n) asm volatile("s_waitcnt vmcnt(" #n ")" ::: "memory")
; #define PG8_WAIT_L(n) asm volatile("s_waitcnt lgkmcnt(" #n ")" ::: "memory")
; #define PG8_BAR __builtin_amdgcn_s_barrier()
; #define PG8_SCHED __builtin_amdgcn_sched_barrier(0)
; #define PG8_LDA(dst, b, h) do { _Pragma("unroll") for (int m = 0; m < 4; ++m) _Pragma("unroll") for (int k = 0; k < 2; ++k) dst[m][k] = *(const PG8_LAS bf16x8*)(lds + PG8_SA(b, h) + aoff + m * 2048 + k * 1024); } while (0)
; template <class Epi, class Sched, bool ALIGN_EPI = false, bool SP2 = false>
; __device__ __forceinline__ void gemm_phase(PG8_LAS unsigned char* lds, PG8_LAS unsigned char* pf, const Gemm g, const Sched& S, const Epi& E, int wv) {
;     ...
;             PG8_LDB(B0, 0, 0); PG8_LDB(B1, 0, 1); PG8_SCHED; PG8_LDA(At, 0, 0); PG8_STAGE(PG8_SA(1, 1), a1 + (Sched::SPLIT ? hsA : (long)hstepA), voffA);
;             PG8_WAIT_V(8); PG8_WAIT_L(0); PG8_BAR; PG8_MMA(0, 0, At, B0); PG8_MMA(0, 1, At, B1); PG8_BAR; PG8_SCHED;
;             PG8_LDA(At, 0, 1); PG8_STAGE(PG8_SB(0, 0), b2, voffB); PG8_STAGE(PG8_SB(0, 1), b2 + hstepB, voffB); PG8_STAGE(PG8_SA(0, 0), a2, voffA);
;             PG8_WAIT_V(8); PG8_WAIT_L(0); PG8_BAR; PG8_MMA(1, 0, At, B0); PG8_MMA(1, 1, At, B1); PG8_BAR; PG8_SCHED;
.LBB0_1456:
	s_cmp_eq_u32 s25, s60
	s_cselect_b64 s[28:29], -1, 0
	s_add_i32 s15, s15, 2
	s_add_u32 s31, s38, s60
	s_addc_u32 s62, s39, s61
	s_add_u32 s31, s31, 0x100
	s_addc_u32 s94, s62, 0
	s_add_u32 s64, s23, s60
	s_addc_u32 s65, s24, s61
	s_and_b64 s[62:63], s[28:29], exec
	s_cselect_b32 s63, s20, s65
	s_cselect_b32 s62, s21, s64
	s_add_i32 s95, 0, 0x10000
	s_and_b64 s[64:65], s[28:29], exec
	v_add_u32_e32 v160, s95, v162
	s_cselect_b32 s65, s45, s94
	s_cselect_b32 s64, s44, s31
	s_add_i32 s31, 0, 0x14000
	ds_read_b128 v[132:135], v160
	ds_read_b128 v[136:139], v160 offset:1024
	ds_read_b128 v[140:143], v160 offset:2048
	ds_read_b128 v[164:167], v160 offset:3072
	v_add_u32_e32 v160, s31, v162
	ds_read_b128 v[168:171], v160
	ds_read_b128 v[172:175], v160 offset:1024
	ds_read_b128 v[176:179], v160 offset:2048
	ds_read_b128 v[180:183], v160 offset:3072
	v_lshl_add_u64 v[208:209], v[130:131], 0, s[60:61]
	s_add_i32 m0, s5, 0xc000
	ds_read_b128 v[184:187], v163
	ds_read_b128 v[188:191], v163 offset:1024
	ds_read_b128 v[192:195], v163 offset:2048
	ds_read_b128 v[196:199], v163 offset:3072
	ds_read_b128 v[200:203], v163 offset:4096
	ds_read_b128 v[204:207], v163 offset:5120
	ds_read_b128 v[214:217], v163 offset:6144
	ds_read_b128 v[218:221], v163 offset:7168
	global_load_lds_dwordx4 v[208:209], off
	v_lshl_add_u64 v[208:209], v[128:129], 0, s[60:61]
	s_add_i32 m0, s5, 0xe000
	s_nop 0
	global_load_lds_dwordx4 v[208:209], off
	s_waitcnt vmcnt(8)
	s_waitcnt lgkmcnt(0)
	s_barrier
	s_waitcnt lgkmcnt(0)
	v_mfma_f32_16x16x32_bf16 v[124:127], v[132:135], v[184:187], v[124:127]
	v_mfma_f32_16x16x32_bf16 v[120:123], v[140:143], v[184:187], v[120:123]
	v_mfma_f32_16x16x32_bf16 v[108:111], v[132:135], v[192:195], v[108:111]
	v_mfma_f32_16x16x32_bf16 v[104:107], v[140:143], v[192:195], v[104:107]
	v_mfma_f32_16x16x32_bf16 v[92:95], v[132:135], v[200:203], v[92:95]
	v_mfma_f32_16x16x32_bf16 v[88:91], v[140:143], v[200:203], v[88:91]
	v_mfma_f32_16x16x32_bf16 v[76:79], v[132:135], v[214:217], v[76:79]
	v_mfma_f32_16x16x32_bf16 v[72:75], v[140:143], v[214:217], v[72:75]
	v_mfma_f32_16x16x32_bf16 v[124:127], v[136:139], v[188:191], v[124:127]
	v_mfma_f32_16x16x32_bf16 v[120:123], v[164:167], v[188:191], v[120:123]
	v_mfma_f32_16x16x32_bf16 v[108:111], v[136:139], v[196:199], v[108:111]
	v_mfma_f32_16x16x32_bf16 v[104:107], v[164:167], v[196:199], v[104:107]
	v_mfma_f32_16x16x32_bf16 v[92:95], v[136:139], v[204:207], v[92:95]
	v_mfma_f32_16x16x32_bf16 v[88:91], v[164:167], v[204:207], v[88:91]
	v_mfma_f32_16x16x32_bf16 v[76:79], v[136:139], v[218:221], v[76:79]
	v_mfma_f32_16x16x32_bf16 v[72:75], v[164:167], v[218:221], v[72:75]
	v_mfma_f32_16x16x32_bf16 v[116:119], v[168:171], v[184:187], v[116:119]
	v_mfma_f32_16x16x32_bf16 v[112:115], v[176:179], v[184:187], v[112:115]
	v_mfma_f32_16x16x32_bf16 v[100:103], v[168:171], v[192:195], v[100:103]
	v_mfma_f32_16x16x32_bf16 v[96:99], v[176:179], v[192:195], v[96:99]
	v_mfma_f32_16x16x32_bf16 v[84:87], v[168:171], v[200:203], v[84:87]
	v_mfma_f32_16x16x32_bf16 v[80:83], v[176:179], v[200:203], v[80:83]
	v_mfma_f32_16x16x32_bf16 v[68:71], v[168:171], v[214:217], v[68:71]
	v_mfma_f32_16x16x32_bf16 v[64:67], v[176:179], v[214:217], v[64:67]
	v_mfma_f32_16x16x32_bf16 v[116:119], v[172:175], v[188:191], v[116:119]
	v_mfma_f32_16x16x32_bf16 v[112:115], v[180:183], v[188:191], v[112:115]
	v_mfma_f32_16x16x32_bf16 v[100:103], v[172:175], v[196:199], v[100:103]
	v_mfma_f32_16x16x32_bf16 v[96:99], v[180:183], v[196:199], v[96:99]
	v_mfma_f32_16x16x32_bf16 v[84:87], v[172:175], v[204:207], v[84:87]
	v_mfma_f32_16x16x32_bf16 v[80:83], v[180:183], v[204:207], v[80:83]
	v_mfma_f32_16x16x32_bf16 v[68:71], v[172:175], v[218:221], v[68:71]
	v_mfma_f32_16x16x32_bf16 v[64:67], v[180:183], v[218:221], v[64:67]
	s_barrier
	s_add_i32 s94, s95, s27
	v_lshl_add_u64 v[208:209], s[62:63], 0, v[146:147]
	s_mov_b32 m0, s94
	ds_read_b128 v[184:187], v163 offset:16384
	ds_read_b128 v[188:191], v163 offset:17408
	ds_read_b128 v[192:195], v163 offset:18432
	ds_read_b128 v[196:199], v163 offset:19456
	ds_read_b128 v[200:203], v163 offset:20480
	ds_read_b128 v[204:207], v163 offset:21504
	ds_read_b128 v[214:217], v163 offset:22528
	ds_read_b128 v[218:221], v163 offset:23552
	global_load_lds_dwordx4 v[208:209], off
	s_add_i32 m0, s94, 0x2000
	s_add_u32 s94, s62, 0x80000
	v_lshl_add_u64 v[222:223], s[62:63], 0, v[150:151]
	s_addc_u32 s95, s63, 0
	s_add_i32 s31, s31, s27
	global_load_lds_dwordx4 v[222:223], off
	v_lshl_add_u64 v[224:225], s[94:95], 0, v[146:147]
	s_mov_b32 m0, s31
	v_lshl_add_u64 v[226:227], s[64:65], 0, v[148:149]
	global_load_lds_dwordx4 v[224:225], off
	v_lshl_add_u64 v[224:225], s[94:95], 0, v[150:151]
	s_add_i32 m0, s31, 0x2000
	s_nop 0
	global_load_lds_dwordx4 v[224:225], off
	v_lshl_add_u64 v[224:225], s[64:65], 0, v[144:145]
	s_mov_b32 m0, s5
	s_nop 0
	global_load_lds_dwordx4 v[224:225], off
	s_mov_b32 m0, s53
	s_nop 0
	global_load_lds_dwordx4 v[226:227], off
	s_waitcnt vmcnt(8)
	s_waitcnt lgkmcnt(0)
	s_barrier
; #define PG8_STAGE(bufoff, gbase, voff) do { _Pragma("unroll") for (int _i = 0; _i < 2; ++_i) \
;         __builtin_amdgcn_global_load_lds((const GAS unsigned*)((const GAS char*)(gbase) + (voff)[_i]), (PG8_LAS unsigned*)(lds + (bufoff) + ldsw + _i * 8192), 16, 0, 0); } while (0)
; #define PG8_LDA(dst, b, h) do { _Pragma("unroll") for (int m = 0; m < 4; ++m) _Pragma("unroll") for (int k = 0; k < 2; ++k) dst[m][k] = *(const PG8_LAS bf16x8*)(lds + PG8_SA(b, h) + aoff + m * 2048 + k * 1024); } while (0)
; #define PG8_LDB(dst, b, h) do { _Pragma("unroll") for (int n = 0; n < 2; ++n) _Pragma("unroll") for (int k = 0; k < 2; ++k) dst[n][k] = *(const PG8_LAS bf16x8*)(lds + PG8_SB(b, h) + boff + n * 2048 + k * 1024); } while (0)
; #define PG8_MMA(ai, bj, At, Bt) do { __builtin_amdgcn_s_setprio(1); _Pragma("unroll") for (int m = 0; m < 4; ++m) _Pragma("unroll") for (int n = 0; n < 2; ++n) _Pragma("unroll") for (int k = 0; k < 2; ++k) \
;         acc[ai][bj][m][n] = __builtin_amdgcn_mfma_f32_16x16x32_bf16(Bt[n][k], At[m][k], acc[ai][bj][m][n], 0, 0, 0); __builtin_amdgcn_s_setprio(0); } while (0)
; #define PG8_WAIT_V(n) asm volatile("s_waitcnt vmcnt(" #n ")" ::: "memory")
; #define PG8_WAIT_L(n) asm volatile("s_waitcnt lgkmcnt(" #n ")" ::: "memory")
; #define PG8_BAR __builtin_amdgcn_s_barrier()
; #define PG8_SCHED __builtin_amdgcn_sched_barrier(0)
; #define PG8_STAGE(bufoff, gbase, voff) do { _Pragma("unroll") for (int _i = 0; _i < 2; ++_i) \
;         __builtin_amdgcn_global_load_lds((const GAS unsigned*)((const GAS char*)(gbase) + (voff)[_i]), (PG8_LAS unsigned*)(lds + (bufoff) + ldsw + _i * 8192), 16, 0, 0); } while (0)
; #define PG8_BAR __builtin_amdgcn_s_barrier()
; template <class Epi, class Sched, bool ALIGN_EPI = false, bool SP2 = false>
; __device__ __forceinline__ void gemm_phase(PG8_LAS unsigned char* lds, PG8_LAS unsigned char* pf, const Gemm g, const Sched& S, const Epi& E, int wv) {
;     ...
;             PG8_WAIT_V(8); PG8_WAIT_L(0); PG8_BAR; PG8_MMA(1, 0, At, B0); PG8_MMA(1, 1, At, B1); PG8_BAR; PG8_SCHED;
;             PG8_LDB(B0, 1, 0); PG8_LDB(B1, 1, 1); PG8_SCHED; PG8_LDA(At, 1, 0); PG8_STAGE(PG8_SA(0, 1), a2 + (Sched::SPLIT ? ((last && has_next) ? (nxt.kh > 0 ? -(long)hstepA : (long)hstepA) : hsA) : (long)hstepA), voffA);
;             PG8_WAIT_V(8); PG8_WAIT_L(0); PG8_BAR; PG8_MMA(0, 0, At, B0); PG8_MMA(0, 1, At, B1); PG8_BAR; PG8_SCHED;
	s_waitcnt lgkmcnt(0)
	v_mfma_f32_16x16x32_bf16 v[60:63], v[132:135], v[184:187], v[60:63]
	v_mfma_f32_16x16x32_bf16 v[56:59], v[140:143], v[184:187], v[56:59]
	v_mfma_f32_16x16x32_bf16 v[44:47], v[132:135], v[192:195], v[44:47]
	v_mfma_f32_16x16x32_bf16 v[40:43], v[140:143], v[192:195], v[40:43]
	v_mfma_f32_16x16x32_bf16 v[28:31], v[132:135], v[200:203], v[28:31]
	v_mfma_f32_16x16x32_bf16 v[24:27], v[140:143], v[200:203], v[24:27]
	v_mfma_f32_16x16x32_bf16 v[12:15], v[132:135], v[214:217], v[12:15]
	v_mfma_f32_16x16x32_bf16 v[8:11], v[140:143], v[214:217], v[8:11]
	v_mfma_f32_16x16x32_bf16 v[60:63], v[136:139], v[188:191], v[60:63]
	v_mfma_f32_16x16x32_bf16 v[56:59], v[164:167], v[188:191], v[56:59]
	v_mfma_f32_16x16x32_bf16 v[44:47], v[136:139], v[196:199], v[44:47]
	v_mfma_f32_16x16x32_bf16 v[40:43], v[164:167], v[196:199], v[40:43]
	v_mfma_f32_16x16x32_bf16 v[28:31], v[136:139], v[204:207], v[28:31]
	v_mfma_f32_16x16x32_bf16 v[24:27], v[164:167], v[204:207], v[24:27]
	v_mfma_f32_16x16x32_bf16 v[12:15], v[136:139], v[218:221], v[12:15]
	v_mfma_f32_16x16x32_bf16 v[8:11], v[164:167], v[218:221], v[8:11]
	v_mfma_f32_16x16x32_bf16 v[52:55], v[168:171], v[184:187], v[52:55]
	v_mfma_f32_16x16x32_bf16 v[48:51], v[176:179], v[184:187], v[48:51]
	v_mfma_f32_16x16x32_bf16 v[36:39], v[168:171], v[192:195], v[36:39]
	v_mfma_f32_16x16x32_bf16 v[32:35], v[176:179], v[192:195], v[32:35]
	v_mfma_f32_16x16x32_bf16 v[20:23], v[168:171], v[200:203], v[20:23]
	v_mfma_f32_16x16x32_bf16 v[16:19], v[176:179], v[200:203], v[16:19]
	v_mfma_f32_16x16x32_bf16 v[4:7], v[168:171], v[214:217], v[4:7]
	v_mfma_f32_16x16x32_bf16 v[0:3], v[176:179], v[214:217], v[0:3]
	v_mfma_f32_16x16x32_bf16 v[52:55], v[172:175], v[188:191], v[52:55]
	v_mfma_f32_16x16x32_bf16 v[48:51], v[180:183], v[188:191], v[48:51]
	v_mfma_f32_16x16x32_bf16 v[36:39], v[172:175], v[196:199], v[36:39]
	v_mfma_f32_16x16x32_bf16 v[32:35], v[180:183], v[196:199], v[32:35]
	v_mfma_f32_16x16x32_bf16 v[20:23], v[172:175], v[204:207], v[20:23]
	v_mfma_f32_16x16x32_bf16 v[16:19], v[180:183], v[204:207], v[16:19]
	v_mfma_f32_16x16x32_bf16 v[4:7], v[172:175], v[218:221], v[4:7]
	v_mfma_f32_16x16x32_bf16 v[0:3], v[180:183], v[218:221], v[0:3]
	s_barrier
	s_add_i32 s31, 0, 0x18000
	v_add_u32_e32 v160, s31, v162
	s_add_i32 s94, 0, 0x1c000
	ds_read_b128 v[132:135], v160
	ds_read_b128 v[136:139], v160 offset:1024
	ds_read_b128 v[140:143], v160 offset:2048
	ds_read_b128 v[164:167], v160 offset:3072
	v_add_u32_e32 v160, s94, v162
	ds_read_b128 v[168:171], v160
	ds_read_b128 v[172:175], v160 offset:1024
	ds_read_b128 v[176:179], v160 offset:2048
	ds_read_b128 v[180:183], v160 offset:3072
	s_and_b64 s[28:29], s[56:57], s[28:29]
	s_and_b64 s[28:29], s[28:29], exec
	s_cselect_b32 s28, s40, s36
	s_cselect_b32 s29, s41, s37
	s_add_u32 s28, s64, s28
	s_addc_u32 s29, s65, s29
	s_mov_b32 m0, s75
	v_lshl_add_u64 v[228:229], s[28:29], 0, v[144:145]
	ds_read_b128 v[184:187], v163 offset:32768
	ds_read_b128 v[188:191], v163 offset:33792
	ds_read_b128 v[192:195], v163 offset:34816
	ds_read_b128 v[196:199], v163 offset:35840
	ds_read_b128 v[200:203], v163 offset:36864
	ds_read_b128 v[204:207], v163 offset:37888
	ds_read_b128 v[214:217], v163 offset:38912
	ds_read_b128 v[218:221], v163 offset:39936
	global_load_lds_dwordx4 v[228:229], off
	v_lshl_add_u64 v[228:229], s[28:29], 0, v[148:149]
	s_mov_b32 m0, s76
	s_nop 0
	global_load_lds_dwordx4 v[228:229], off
	s_waitcnt vmcnt(8)
	s_waitcnt lgkmcnt(0)
	s_barrier
	s_waitcnt lgkmcnt(0)
	v_mfma_f32_16x16x32_bf16 v[124:127], v[132:135], v[184:187], v[124:127]
	v_mfma_f32_16x16x32_bf16 v[120:123], v[140:143], v[184:187], v[120:123]
	v_mfma_f32_16x16x32_bf16 v[108:111], v[132:135], v[192:195], v[108:111]
	v_mfma_f32_16x16x32_bf16 v[104:107], v[140:143], v[192:195], v[104:107]
	v_mfma_f32_16x16x32_bf16 v[92:95], v[132:135], v[200:203], v[92:95]
	v_mfma_f32_16x16x32_bf16 v[88:91], v[140:143], v[200:203], v[88:91]
	v_mfma_f32_16x16x32_bf16 v[76:79], v[132:135], v[214:217], v[76:79]
	v_mfma_f32_16x16x32_bf16 v[72:75], v[140:143], v[214:217], v[72:75]
	v_mfma_f32_16x16x32_bf16 v[124:127], v[136:139], v[188:191], v[124:127]
	v_mfma_f32_16x16x32_bf16 v[120:123], v[164:167], v[188:191], v[120:123]
	v_mfma_f32_16x16x32_bf16 v[108:111], v[136:139], v[196:199], v[108:111]
	v_mfma_f32_16x16x32_bf16 v[104:107], v[164:167], v[196:199], v[104:107]
	v_mfma_f32_16x16x32_bf16 v[92:95], v[136:139], v[204:207], v[92:95]
	v_mfma_f32_16x16x32_bf16 v[88:91], v[164:167], v[204:207], v[88:91]
	v_mfma_f32_16x16x32_bf16 v[76:79], v[136:139], v[218:221], v[76:79]
	v_mfma_f32_16x16x32_bf16 v[72:75], v[164:167], v[218:221], v[72:75]
	v_mfma_f32_16x16x32_bf16 v[116:119], v[168:171], v[184:187], v[116:119]
	v_mfma_f32_16x16x32_bf16 v[112:115], v[176:179], v[184:187], v[112:115]
	v_mfma_f32_16x16x32_bf16 v[100:103], v[168:171], v[192:195], v[100:103]
	v_mfma_f32_16x16x32_bf16 v[96:99], v[176:179], v[192:195], v[96:99]
	v_mfma_f32_16x16x32_bf16 v[84:87], v[168:171], v[200:203], v[84:87]
	v_mfma_f32_16x16x32_bf16 v[80:83], v[176:179], v[200:203], v[80:83]
	v_mfma_f32_16x16x32_bf16 v[68:71], v[168:171], v[214:217], v[68:71]
	v_mfma_f32_16x16x32_bf16 v[64:67], v[176:179], v[214:217], v[64:67]
	v_mfma_f32_16x16x32_bf16 v[116:119], v[172:175], v[188:191], v[116:119]
	v_mfma_f32_16x16x32_bf16 v[112:115], v[180:183], v[188:191], v[112:115]
	v_mfma_f32_16x16x32_bf16 v[100:103], v[172:175], v[196:199], v[100:103]
	v_mfma_f32_16x16x32_bf16 v[96:99], v[180:183], v[196:199], v[96:99]
	v_mfma_f32_16x16x32_bf16 v[84:87], v[172:175], v[204:207], v[84:87]
	v_mfma_f32_16x16x32_bf16 v[80:83], v[180:183], v[204:207], v[80:83]
	v_mfma_f32_16x16x32_bf16 v[68:71], v[172:175], v[218:221], v[68:71]
	v_mfma_f32_16x16x32_bf16 v[64:67], v[180:183], v[218:221], v[64:67]
	s_barrier
; #define PG8_STAGE(bufoff, gbase, voff) do { _Pragma("unroll") for (int _i = 0; _i < 2; ++_i) \
;         __builtin_amdgcn_global_load_lds((const GAS unsigned*)((const GAS char*)(gbase) + (voff)[_i]), (PG8_LAS unsigned*)(lds + (bufoff) + ldsw + _i * 8192), 16, 0, 0); } while (0)
; #define PG8_LDA(dst, b, h) do { _Pragma("unroll") for (int m = 0; m < 4; ++m) _Pragma("unroll") for (int k = 0; k < 2; ++k) dst[m][k] = *(const PG8_LAS bf16x8*)(lds + PG8_SA(b, h) + aoff + m * 2048 + k * 1024); } while (0)
; #define PG8_MMA(ai, bj, At, Bt) do { __builtin_amdgcn_s_setprio(1); _Pragma("unroll") for (int m = 0; m < 4; ++m) _Pragma("unroll") for (int n = 0; n < 2; ++n) _Pragma("unroll") for (int k = 0; k < 2; ++k) \
;         acc[ai][bj][m][n] = __builtin_amdgcn_mfma_f32_16x16x32_bf16(Bt[n][k], At[m][k], acc[ai][bj][m][n], 0, 0, 0); __builtin_amdgcn_s_setprio(0); } while (0)
; #define PG8_WAIT_V(n) asm volatile("s_waitcnt vmcnt(" #n ")" ::: "memory")
; #define PG8_WAIT_L(n) asm volatile("s_waitcnt lgkmcnt(" #n ")" ::: "memory")
; #define PG8_BAR __builtin_amdgcn_s_barrier()
; #define PG8_SCHED __builtin_amdgcn_sched_barrier(0)
; #define PG8_STAGE(bufoff, gbase, voff) do { _Pragma("unroll") for (int _i = 0; _i < 2; ++_i) \
;         __builtin_amdgcn_global_load_lds((const GAS unsigned*)((const GAS char*)(gbase) + (voff)[_i]), (PG8_LAS unsigned*)(lds + (bufoff) + ldsw + _i * 8192), 16, 0, 0); } while (0)
; #define PG8_LDA(dst, b, h) do { _Pragma("unroll") for (int m = 0; m < 4; ++m) _Pragma("unroll") for (int k = 0; k < 2; ++k) dst[m][k] = *(const PG8_LAS bf16x8*)(lds + PG8_SA(b, h) + aoff + m * 2048 + k * 1024); } while (0)
; #define PG8_WAIT_V(n) asm volatile("s_waitcnt vmcnt(" #n ")" ::: "memory")
; #define PG8_WAIT_L(n) asm volatile("s_waitcnt lgkmcnt(" #n ")" ::: "memory")
; #define PG8_BAR __builtin_amdgcn_s_barrier()
; #define PG8_SCHED __builtin_amdgcn_sched_barrier(0)
; template <class Epi, class Sched, bool ALIGN_EPI = false, bool SP2 = false>
; __device__ __forceinline__ void gemm_phase(PG8_LAS unsigned char* lds, PG8_LAS unsigned char* pf, const Gemm g, const Sched& S, const Epi& E, int wv) {
;     ...
;             PG8_LDA(At, 1, 1); PG8_STAGE(PG8_SB(1, 0), b3, voffB); PG8_STAGE(PG8_SB(1, 1), b3 + hstepB, voffB); PG8_STAGE(PG8_SA(1, 0), a3, voffA);
;             PG8_WAIT_V(8); PG8_WAIT_L(0); PG8_BAR; PG8_MMA(1, 0, At, B0); PG8_MMA(1, 1, At, B1); PG8_BAR; PG8_SCHED;
	s_add_i32 s28, s31, s27
	v_lshl_add_u64 v[208:209], v[208:209], 0, s[16:17]
	s_mov_b32 m0, s28
	ds_read_b128 v[184:187], v163 offset:49152
	ds_read_b128 v[188:191], v163 offset:50176
	ds_read_b128 v[192:195], v163 offset:51200
	ds_read_b128 v[196:199], v163 offset:52224
	ds_read_b128 v[200:203], v163 offset:53248
	ds_read_b128 v[204:207], v163 offset:54272
	ds_read_b128 v[214:217], v163 offset:55296
	ds_read_b128 v[218:221], v163 offset:56320
	global_load_lds_dwordx4 v[208:209], off
	s_add_i32 m0, s28, 0x2000
	s_add_u32 s28, s62, 0x80080
	v_lshl_add_u64 v[208:209], v[222:223], 0, s[16:17]
	s_addc_u32 s29, s63, 0
	s_add_i32 s31, s94, s27
	global_load_lds_dwordx4 v[208:209], off
	v_lshl_add_u64 v[208:209], s[28:29], 0, v[146:147]
	s_mov_b32 m0, s31
	s_nop 0
	global_load_lds_dwordx4 v[208:209], off
	v_lshl_add_u64 v[208:209], s[28:29], 0, v[150:151]
	s_add_i32 m0, s31, 0x2000
	s_nop 0
	global_load_lds_dwordx4 v[208:209], off
	v_lshl_add_u64 v[208:209], v[224:225], 0, s[16:17]
	s_mov_b32 m0, s77
	s_nop 0
	global_load_lds_dwordx4 v[208:209], off
	v_lshl_add_u64 v[208:209], v[226:227], 0, s[16:17]
	s_mov_b32 m0, s78
	s_nop 0
	global_load_lds_dwordx4 v[208:209], off
	s_waitcnt vmcnt(8)
	s_waitcnt lgkmcnt(0)
	s_barrier
	s_waitcnt lgkmcnt(0)
	v_mfma_f32_16x16x32_bf16 v[60:63], v[132:135], v[184:187], v[60:63]
	v_mfma_f32_16x16x32_bf16 v[56:59], v[140:143], v[184:187], v[56:59]
	v_mfma_f32_16x16x32_bf16 v[44:47], v[132:135], v[192:195], v[44:47]
	v_mfma_f32_16x16x32_bf16 v[40:43], v[140:143], v[192:195], v[40:43]
	v_mfma_f32_16x16x32_bf16 v[28:31], v[132:135], v[200:203], v[28:31]
	v_mfma_f32_16x16x32_bf16 v[24:27], v[140:143], v[200:203], v[24:27]
	v_mfma_f32_16x16x32_bf16 v[12:15], v[132:135], v[214:217], v[12:15]
	v_mfma_f32_16x16x32_bf16 v[8:11], v[140:143], v[214:217], v[8:11]
	v_mfma_f32_16x16x32_bf16 v[60:63], v[136:139], v[188:191], v[60:63]
	v_mfma_f32_16x16x32_bf16 v[56:59], v[164:167], v[188:191], v[56:59]
	v_mfma_f32_16x16x32_bf16 v[44:47], v[136:139], v[196:199], v[44:47]
	v_mfma_f32_16x16x32_bf16 v[40:43], v[164:167], v[196:199], v[40:43]
	v_mfma_f32_16x16x32_bf16 v[28:31], v[136:139], v[204:207], v[28:31]
	v_mfma_f32_16x16x32_bf16 v[24:27], v[164:167], v[204:207], v[24:27]
	v_mfma_f32_16x16x32_bf16 v[12:15], v[136:139], v[218:221], v[12:15]
	v_mfma_f32_16x16x32_bf16 v[8:11], v[164:167], v[218:221], v[8:11]
	v_mfma_f32_16x16x32_bf16 v[52:55], v[168:171], v[184:187], v[52:55]
	v_mfma_f32_16x16x32_bf16 v[48:51], v[176:179], v[184:187], v[48:51]
	v_mfma_f32_16x16x32_bf16 v[36:39], v[168:171], v[192:195], v[36:39]
	v_mfma_f32_16x16x32_bf16 v[32:35], v[176:179], v[192:195], v[32:35]
	v_mfma_f32_16x16x32_bf16 v[20:23], v[168:171], v[200:203], v[20:23]
	v_mfma_f32_16x16x32_bf16 v[16:19], v[176:179], v[200:203], v[16:19]
	v_mfma_f32_16x16x32_bf16 v[4:7], v[168:171], v[214:217], v[4:7]
	v_mfma_f32_16x16x32_bf16 v[0:3], v[176:179], v[214:217], v[0:3]
	v_mfma_f32_16x16x32_bf16 v[52:55], v[172:175], v[188:191], v[52:55]
	v_mfma_f32_16x16x32_bf16 v[48:51], v[180:183], v[188:191], v[48:51]
	v_mfma_f32_16x16x32_bf16 v[36:39], v[172:175], v[196:199], v[36:39]
	v_mfma_f32_16x16x32_bf16 v[32:35], v[180:183], v[196:199], v[32:35]
	v_mfma_f32_16x16x32_bf16 v[20:23], v[172:175], v[204:207], v[20:23]
	v_mfma_f32_16x16x32_bf16 v[16:19], v[180:183], v[204:207], v[16:19]
	v_mfma_f32_16x16x32_bf16 v[4:7], v[172:175], v[218:221], v[4:7]
	v_mfma_f32_16x16x32_bf16 v[0:3], v[180:183], v[218:221], v[0:3]
	s_barrier
	s_add_u32 s60, s60, 0x100
	s_addc_u32 s61, s61, 0
	s_cmp_ge_u32 s15, s22
	s_cbranch_scc0 .LBB0_1456
	s_and_b64 vcc, exec, s[8:9]
	s_cbranch_vccz .LBB0_1459
	s_barrier

; #define PG8_STAGE(bufoff, gbase, voff) do { _Pragma("unroll") for (int _i = 0; _i < 2; ++_i) \
;         __builtin_amdgcn_global_load_lds((const GAS unsigned*)((const GAS char*)(gbase) + (voff)[_i]), (PG8_LAS unsigned*)(lds + (bufoff) + ldsw + _i * 8192), 16, 0, 0); } while (0)
; #define PG8_LDA(dst, b, h) do { _Pragma("unroll") for (int m = 0; m < 4; ++m) _Pragma("unroll") for (int k = 0; k < 2; ++k) dst[m][k] = *(const PG8_LAS bf16x8*)(lds + PG8_SA(b, h) + aoff + m * 2048 + k * 1024); } while (0)
; #define PG8_LDB(dst, b, h) do { _Pragma("unroll") for (int n = 0; n < 2; ++n) _Pragma("unroll") for (int k = 0; k < 2; ++k) dst[n][k] = *(const PG8_LAS bf16x8*)(lds + PG8_SB(b, h) + boff + n * 2048 + k * 1024); } while (0)
; #define PG8_MMA(ai, bj, At, Bt) do { __builtin_amdgcn_s_setprio(1); _Pragma("unroll") for (int m = 0; m < 4; ++m) _Pragma("unroll") for (int n = 0; n < 2; ++n) _Pragma("unroll") for (int k = 0; k < 2; ++k) \
;         acc[ai][bj][m][n] = __builtin_amdgcn_mfma_f32_16x16x32_bf16(Bt[n][k], At[m][k], acc[ai][bj][m][n], 0, 0, 0); __builtin_amdgcn_s_setprio(0); } while (0)
; #define PG8_WAIT_V(n) asm volatile("s_waitcnt vmcnt(" #n ")" ::: "memory")
; #define PG8_WAIT_L(n) asm volatile("s_waitcnt lgkmcnt(" #n ")" ::: "memory")
; #define PG8_BAR __builtin_amdgcn_s_barrier()
; #define PG8_SCHED __builtin_amdgcn_sched_barrier(0)
; #define PG8_STAGE(bufoff, gbase, voff) do { _Pragma("unroll") for (int _i = 0; _i < 2; ++_i) \
;         __builtin_amdgcn_global_load_lds((const GAS unsigned*)((const GAS char*)(gbase) + (voff)[_i]), (PG8_LAS unsigned*)(lds + (bufoff) + ldsw + _i * 8192), 16, 0, 0); } while (0)
; #define PG8_LDA(dst, b, h) do { _Pragma("unroll") for (int m = 0; m < 4; ++m) _Pragma("unroll") for (int k = 0; k < 2; ++k) dst[m][k] = *(const PG8_LAS bf16x8*)(lds + PG8_SA(b, h) + aoff + m * 2048 + k * 1024); } while (0)
; #define PG8_BAR __builtin_amdgcn_s_barrier()
; template <class Epi, class Sched>
; __device__ __forceinline__ void gemm_phase_strip(PG8_LAS unsigned char* lds, PG8_LAS unsigned char* slds, PG8_LAS unsigned char* pf, const Gemm g, const Sched& S, const Epi& E, int wv) {
;     ...
;             PG8_LDB(B0, 0, 0); PG8_LDB(B1, 0, 1); PG8_SCHED; PG8_LDA(At, 0, 0); PG8_STAGE(PG8_SA(1, 1), a1 + PG8_HS, voffA);
;             PG8_WAIT_V(8); PG8_WAIT_L(0); PG8_BAR; PG8_MMA(0, 0, At, B0); PG8_MMA(0, 1, At, B1); PG8_BAR; PG8_SCHED;
.LBB0_1560:
	s_barrier
	s_xor_b32 s74, s74, 0x1000
	s_add_i32 s23, s23, 2
	s_add_u32 s14, s14, 0x100
	s_addc_u32 s15, s15, 0
	s_cmpk_gt_u32 s23, 0x55
	s_cbranch_scc1 .LBB0_1573
.LBB0_1561:
	s_add_u32 s24, s12, s14
	s_addc_u32 s25, s13, s15
	s_add_u32 s40, s24, 0x100
	s_addc_u32 s41, s25, 0
	s_add_u32 s52, s21, s14
	s_addc_u32 s53, s22, s15
	s_add_i32 s58, 0, 0x10000
	s_add_i32 s59, 0, 0x14000
	v_add_u32_e32 v136, s58, v233
	ds_read_b128 v[148:151], v136
	ds_read_b128 v[144:147], v136 offset:1024
	ds_read_b128 v[166:169], v136 offset:2048
	ds_read_b128 v[162:165], v136 offset:3072
	v_add_u32_e32 v136, s59, v233
	ds_read_b128 v[156:159], v136
	ds_read_b128 v[152:155], v136 offset:1024
	ds_read_b128 v[174:177], v136 offset:2048
	ds_read_b128 v[170:173], v136 offset:3072
	s_cmpk_eq_i32 s14, 0x2b00
	s_cselect_b64 s[54:55], -1, 0
	s_and_b64 s[24:25], s[54:55], exec
	s_cselect_b32 s57, s11, s41
	s_cselect_b32 s56, s10, s40
	s_cselect_b32 s53, s45, s53
	s_cselect_b32 s52, s44, s52
	v_lshl_add_u64 v[222:223], v[220:221], 0, s[14:15]
	s_add_i32 m0, s66, 0xc000
	ds_read_b128 v[136:139], v236
	ds_read_b128 v[140:143], v236 offset:1024
	ds_read_b128 v[178:181], v236 offset:2048
	ds_read_b128 v[182:185], v236 offset:3072
	ds_read_b128 v[186:189], v236 offset:4096
	ds_read_b128 v[190:193], v236 offset:5120
	ds_read_b128 v[194:197], v236 offset:6144
	ds_read_b128 v[198:201], v236 offset:7168
	global_load_lds_dwordx4 v[222:223], off
	v_lshl_add_u64 v[222:223], v[218:219], 0, s[14:15]
	s_add_i32 m0, s66, 0xe000
	s_nop 0
	global_load_lds_dwordx4 v[222:223], off
	s_waitcnt vmcnt(8)
	s_waitcnt lgkmcnt(0)
	s_barrier
	s_waitcnt lgkmcnt(0)
	v_mfma_f32_16x16x32_bf16 v[132:135], v[148:151], v[136:139], v[132:135]
	v_mfma_f32_16x16x32_bf16 v[128:131], v[166:169], v[136:139], v[128:131]
	v_mfma_f32_16x16x32_bf16 v[124:127], v[148:151], v[178:181], v[124:127]
	v_mfma_f32_16x16x32_bf16 v[120:123], v[166:169], v[178:181], v[120:123]
	v_mfma_f32_16x16x32_bf16 v[116:119], v[148:151], v[186:189], v[116:119]
	v_mfma_f32_16x16x32_bf16 v[112:115], v[166:169], v[186:189], v[112:115]
	v_mfma_f32_16x16x32_bf16 v[108:111], v[148:151], v[194:197], v[108:111]
	v_mfma_f32_16x16x32_bf16 v[104:107], v[166:169], v[194:197], v[104:107]
	v_mfma_f32_16x16x32_bf16 v[132:135], v[144:147], v[140:143], v[132:135]
	v_mfma_f32_16x16x32_bf16 v[128:131], v[162:165], v[140:143], v[128:131]
	v_mfma_f32_16x16x32_bf16 v[124:127], v[144:147], v[182:185], v[124:127]
	v_mfma_f32_16x16x32_bf16 v[120:123], v[162:165], v[182:185], v[120:123]
	v_mfma_f32_16x16x32_bf16 v[116:119], v[144:147], v[190:193], v[116:119]
	v_mfma_f32_16x16x32_bf16 v[112:115], v[162:165], v[190:193], v[112:115]
	v_mfma_f32_16x16x32_bf16 v[108:111], v[144:147], v[198:201], v[108:111]
	v_mfma_f32_16x16x32_bf16 v[104:107], v[162:165], v[198:201], v[104:107]
	v_mfma_f32_16x16x32_bf16 v[68:71], v[156:159], v[136:139], v[68:71]
	v_mfma_f32_16x16x32_bf16 v[64:67], v[174:177], v[136:139], v[64:67]
	v_mfma_f32_16x16x32_bf16 v[60:63], v[156:159], v[178:181], v[60:63]
	v_mfma_f32_16x16x32_bf16 v[56:59], v[174:177], v[178:181], v[56:59]
	v_mfma_f32_16x16x32_bf16 v[52:55], v[156:159], v[186:189], v[52:55]
	v_mfma_f32_16x16x32_bf16 v[48:51], v[174:177], v[186:189], v[48:51]
	v_mfma_f32_16x16x32_bf16 v[44:47], v[156:159], v[194:197], v[44:47]
	v_mfma_f32_16x16x32_bf16 v[40:43], v[174:177], v[194:197], v[40:43]
	v_mfma_f32_16x16x32_bf16 v[68:71], v[152:155], v[140:143], v[68:71]
	v_mfma_f32_16x16x32_bf16 v[64:67], v[170:173], v[140:143], v[64:67]
	v_mfma_f32_16x16x32_bf16 v[60:63], v[152:155], v[182:185], v[60:63]
	v_mfma_f32_16x16x32_bf16 v[56:59], v[170:173], v[182:185], v[56:59]
	v_mfma_f32_16x16x32_bf16 v[52:55], v[152:155], v[190:193], v[52:55]
	v_mfma_f32_16x16x32_bf16 v[48:51], v[170:173], v[190:193], v[48:51]
	v_mfma_f32_16x16x32_bf16 v[44:47], v[152:155], v[198:201], v[44:47]
	v_mfma_f32_16x16x32_bf16 v[40:43], v[170:173], v[198:201], v[40:43]
	s_barrier
; #define PG8_STAGE(bufoff, gbase, voff) do { _Pragma("unroll") for (int _i = 0; _i < 2; ++_i) \
;         __builtin_amdgcn_global_load_lds((const GAS unsigned*)((const GAS char*)(gbase) + (voff)[_i]), (PG8_LAS unsigned*)(lds + (bufoff) + ldsw + _i * 8192), 16, 0, 0); } while (0)
; #define PG8_LDA(dst, b, h) do { _Pragma("unroll") for (int m = 0; m < 4; ++m) _Pragma("unroll") for (int k = 0; k < 2; ++k) dst[m][k] = *(const PG8_LAS bf16x8*)(lds + PG8_SA(b, h) + aoff + m * 2048 + k * 1024); } while (0)
; #define PG8_MMA(ai, bj, At, Bt) do { __builtin_amdgcn_s_setprio(1); _Pragma("unroll") for (int m = 0; m < 4; ++m) _Pragma("unroll") for (int n = 0; n < 2; ++n) _Pragma("unroll") for (int k = 0; k < 2; ++k) \
;         acc[ai][bj][m][n] = __builtin_amdgcn_mfma_f32_16x16x32_bf16(Bt[n][k], At[m][k], acc[ai][bj][m][n], 0, 0, 0); __builtin_amdgcn_s_setprio(0); } while (0)
; #define PG8_WAIT_V(n) asm volatile("s_waitcnt vmcnt(" #n ")" ::: "memory")
; #define PG8_WAIT_L(n) asm volatile("s_waitcnt lgkmcnt(" #n ")" ::: "memory")
; #define PG8_BAR __builtin_amdgcn_s_barrier()
; #define PG8_SCHED __builtin_amdgcn_sched_barrier(0)
; #define PG8_STAGE(bufoff, gbase, voff) do { _Pragma("unroll") for (int _i = 0; _i < 2; ++_i) \
;         __builtin_amdgcn_global_load_lds((const GAS unsigned*)((const GAS char*)(gbase) + (voff)[_i]), (PG8_LAS unsigned*)(lds + (bufoff) + ldsw + _i * 8192), 16, 0, 0); } while (0)
; #define PG8_LDA(dst, b, h) do { _Pragma("unroll") for (int m = 0; m < 4; ++m) _Pragma("unroll") for (int k = 0; k < 2; ++k) dst[m][k] = *(const PG8_LAS bf16x8*)(lds + PG8_SA(b, h) + aoff + m * 2048 + k * 1024); } while (0)
; #define PG8_LDS_S(dst, boffs) do { dst[0] = *(const PG8_LAS bf16x8*)(slds + (boffs) + soff0); dst[1] = *(const PG8_LAS bf16x8*)(slds + (boffs) + (soff0 ^ 64)); } while (0)
; #define PG8_BAR __builtin_amdgcn_s_barrier()
; template <class Epi, class Sched>
; __device__ __forceinline__ void gemm_phase_strip(PG8_LAS unsigned char* lds, PG8_LAS unsigned char* slds, PG8_LAS unsigned char* pf, const Gemm g, const Sched& S, const Epi& E, int wv) {
;     ...
;             PG8_LDA(At, 0, 1); PG8_LDS_S(As, sq); PG8_STAGE(PG8_SB(0, 0), b2, voffB); PG8_STAGE(PG8_SB(0, 1), b2 + hstepB, voffB); PG8_STAGE(PG8_SA(0, 0), a2, voffA);
;             PG8_WAIT_V(8); PG8_WAIT_L(0); PG8_BAR; PG8_MMA(1, 0, At, B0); PG8_MMA(1, 1, At, B1); PG8_MMA_S(); PG8_BAR; PG8_SCHED;
	s_add_i32 s24, s74, 0
	s_add_i32 s24, s24, 0x21000
	v_add_u32_e32 v160, s24, v234
	v_add_u32_e32 v237, s24, v235
	s_add_i32 s24, s58, s64
	v_lshl_add_u64 v[222:223], s[52:53], 0, v[204:205]
	s_mov_b32 m0, s24
	ds_read_b128 v[136:139], v236 offset:16384
	ds_read_b128 v[140:143], v236 offset:17408
	ds_read_b128 v[186:189], v236 offset:18432
	ds_read_b128 v[190:193], v236 offset:19456
	ds_read_b128 v[194:197], v236 offset:20480
	ds_read_b128 v[198:201], v236 offset:21504
	ds_read_b128 v[242:245], v236 offset:22528
	ds_read_b128 v[246:249], v236 offset:23552
	ds_read_b128 v[182:185], v160
	ds_read_b128 v[178:181], v237
	global_load_lds_dwordx4 v[222:223], off
	s_add_i32 m0, s24, 0x2000
	s_add_u32 s24, s52, 0x160000
	v_lshl_add_u64 v[224:225], s[52:53], 0, v[208:209]
	s_addc_u32 s25, s53, 0
	s_add_i32 s40, s59, s64
	global_load_lds_dwordx4 v[224:225], off
	v_lshl_add_u64 v[226:227], s[24:25], 0, v[204:205]
	s_mov_b32 m0, s40
	v_lshl_add_u64 v[228:229], s[56:57], 0, v[206:207]
	global_load_lds_dwordx4 v[226:227], off
	v_lshl_add_u64 v[226:227], s[24:25], 0, v[208:209]
	s_add_i32 m0, s40, 0x2000
	s_nop 0
	global_load_lds_dwordx4 v[226:227], off
	v_lshl_add_u64 v[226:227], s[56:57], 0, v[202:203]
	s_mov_b32 m0, s66
	s_nop 0
	global_load_lds_dwordx4 v[226:227], off
	s_mov_b32 m0, s67
	s_nop 0
	global_load_lds_dwordx4 v[228:229], off
	s_waitcnt vmcnt(8)
	s_waitcnt lgkmcnt(0)
	s_barrier
	s_waitcnt lgkmcnt(0)
	v_mfma_f32_16x16x32_bf16 v[100:103], v[148:151], v[136:139], v[100:103]
	v_mfma_f32_16x16x32_bf16 v[96:99], v[166:169], v[136:139], v[96:99]
	v_mfma_f32_16x16x32_bf16 v[92:95], v[148:151], v[186:189], v[92:95]
	v_mfma_f32_16x16x32_bf16 v[88:91], v[166:169], v[186:189], v[88:91]
	v_mfma_f32_16x16x32_bf16 v[84:87], v[148:151], v[194:197], v[84:87]
	v_mfma_f32_16x16x32_bf16 v[80:83], v[166:169], v[194:197], v[80:83]
	v_mfma_f32_16x16x32_bf16 v[76:79], v[148:151], v[242:245], v[76:79]
	v_mfma_f32_16x16x32_bf16 v[72:75], v[166:169], v[242:245], v[72:75]
	v_mfma_f32_16x16x32_bf16 v[100:103], v[144:147], v[140:143], v[100:103]
	v_mfma_f32_16x16x32_bf16 v[96:99], v[162:165], v[140:143], v[96:99]
	v_mfma_f32_16x16x32_bf16 v[92:95], v[144:147], v[190:193], v[92:95]
	v_mfma_f32_16x16x32_bf16 v[88:91], v[162:165], v[190:193], v[88:91]
	v_mfma_f32_16x16x32_bf16 v[84:87], v[144:147], v[198:201], v[84:87]
	v_mfma_f32_16x16x32_bf16 v[80:83], v[162:165], v[198:201], v[80:83]
	v_mfma_f32_16x16x32_bf16 v[76:79], v[144:147], v[246:249], v[76:79]
	v_mfma_f32_16x16x32_bf16 v[72:75], v[162:165], v[246:249], v[72:75]
	v_mfma_f32_16x16x32_bf16 v[36:39], v[156:159], v[136:139], v[36:39]
	v_mfma_f32_16x16x32_bf16 v[32:35], v[174:177], v[136:139], v[32:35]
	v_mfma_f32_16x16x32_bf16 v[28:31], v[156:159], v[186:189], v[28:31]
	v_mfma_f32_16x16x32_bf16 v[24:27], v[174:177], v[186:189], v[24:27]
	v_mfma_f32_16x16x32_bf16 v[20:23], v[156:159], v[194:197], v[20:23]
	v_mfma_f32_16x16x32_bf16 v[16:19], v[174:177], v[194:197], v[16:19]
	v_mfma_f32_16x16x32_bf16 v[12:15], v[156:159], v[242:245], v[12:15]
	v_mfma_f32_16x16x32_bf16 v[8:11], v[174:177], v[242:245], v[8:11]
	v_mfma_f32_16x16x32_bf16 v[36:39], v[152:155], v[140:143], v[36:39]
	v_mfma_f32_16x16x32_bf16 v[32:35], v[170:173], v[140:143], v[32:35]
	v_mfma_f32_16x16x32_bf16 v[28:31], v[152:155], v[190:193], v[28:31]
	v_mfma_f32_16x16x32_bf16 v[24:27], v[170:173], v[190:193], v[24:27]
	v_mfma_f32_16x16x32_bf16 v[20:23], v[152:155], v[198:201], v[20:23]
	v_mfma_f32_16x16x32_bf16 v[16:19], v[170:173], v[198:201], v[16:19]
	v_mfma_f32_16x16x32_bf16 v[12:15], v[152:155], v[246:249], v[12:15]
	v_mfma_f32_16x16x32_bf16 v[8:11], v[170:173], v[246:249], v[8:11]
	v_cndmask_b32_e64 v136, 0, 1, s[30:31]
	v_cmp_ne_u32_e64 s[40:41], 1, v136
	s_andn2_b64 vcc, exec, s[30:31]
	s_mov_b64 s[58:59], -1
	s_cbranch_vccnz .LBB0_1563
	v_mfma_f32_16x16x32_bf16 v[136:139], v[166:169], v[182:185], v[4:7]
	s_mov_b64 s[58:59], 0
	v_mfma_f32_16x16x32_bf16 v[140:143], v[174:177], v[182:185], v[0:3]
	v_mfma_f32_16x16x32_bf16 v[136:139], v[162:165], v[178:181], v[136:139]
	v_mfma_f32_16x16x32_bf16 v[140:143], v[170:173], v[178:181], v[140:143]

; #define PG8_STAGE(bufoff, gbase, voff) do { _Pragma("unroll") for (int _i = 0; _i < 2; ++_i) \
;         __builtin_amdgcn_global_load_lds((const GAS unsigned*)((const GAS char*)(gbase) + (voff)[_i]), (PG8_LAS unsigned*)(lds + (bufoff) + ldsw + _i * 8192), 16, 0, 0); } while (0)
; #define PG8_LDA(dst, b, h) do { _Pragma("unroll") for (int m = 0; m < 4; ++m) _Pragma("unroll") for (int k = 0; k < 2; ++k) dst[m][k] = *(const PG8_LAS bf16x8*)(lds + PG8_SA(b, h) + aoff + m * 2048 + k * 1024); } while (0)
; #define PG8_LDB(dst, b, h) do { _Pragma("unroll") for (int n = 0; n < 2; ++n) _Pragma("unroll") for (int k = 0; k < 2; ++k) dst[n][k] = *(const PG8_LAS bf16x8*)(lds + PG8_SB(b, h) + boff + n * 2048 + k * 1024); } while (0)
; #define PG8_MMA(ai, bj, At, Bt) do { __builtin_amdgcn_s_setprio(1); _Pragma("unroll") for (int m = 0; m < 4; ++m) _Pragma("unroll") for (int n = 0; n < 2; ++n) _Pragma("unroll") for (int k = 0; k < 2; ++k) \
;         acc[ai][bj][m][n] = __builtin_amdgcn_mfma_f32_16x16x32_bf16(Bt[n][k], At[m][k], acc[ai][bj][m][n], 0, 0, 0); __builtin_amdgcn_s_setprio(0); } while (0)
; #define PG8_WAIT_V(n) asm volatile("s_waitcnt vmcnt(" #n ")" ::: "memory")
; #define PG8_WAIT_L(n) asm volatile("s_waitcnt lgkmcnt(" #n ")" ::: "memory")
; #define PG8_BAR __builtin_amdgcn_s_barrier()
; #define PG8_SCHED __builtin_amdgcn_sched_barrier(0)
; #define PG8_STAGE(bufoff, gbase, voff) do { _Pragma("unroll") for (int _i = 0; _i < 2; ++_i) \
;         __builtin_amdgcn_global_load_lds((const GAS unsigned*)((const GAS char*)(gbase) + (voff)[_i]), (PG8_LAS unsigned*)(lds + (bufoff) + ldsw + _i * 8192), 16, 0, 0); } while (0)
; #define PG8_WAIT_V(n) asm volatile("s_waitcnt vmcnt(" #n ")" ::: "memory")
; #define PG8_BAR __builtin_amdgcn_s_barrier()
; template <class Epi, class Sched>
; __device__ __forceinline__ void gemm_phase_strip(PG8_LAS unsigned char* lds, PG8_LAS unsigned char* slds, PG8_LAS unsigned char* pf, const Gemm g, const Sched& S, const Epi& E, int wv) {
;     ...
;             PG8_WAIT_V(8); PG8_WAIT_L(0); PG8_BAR; PG8_MMA(1, 0, At, B0); PG8_MMA(1, 1, At, B1); PG8_MMA_S(); PG8_BAR; PG8_SCHED;
;             PG8_LDB(B0, 1, 0); PG8_LDB(B1, 1, 1); PG8_SCHED; PG8_LDA(At, 1, 0); PG8_STAGE(PG8_SA(0, 1), a2 + (Sched::SPLIT ? ((last && has_next) ? (nxt.kh > 0 ? -(long)hstepA : (long)hstepA) : hsA) : (long)hstepA), voffA); PG8_STAGE_S(sq ^ 4096u, s2);
.LBB0_1565:
	s_barrier
	s_nop 3
	v_add_u32_e32 v0, 0, v233
	v_add_u32_e32 v1, 0x18000, v0
	v_add_u32_e32 v0, 0x1c000, v0
	ds_read_b128 v[148:151], v1
	ds_read_b128 v[144:147], v1 offset:1024
	ds_read_b128 v[166:169], v1 offset:2048
	ds_read_b128 v[162:165], v1 offset:3072
	ds_read_b128 v[156:159], v0
	ds_read_b128 v[152:155], v0 offset:1024
	ds_read_b128 v[174:177], v0 offset:2048
	ds_read_b128 v[170:173], v0 offset:3072
	s_add_u32 s24, s56, 0x160000
	s_addc_u32 s25, s57, 0
	s_mov_b32 m0, s68
	v_lshl_add_u64 v[242:243], s[24:25], 0, v[202:203]
	ds_read_b128 v[194:197], v236 offset:32768
	ds_read_b128 v[198:201], v236 offset:33792
	ds_read_b128 v[186:189], v236 offset:34816
	ds_read_b128 v[190:193], v236 offset:35840
	ds_read_b128 v[178:181], v236 offset:36864
	ds_read_b128 v[182:185], v236 offset:37888
	ds_read_b128 v[0:3], v236 offset:38912
	ds_read_b128 v[4:7], v236 offset:39936
	global_load_lds_dwordx4 v[242:243], off
	v_lshl_add_u64 v[242:243], s[24:25], 0, v[206:207]
	s_mov_b32 m0, s69
	s_nop 0
	global_load_lds_dwordx4 v[242:243], off
	v_mov_b32_e32 v242, v230
	s_and_saveexec_b64 s[56:57], s[36:37]
	s_cbranch_execz .LBB0_1567
	s_add_u32 s58, s9, s14
	s_addc_u32 s59, s20, s15
	s_and_b64 s[24:25], s[54:55], exec
	s_cselect_b32 s25, s51, s59
	s_cselect_b32 s24, s50, s58
	s_xor_b32 s54, s74, 0x1000
	s_add_i32 m0, s90, s54
	s_nop 0
	global_load_lds_dwordx4 v242, s[24:25]
; #define PG8_STAGE(bufoff, gbase, voff) do { _Pragma("unroll") for (int _i = 0; _i < 2; ++_i) \
;         __builtin_amdgcn_global_load_lds((const GAS unsigned*)((const GAS char*)(gbase) + (voff)[_i]), (PG8_LAS unsigned*)(lds + (bufoff) + ldsw + _i * 8192), 16, 0, 0); } while (0)
; #define PG8_LDA(dst, b, h) do { _Pragma("unroll") for (int m = 0; m < 4; ++m) _Pragma("unroll") for (int k = 0; k < 2; ++k) dst[m][k] = *(const PG8_LAS bf16x8*)(lds + PG8_SA(b, h) + aoff + m * 2048 + k * 1024); } while (0)
; #define PG8_MMA(ai, bj, At, Bt) do { __builtin_amdgcn_s_setprio(1); _Pragma("unroll") for (int m = 0; m < 4; ++m) _Pragma("unroll") for (int n = 0; n < 2; ++n) _Pragma("unroll") for (int k = 0; k < 2; ++k) \
;         acc[ai][bj][m][n] = __builtin_amdgcn_mfma_f32_16x16x32_bf16(Bt[n][k], At[m][k], acc[ai][bj][m][n], 0, 0, 0); __builtin_amdgcn_s_setprio(0); } while (0)
; #define PG8_WAIT_V(n) asm volatile("s_waitcnt vmcnt(" #n ")" ::: "memory")
; #define PG8_WAIT_L(n) asm volatile("s_waitcnt lgkmcnt(" #n ")" ::: "memory")
; #define PG8_BAR __builtin_amdgcn_s_barrier()
; #define PG8_SCHED __builtin_amdgcn_sched_barrier(0)
; #define PG8_STAGE(bufoff, gbase, voff) do { _Pragma("unroll") for (int _i = 0; _i < 2; ++_i) \
;         __builtin_amdgcn_global_load_lds((const GAS unsigned*)((const GAS char*)(gbase) + (voff)[_i]), (PG8_LAS unsigned*)(lds + (bufoff) + ldsw + _i * 8192), 16, 0, 0); } while (0)
; #define PG8_LDA(dst, b, h) do { _Pragma("unroll") for (int m = 0; m < 4; ++m) _Pragma("unroll") for (int k = 0; k < 2; ++k) dst[m][k] = *(const PG8_LAS bf16x8*)(lds + PG8_SA(b, h) + aoff + m * 2048 + k * 1024); } while (0)
; #define PG8_WAIT_V(n) asm volatile("s_waitcnt vmcnt(" #n ")" ::: "memory")
; template <class Epi, class Sched>
; __device__ __forceinline__ void gemm_phase_strip(PG8_LAS unsigned char* lds, PG8_LAS unsigned char* slds, PG8_LAS unsigned char* pf, const Gemm g, const Sched& S, const Epi& E, int wv) {
;     ...
;             PG8_WAIT_V(9); PG8_WAIT_L(0); PG8_BAR; PG8_MMA(0, 0, At, B0); PG8_MMA(0, 1, At, B1); PG8_BAR; PG8_SCHED;
;             PG8_LDA(At, 1, 1); PG8_LDS_S(As, sq + 2048u); PG8_STAGE(PG8_SB(1, 0), b3, voffB); PG8_STAGE(PG8_SB(1, 1), b3 + hstepB, voffB); PG8_STAGE(PG8_SA(1, 0), a3, voffA);
;             PG8_WAIT_V(9); PG8_WAIT_L(0); PG8_BAR; PG8_MMA(1, 0, At, B0); PG8_MMA(1, 1, At, B1); PG8_MMA_S(); PG8_BAR; PG8_SCHED;
.LBB0_1567:
	s_or_b64 exec, exec, s[56:57]
	s_waitcnt vmcnt(9)
	s_waitcnt lgkmcnt(0)
	s_barrier
	s_waitcnt lgkmcnt(0)
	v_mfma_f32_16x16x32_bf16 v[132:135], v[148:151], v[194:197], v[132:135]
	v_mfma_f32_16x16x32_bf16 v[128:131], v[166:169], v[194:197], v[128:131]
	v_mfma_f32_16x16x32_bf16 v[124:127], v[148:151], v[186:189], v[124:127]
	v_mfma_f32_16x16x32_bf16 v[120:123], v[166:169], v[186:189], v[120:123]
	v_mfma_f32_16x16x32_bf16 v[116:119], v[148:151], v[178:181], v[116:119]
	v_mfma_f32_16x16x32_bf16 v[112:115], v[166:169], v[178:181], v[112:115]
	v_mfma_f32_16x16x32_bf16 v[108:111], v[148:151], v[0:3], v[108:111]
	v_mfma_f32_16x16x32_bf16 v[104:107], v[166:169], v[0:3], v[104:107]
	v_mfma_f32_16x16x32_bf16 v[132:135], v[144:147], v[198:201], v[132:135]
	v_mfma_f32_16x16x32_bf16 v[128:131], v[162:165], v[198:201], v[128:131]
	v_mfma_f32_16x16x32_bf16 v[124:127], v[144:147], v[190:193], v[124:127]
	v_mfma_f32_16x16x32_bf16 v[120:123], v[162:165], v[190:193], v[120:123]
	v_mfma_f32_16x16x32_bf16 v[116:119], v[144:147], v[182:185], v[116:119]
	v_mfma_f32_16x16x32_bf16 v[112:115], v[162:165], v[182:185], v[112:115]
	v_mfma_f32_16x16x32_bf16 v[108:111], v[144:147], v[4:7], v[108:111]
	v_mfma_f32_16x16x32_bf16 v[104:107], v[162:165], v[4:7], v[104:107]
	v_mfma_f32_16x16x32_bf16 v[68:71], v[156:159], v[194:197], v[68:71]
	v_mfma_f32_16x16x32_bf16 v[64:67], v[174:177], v[194:197], v[64:67]
	v_mfma_f32_16x16x32_bf16 v[60:63], v[156:159], v[186:189], v[60:63]
	v_mfma_f32_16x16x32_bf16 v[56:59], v[174:177], v[186:189], v[56:59]
	v_mfma_f32_16x16x32_bf16 v[52:55], v[156:159], v[178:181], v[52:55]
	v_mfma_f32_16x16x32_bf16 v[48:51], v[174:177], v[178:181], v[48:51]
	v_mfma_f32_16x16x32_bf16 v[44:47], v[156:159], v[0:3], v[44:47]
	v_mfma_f32_16x16x32_bf16 v[0:3], v[174:177], v[0:3], v[40:43]
	v_mfma_f32_16x16x32_bf16 v[68:71], v[152:155], v[198:201], v[68:71]
	v_mfma_f32_16x16x32_bf16 v[64:67], v[170:173], v[198:201], v[64:67]
	v_mfma_f32_16x16x32_bf16 v[60:63], v[152:155], v[190:193], v[60:63]
	v_mfma_f32_16x16x32_bf16 v[56:59], v[170:173], v[190:193], v[56:59]
	v_mfma_f32_16x16x32_bf16 v[52:55], v[152:155], v[182:185], v[52:55]
	v_mfma_f32_16x16x32_bf16 v[48:51], v[170:173], v[182:185], v[48:51]
	v_mfma_f32_16x16x32_bf16 v[44:47], v[152:155], v[4:7], v[44:47]
	v_mfma_f32_16x16x32_bf16 v[40:43], v[170:173], v[4:7], v[0:3]
	s_barrier
	s_mov_b32 m0, s84
	v_lshl_add_u64 v[222:223], v[222:223], 0, s[16:17]
	s_add_u32 s24, s52, 0x160080
	ds_read_b128 v[0:3], v236 offset:49152
	ds_read_b128 v[4:7], v236 offset:50176
	ds_read_b128 v[186:189], v236 offset:51200
	ds_read_b128 v[190:193], v236 offset:52224
	ds_read_b128 v[194:197], v236 offset:53248
	ds_read_b128 v[198:201], v236 offset:54272
	ds_read_b128 v[242:245], v236 offset:55296
	ds_read_b128 v[246:249], v236 offset:56320
	ds_read_b128 v[182:185], v160 offset:2048
	ds_read_b128 v[178:181], v237 offset:2048
	global_load_lds_dwordx4 v[222:223], off
	v_lshl_add_u64 v[222:223], v[224:225], 0, s[16:17]
	s_mov_b32 m0, s85
	s_addc_u32 s25, s53, 0
	global_load_lds_dwordx4 v[222:223], off
	v_lshl_add_u64 v[222:223], s[24:25], 0, v[204:205]
	s_mov_b32 m0, s88
	s_nop 0
	global_load_lds_dwordx4 v[222:223], off
	v_lshl_add_u64 v[222:223], s[24:25], 0, v[208:209]
	s_mov_b32 m0, s89
	s_nop 0
	global_load_lds_dwordx4 v[222:223], off
	v_lshl_add_u64 v[222:223], v[226:227], 0, s[16:17]
	s_mov_b32 m0, s86
	s_nop 0
	global_load_lds_dwordx4 v[222:223], off
	v_lshl_add_u64 v[222:223], v[228:229], 0, s[16:17]
	s_mov_b32 m0, s87
	s_nop 0
	global_load_lds_dwordx4 v[222:223], off
	s_waitcnt vmcnt(9)
	s_waitcnt lgkmcnt(0)
	s_barrier
	s_waitcnt lgkmcnt(0)
	v_mfma_f32_16x16x32_bf16 v[100:103], v[148:151], v[0:3], v[100:103]
	v_mfma_f32_16x16x32_bf16 v[96:99], v[166:169], v[0:3], v[96:99]
	v_mfma_f32_16x16x32_bf16 v[92:95], v[148:151], v[186:189], v[92:95]
	v_mfma_f32_16x16x32_bf16 v[88:91], v[166:169], v[186:189], v[88:91]
	v_mfma_f32_16x16x32_bf16 v[84:87], v[148:151], v[194:197], v[84:87]
	v_mfma_f32_16x16x32_bf16 v[80:83], v[166:169], v[194:197], v[80:83]
	v_mfma_f32_16x16x32_bf16 v[76:79], v[148:151], v[242:245], v[76:79]
	v_mfma_f32_16x16x32_bf16 v[72:75], v[166:169], v[242:245], v[72:75]
	v_mfma_f32_16x16x32_bf16 v[100:103], v[144:147], v[4:7], v[100:103]
	v_mfma_f32_16x16x32_bf16 v[96:99], v[162:165], v[4:7], v[96:99]
	v_mfma_f32_16x16x32_bf16 v[92:95], v[144:147], v[190:193], v[92:95]
	v_mfma_f32_16x16x32_bf16 v[88:91], v[162:165], v[190:193], v[88:91]
	v_mfma_f32_16x16x32_bf16 v[84:87], v[144:147], v[198:201], v[84:87]
	v_mfma_f32_16x16x32_bf16 v[80:83], v[162:165], v[198:201], v[80:83]
	v_mfma_f32_16x16x32_bf16 v[76:79], v[144:147], v[246:249], v[76:79]
	v_mfma_f32_16x16x32_bf16 v[72:75], v[162:165], v[246:249], v[72:75]
	v_mfma_f32_16x16x32_bf16 v[36:39], v[156:159], v[0:3], v[36:39]
	v_mfma_f32_16x16x32_bf16 v[0:3], v[174:177], v[0:3], v[32:35]
	v_mfma_f32_16x16x32_bf16 v[32:35], v[170:173], v[4:7], v[0:3]
	v_mfma_f32_16x16x32_bf16 v[0:3], v[156:159], v[186:189], v[28:31]
	v_mfma_f32_16x16x32_bf16 v[28:31], v[152:155], v[190:193], v[0:3]
	v_mfma_f32_16x16x32_bf16 v[0:3], v[174:177], v[186:189], v[24:27]
	v_mfma_f32_16x16x32_bf16 v[24:27], v[170:173], v[190:193], v[0:3]
	v_mfma_f32_16x16x32_bf16 v[0:3], v[156:159], v[194:197], v[20:23]
	v_mfma_f32_16x16x32_bf16 v[20:23], v[152:155], v[198:201], v[0:3]
	v_mfma_f32_16x16x32_bf16 v[0:3], v[174:177], v[194:197], v[16:19]
	v_mfma_f32_16x16x32_bf16 v[16:19], v[170:173], v[198:201], v[0:3]
	v_mfma_f32_16x16x32_bf16 v[0:3], v[156:159], v[242:245], v[12:15]
	v_mfma_f32_16x16x32_bf16 v[12:15], v[152:155], v[246:249], v[0:3]
	v_mfma_f32_16x16x32_bf16 v[0:3], v[174:177], v[242:245], v[8:11]
	v_mfma_f32_16x16x32_bf16 v[36:39], v[152:155], v[4:7], v[36:39]
	v_mfma_f32_16x16x32_bf16 v[8:11], v[170:173], v[246:249], v[0:3]
	s_and_b64 vcc, exec, s[40:41]
	s_mov_b64 s[40:41], -1
	s_cbranch_vccnz .LBB0_1569
	v_mfma_f32_16x16x32_bf16 v[0:3], v[166:169], v[182:185], v[136:139]
	s_mov_b64 s[40:41], 0
	v_mfma_f32_16x16x32_bf16 v[166:169], v[174:177], v[182:185], v[140:143]
	v_mfma_f32_16x16x32_bf16 v[4:7], v[162:165], v[178:181], v[0:3]
	v_mfma_f32_16x16x32_bf16 v[0:3], v[170:173], v[178:181], v[166:169]

; #define PG8_STAGE(bufoff, gbase, voff) do { _Pragma("unroll") for (int _i = 0; _i < 2; ++_i) \
;         __builtin_amdgcn_global_load_lds((const GAS unsigned*)((const GAS char*)(gbase) + (voff)[_i]), (PG8_LAS unsigned*)(lds + (bufoff) + ldsw + _i * 8192), 16, 0, 0); } while (0)
; #define PG8_LDA(dst, b, h) do { _Pragma("unroll") for (int m = 0; m < 4; ++m) _Pragma("unroll") for (int k = 0; k < 2; ++k) dst[m][k] = *(const PG8_LAS bf16x8*)(lds + PG8_SA(b, h) + aoff + m * 2048 + k * 1024); } while (0)
; #define PG8_LDB(dst, b, h) do { _Pragma("unroll") for (int n = 0; n < 2; ++n) _Pragma("unroll") for (int k = 0; k < 2; ++k) dst[n][k] = *(const PG8_LAS bf16x8*)(lds + PG8_SB(b, h) + boff + n * 2048 + k * 1024); } while (0)
; #define PG8_MMA(ai, bj, At, Bt) do { __builtin_amdgcn_s_setprio(1); _Pragma("unroll") for (int m = 0; m < 4; ++m) _Pragma("unroll") for (int n = 0; n < 2; ++n) _Pragma("unroll") for (int k = 0; k < 2; ++k) \
;         acc[ai][bj][m][n] = __builtin_amdgcn_mfma_f32_16x16x32_bf16(Bt[n][k], At[m][k], acc[ai][bj][m][n], 0, 0, 0); __builtin_amdgcn_s_setprio(0); } while (0)
; #define PG8_WAIT_V(n) asm volatile("s_waitcnt vmcnt(" #n ")" ::: "memory")
; #define PG8_WAIT_L(n) asm volatile("s_waitcnt lgkmcnt(" #n ")" ::: "memory")
; #define PG8_BAR __builtin_amdgcn_s_barrier()
; #define PG8_SCHED __builtin_amdgcn_sched_barrier(0)
; #define PG8_STAGE(bufoff, gbase, voff) do { _Pragma("unroll") for (int _i = 0; _i < 2; ++_i) \
;         __builtin_amdgcn_global_load_lds((const GAS unsigned*)((const GAS char*)(gbase) + (voff)[_i]), (PG8_LAS unsigned*)(lds + (bufoff) + ldsw + _i * 8192), 16, 0, 0); } while (0)
; #define PG8_WAIT_V(n) asm volatile("s_waitcnt vmcnt(" #n ")" ::: "memory")
; template <class Epi, class Sched, bool ALIGN_EPI = false, bool SP2 = false>
; __device__ __forceinline__ void gemm_phase(PG8_LAS unsigned char* lds, PG8_LAS unsigned char* pf, const Gemm g, const Sched& S, const Epi& E, int wv) {
;     ...
;             PG8_LDB(B0, 0, 0); PG8_LDB(B1, 0, 1); PG8_SCHED; PG8_LDA(At, 0, 0); PG8_STAGE(PG8_SA(1, 1), a1 + (Sched::SPLIT ? hsA : (long)hstepA), voffA);
;             PG8_WAIT_V(8); PG8_WAIT_L(0); PG8_BAR; PG8_MMA(0, 0, At, B0); PG8_MMA(0, 1, At, B1); PG8_BAR; PG8_SCHED;
;             PG8_LDA(At, 0, 1); PG8_STAGE(PG8_SB(0, 0), b2, voffB); PG8_STAGE(PG8_SB(0, 1), b2 + hstepB, voffB); PG8_STAGE(PG8_SA(0, 0), a2, voffA);
.LBB0_1725:
	s_add_u32 s12, s10, 0x100
	s_addc_u32 s13, s11, 0
	s_add_i32 s23, 0, 0x10000
	s_cmpk_eq_i32 s22, 0x54
	s_cselect_b32 s29, s5, s13
	s_cselect_b32 s28, s4, s12
	s_cselect_b32 s15, s7, s21
	s_cselect_b32 s14, s6, s20
	s_add_i32 s24, 0, 0x14000
	v_add_u32_e32 v140, s23, v170
	v_add_u32_e32 v172, s24, v170
	ds_read_b128 v[128:131], v140
	ds_read_b128 v[132:135], v140 offset:1024
	ds_read_b128 v[136:139], v140 offset:2048
	ds_read_b128 v[140:143], v140 offset:3072
	ds_read_b128 v[144:147], v172
	ds_read_b128 v[148:151], v172 offset:1024
	ds_read_b128 v[152:155], v172 offset:2048
	ds_read_b128 v[172:175], v172 offset:3072
	v_lshl_add_u64 v[208:209], s[10:11], 0, v[166:167]
	s_add_i32 m0, s27, 0xc000
	ds_read_b128 v[176:179], v171
	ds_read_b128 v[180:183], v171 offset:1024
	ds_read_b128 v[184:187], v171 offset:2048
	ds_read_b128 v[188:191], v171 offset:3072
	ds_read_b128 v[192:195], v171 offset:4096
	ds_read_b128 v[196:199], v171 offset:5120
	ds_read_b128 v[200:203], v171 offset:6144
	ds_read_b128 v[204:207], v171 offset:7168
	global_load_lds_dwordx4 v[208:209], off
	v_lshl_add_u64 v[208:209], s[10:11], 0, v[164:165]
	s_add_i32 m0, s27, 0xe000
	s_nop 0
	global_load_lds_dwordx4 v[208:209], off
	s_waitcnt vmcnt(8)
	s_waitcnt lgkmcnt(0)
	s_barrier
	s_waitcnt lgkmcnt(0)
	v_mfma_f32_16x16x32_bf16 v[124:127], v[128:131], v[176:179], v[124:127]
	v_mfma_f32_16x16x32_bf16 v[120:123], v[136:139], v[176:179], v[120:123]
	v_mfma_f32_16x16x32_bf16 v[116:119], v[128:131], v[184:187], v[116:119]
	v_mfma_f32_16x16x32_bf16 v[112:115], v[136:139], v[184:187], v[112:115]
	v_mfma_f32_16x16x32_bf16 v[108:111], v[128:131], v[192:195], v[108:111]
	v_mfma_f32_16x16x32_bf16 v[104:107], v[136:139], v[192:195], v[104:107]
	v_mfma_f32_16x16x32_bf16 v[100:103], v[128:131], v[200:203], v[100:103]
	v_mfma_f32_16x16x32_bf16 v[96:99], v[136:139], v[200:203], v[96:99]
	v_mfma_f32_16x16x32_bf16 v[124:127], v[132:135], v[180:183], v[124:127]
	v_mfma_f32_16x16x32_bf16 v[120:123], v[140:143], v[180:183], v[120:123]
	v_mfma_f32_16x16x32_bf16 v[116:119], v[132:135], v[188:191], v[116:119]
	v_mfma_f32_16x16x32_bf16 v[112:115], v[140:143], v[188:191], v[112:115]
	v_mfma_f32_16x16x32_bf16 v[108:111], v[132:135], v[196:199], v[108:111]
	v_mfma_f32_16x16x32_bf16 v[104:107], v[140:143], v[196:199], v[104:107]
	v_mfma_f32_16x16x32_bf16 v[100:103], v[132:135], v[204:207], v[100:103]
	v_mfma_f32_16x16x32_bf16 v[96:99], v[140:143], v[204:207], v[96:99]
	v_mfma_f32_16x16x32_bf16 v[60:63], v[144:147], v[176:179], v[60:63]
	v_mfma_f32_16x16x32_bf16 v[56:59], v[152:155], v[176:179], v[56:59]
	v_mfma_f32_16x16x32_bf16 v[52:55], v[144:147], v[184:187], v[52:55]
	v_mfma_f32_16x16x32_bf16 v[48:51], v[152:155], v[184:187], v[48:51]
	v_mfma_f32_16x16x32_bf16 v[44:47], v[144:147], v[192:195], v[44:47]
	v_mfma_f32_16x16x32_bf16 v[40:43], v[152:155], v[192:195], v[40:43]
	v_mfma_f32_16x16x32_bf16 v[36:39], v[144:147], v[200:203], v[36:39]
	v_mfma_f32_16x16x32_bf16 v[32:35], v[152:155], v[200:203], v[32:35]
	v_mfma_f32_16x16x32_bf16 v[60:63], v[148:151], v[180:183], v[60:63]
	v_mfma_f32_16x16x32_bf16 v[56:59], v[172:175], v[180:183], v[56:59]
	v_mfma_f32_16x16x32_bf16 v[52:55], v[148:151], v[188:191], v[52:55]
	v_mfma_f32_16x16x32_bf16 v[48:51], v[172:175], v[188:191], v[48:51]
	v_mfma_f32_16x16x32_bf16 v[44:47], v[148:151], v[196:199], v[44:47]
	v_mfma_f32_16x16x32_bf16 v[40:43], v[172:175], v[196:199], v[40:43]
	v_mfma_f32_16x16x32_bf16 v[36:39], v[148:151], v[204:207], v[36:39]
	v_mfma_f32_16x16x32_bf16 v[32:35], v[172:175], v[204:207], v[32:35]
	s_barrier
	s_add_i32 s10, s23, s19
	v_lshl_add_u64 v[208:209], s[14:15], 0, v[160:161]
	s_mov_b32 m0, s10
	ds_read_b128 v[176:179], v171 offset:16384
	ds_read_b128 v[180:183], v171 offset:17408
	ds_read_b128 v[184:187], v171 offset:18432
	ds_read_b128 v[188:191], v171 offset:19456
	ds_read_b128 v[192:195], v171 offset:20480
	ds_read_b128 v[196:199], v171 offset:21504
	ds_read_b128 v[200:203], v171 offset:22528
	ds_read_b128 v[204:207], v171 offset:23552
	global_load_lds_dwordx4 v[208:209], off
	s_add_i32 m0, s10, 0x2000
	s_add_u32 s10, s14, 0x160000
	v_lshl_add_u64 v[214:215], s[14:15], 0, v[162:163]
	s_addc_u32 s11, s15, 0
	s_add_i32 s23, s24, s19
	global_load_lds_dwordx4 v[214:215], off
	v_lshl_add_u64 v[216:217], s[10:11], 0, v[160:161]
	s_mov_b32 m0, s23
	v_lshl_add_u64 v[218:219], s[28:29], 0, v[158:159]
	global_load_lds_dwordx4 v[216:217], off
	v_lshl_add_u64 v[216:217], s[10:11], 0, v[162:163]
	s_add_i32 m0, s23, 0x2000
	s_nop 0
	global_load_lds_dwordx4 v[216:217], off
	v_lshl_add_u64 v[216:217], s[28:29], 0, v[156:157]
	s_mov_b32 m0, s27
	s_nop 0
	global_load_lds_dwordx4 v[216:217], off
	s_mov_b32 m0, s30
	s_nop 0
	global_load_lds_dwordx4 v[218:219], off
	s_waitcnt vmcnt(8)
	s_waitcnt lgkmcnt(0)
	s_barrier
; #define PG8_STAGE(bufoff, gbase, voff) do { _Pragma("unroll") for (int _i = 0; _i < 2; ++_i) \
;         __builtin_amdgcn_global_load_lds((const GAS unsigned*)((const GAS char*)(gbase) + (voff)[_i]), (PG8_LAS unsigned*)(lds + (bufoff) + ldsw + _i * 8192), 16, 0, 0); } while (0)
; #define PG8_LDA(dst, b, h) do { _Pragma("unroll") for (int m = 0; m < 4; ++m) _Pragma("unroll") for (int k = 0; k < 2; ++k) dst[m][k] = *(const PG8_LAS bf16x8*)(lds + PG8_SA(b, h) + aoff + m * 2048 + k * 1024); } while (0)
; #define PG8_LDB(dst, b, h) do { _Pragma("unroll") for (int n = 0; n < 2; ++n) _Pragma("unroll") for (int k = 0; k < 2; ++k) dst[n][k] = *(const PG8_LAS bf16x8*)(lds + PG8_SB(b, h) + boff + n * 2048 + k * 1024); } while (0)
; #define PG8_MMA(ai, bj, At, Bt) do { __builtin_amdgcn_s_setprio(1); _Pragma("unroll") for (int m = 0; m < 4; ++m) _Pragma("unroll") for (int n = 0; n < 2; ++n) _Pragma("unroll") for (int k = 0; k < 2; ++k) \
;         acc[ai][bj][m][n] = __builtin_amdgcn_mfma_f32_16x16x32_bf16(Bt[n][k], At[m][k], acc[ai][bj][m][n], 0, 0, 0); __builtin_amdgcn_s_setprio(0); } while (0)
; #define PG8_WAIT_V(n) asm volatile("s_waitcnt vmcnt(" #n ")" ::: "memory")
; #define PG8_WAIT_L(n) asm volatile("s_waitcnt lgkmcnt(" #n ")" ::: "memory")
; #define PG8_BAR __builtin_amdgcn_s_barrier()
; #define PG8_SCHED __builtin_amdgcn_sched_barrier(0)
; #define PG8_STAGE(bufoff, gbase, voff) do { _Pragma("unroll") for (int _i = 0; _i < 2; ++_i) \
;         __builtin_amdgcn_global_load_lds((const GAS unsigned*)((const GAS char*)(gbase) + (voff)[_i]), (PG8_LAS unsigned*)(lds + (bufoff) + ldsw + _i * 8192), 16, 0, 0); } while (0)
; #define PG8_BAR __builtin_amdgcn_s_barrier()
; template <class Epi, class Sched, bool ALIGN_EPI = false, bool SP2 = false>
; __device__ __forceinline__ void gemm_phase(PG8_LAS unsigned char* lds, PG8_LAS unsigned char* pf, const Gemm g, const Sched& S, const Epi& E, int wv) {
;     ...
;             PG8_WAIT_V(8); PG8_WAIT_L(0); PG8_BAR; PG8_MMA(1, 0, At, B0); PG8_MMA(1, 1, At, B1); PG8_BAR; PG8_SCHED;
;             PG8_LDB(B0, 1, 0); PG8_LDB(B1, 1, 1); PG8_SCHED; PG8_LDA(At, 1, 0); PG8_STAGE(PG8_SA(0, 1), a2 + (Sched::SPLIT ? ((last && has_next) ? (nxt.kh > 0 ? -(long)hstepA : (long)hstepA) : hsA) : (long)hstepA), voffA);
;             PG8_WAIT_V(8); PG8_WAIT_L(0); PG8_BAR; PG8_MMA(0, 0, At, B0); PG8_MMA(0, 1, At, B1); PG8_BAR; PG8_SCHED;
	s_waitcnt lgkmcnt(0)
	v_mfma_f32_16x16x32_bf16 v[92:95], v[128:131], v[176:179], v[92:95]
	v_mfma_f32_16x16x32_bf16 v[88:91], v[136:139], v[176:179], v[88:91]
	v_mfma_f32_16x16x32_bf16 v[84:87], v[128:131], v[184:187], v[84:87]
	v_mfma_f32_16x16x32_bf16 v[80:83], v[136:139], v[184:187], v[80:83]
	v_mfma_f32_16x16x32_bf16 v[76:79], v[128:131], v[192:195], v[76:79]
	v_mfma_f32_16x16x32_bf16 v[72:75], v[136:139], v[192:195], v[72:75]
	v_mfma_f32_16x16x32_bf16 v[68:71], v[128:131], v[200:203], v[68:71]
	v_mfma_f32_16x16x32_bf16 v[64:67], v[136:139], v[200:203], v[64:67]
	v_mfma_f32_16x16x32_bf16 v[92:95], v[132:135], v[180:183], v[92:95]
	v_mfma_f32_16x16x32_bf16 v[88:91], v[140:143], v[180:183], v[88:91]
	v_mfma_f32_16x16x32_bf16 v[84:87], v[132:135], v[188:191], v[84:87]
	v_mfma_f32_16x16x32_bf16 v[80:83], v[140:143], v[188:191], v[80:83]
	v_mfma_f32_16x16x32_bf16 v[76:79], v[132:135], v[196:199], v[76:79]
	v_mfma_f32_16x16x32_bf16 v[72:75], v[140:143], v[196:199], v[72:75]
	v_mfma_f32_16x16x32_bf16 v[68:71], v[132:135], v[204:207], v[68:71]
	v_mfma_f32_16x16x32_bf16 v[64:67], v[140:143], v[204:207], v[64:67]
	v_mfma_f32_16x16x32_bf16 v[28:31], v[144:147], v[176:179], v[28:31]
	v_mfma_f32_16x16x32_bf16 v[24:27], v[152:155], v[176:179], v[24:27]
	v_mfma_f32_16x16x32_bf16 v[20:23], v[144:147], v[184:187], v[20:23]
	v_mfma_f32_16x16x32_bf16 v[16:19], v[152:155], v[184:187], v[16:19]
	v_mfma_f32_16x16x32_bf16 v[12:15], v[144:147], v[192:195], v[12:15]
	v_mfma_f32_16x16x32_bf16 v[8:11], v[152:155], v[192:195], v[8:11]
	v_mfma_f32_16x16x32_bf16 v[4:7], v[144:147], v[200:203], v[4:7]
	v_mfma_f32_16x16x32_bf16 v[0:3], v[152:155], v[200:203], v[0:3]
	v_mfma_f32_16x16x32_bf16 v[28:31], v[148:151], v[180:183], v[28:31]
	v_mfma_f32_16x16x32_bf16 v[24:27], v[172:175], v[180:183], v[24:27]
	v_mfma_f32_16x16x32_bf16 v[20:23], v[148:151], v[188:191], v[20:23]
	v_mfma_f32_16x16x32_bf16 v[16:19], v[172:175], v[188:191], v[16:19]
	v_mfma_f32_16x16x32_bf16 v[12:15], v[148:151], v[196:199], v[12:15]
	v_mfma_f32_16x16x32_bf16 v[8:11], v[172:175], v[196:199], v[8:11]
	v_mfma_f32_16x16x32_bf16 v[4:7], v[148:151], v[204:207], v[4:7]
	v_mfma_f32_16x16x32_bf16 v[0:3], v[172:175], v[204:207], v[0:3]
	s_barrier
	s_add_i32 s23, 0, 0x18000
	s_add_i32 s24, 0, 0x1c000
	v_add_u32_e32 v140, s23, v170
	v_add_u32_e32 v172, s24, v170
	ds_read_b128 v[128:131], v140
	ds_read_b128 v[132:135], v140 offset:1024
	ds_read_b128 v[136:139], v140 offset:2048
	ds_read_b128 v[140:143], v140 offset:3072
	ds_read_b128 v[144:147], v172
	ds_read_b128 v[148:151], v172 offset:1024
	ds_read_b128 v[152:155], v172 offset:2048
	ds_read_b128 v[172:175], v172 offset:3072
	s_add_u32 s10, s28, 0x160000
	s_addc_u32 s11, s29, 0
	s_mov_b32 m0, s31
	v_lshl_add_u64 v[220:221], s[10:11], 0, v[156:157]
	ds_read_b128 v[176:179], v171 offset:32768
	ds_read_b128 v[180:183], v171 offset:33792
	ds_read_b128 v[184:187], v171 offset:34816
	ds_read_b128 v[188:191], v171 offset:35840
	ds_read_b128 v[192:195], v171 offset:36864
	ds_read_b128 v[196:199], v171 offset:37888
	ds_read_b128 v[200:203], v171 offset:38912
	ds_read_b128 v[204:207], v171 offset:39936
	global_load_lds_dwordx4 v[220:221], off
	v_lshl_add_u64 v[220:221], s[10:11], 0, v[158:159]
	s_mov_b32 m0, s38
	s_nop 0
	global_load_lds_dwordx4 v[220:221], off
	s_waitcnt vmcnt(8)
	s_waitcnt lgkmcnt(0)
	s_barrier
	s_waitcnt lgkmcnt(0)
	v_mfma_f32_16x16x32_bf16 v[124:127], v[128:131], v[176:179], v[124:127]
	v_mfma_f32_16x16x32_bf16 v[120:123], v[136:139], v[176:179], v[120:123]
	v_mfma_f32_16x16x32_bf16 v[116:119], v[128:131], v[184:187], v[116:119]
	v_mfma_f32_16x16x32_bf16 v[112:115], v[136:139], v[184:187], v[112:115]
	v_mfma_f32_16x16x32_bf16 v[108:111], v[128:131], v[192:195], v[108:111]
	v_mfma_f32_16x16x32_bf16 v[104:107], v[136:139], v[192:195], v[104:107]
	v_mfma_f32_16x16x32_bf16 v[100:103], v[128:131], v[200:203], v[100:103]
	v_mfma_f32_16x16x32_bf16 v[96:99], v[136:139], v[200:203], v[96:99]
	v_mfma_f32_16x16x32_bf16 v[124:127], v[132:135], v[180:183], v[124:127]
	v_mfma_f32_16x16x32_bf16 v[120:123], v[140:143], v[180:183], v[120:123]
	v_mfma_f32_16x16x32_bf16 v[116:119], v[132:135], v[188:191], v[116:119]
	v_mfma_f32_16x16x32_bf16 v[112:115], v[140:143], v[188:191], v[112:115]
	v_mfma_f32_16x16x32_bf16 v[108:111], v[132:135], v[196:199], v[108:111]
	v_mfma_f32_16x16x32_bf16 v[104:107], v[140:143], v[196:199], v[104:107]
	v_mfma_f32_16x16x32_bf16 v[100:103], v[132:135], v[204:207], v[100:103]
	v_mfma_f32_16x16x32_bf16 v[96:99], v[140:143], v[204:207], v[96:99]
	v_mfma_f32_16x16x32_bf16 v[60:63], v[144:147], v[176:179], v[60:63]
	v_mfma_f32_16x16x32_bf16 v[56:59], v[152:155], v[176:179], v[56:59]
	v_mfma_f32_16x16x32_bf16 v[52:55], v[144:147], v[184:187], v[52:55]
	v_mfma_f32_16x16x32_bf16 v[48:51], v[152:155], v[184:187], v[48:51]
	v_mfma_f32_16x16x32_bf16 v[44:47], v[144:147], v[192:195], v[44:47]
	v_mfma_f32_16x16x32_bf16 v[40:43], v[152:155], v[192:195], v[40:43]
	v_mfma_f32_16x16x32_bf16 v[36:39], v[144:147], v[200:203], v[36:39]
	v_mfma_f32_16x16x32_bf16 v[32:35], v[152:155], v[200:203], v[32:35]
	v_mfma_f32_16x16x32_bf16 v[60:63], v[148:151], v[180:183], v[60:63]
	v_mfma_f32_16x16x32_bf16 v[56:59], v[172:175], v[180:183], v[56:59]
	v_mfma_f32_16x16x32_bf16 v[52:55], v[148:151], v[188:191], v[52:55]
	v_mfma_f32_16x16x32_bf16 v[48:51], v[172:175], v[188:191], v[48:51]
	v_mfma_f32_16x16x32_bf16 v[44:47], v[148:151], v[196:199], v[44:47]
	v_mfma_f32_16x16x32_bf16 v[40:43], v[172:175], v[196:199], v[40:43]
	v_mfma_f32_16x16x32_bf16 v[36:39], v[148:151], v[204:207], v[36:39]
	v_mfma_f32_16x16x32_bf16 v[32:35], v[172:175], v[204:207], v[32:35]
	s_barrier
; #define GAS __attribute__((address_space(1)))
; #define PG8_STAGE(bufoff, gbase, voff) do { _Pragma("unroll") for (int _i = 0; _i < 2; ++_i) \
;         __builtin_amdgcn_global_load_lds((const GAS unsigned*)((const GAS char*)(gbase) + (voff)[_i]), (PG8_LAS unsigned*)(lds + (bufoff) + ldsw + _i * 8192), 16, 0, 0); } while (0)
; #define PG8_LDA(dst, b, h) do { _Pragma("unroll") for (int m = 0; m < 4; ++m) _Pragma("unroll") for (int k = 0; k < 2; ++k) dst[m][k] = *(const PG8_LAS bf16x8*)(lds + PG8_SA(b, h) + aoff + m * 2048 + k * 1024); } while (0)
; #define PG8_MMA(ai, bj, At, Bt) do { __builtin_amdgcn_s_setprio(1); _Pragma("unroll") for (int m = 0; m < 4; ++m) _Pragma("unroll") for (int n = 0; n < 2; ++n) _Pragma("unroll") for (int k = 0; k < 2; ++k) \
;         acc[ai][bj][m][n] = __builtin_amdgcn_mfma_f32_16x16x32_bf16(Bt[n][k], At[m][k], acc[ai][bj][m][n], 0, 0, 0); __builtin_amdgcn_s_setprio(0); } while (0)
; #define PG8_WAIT_V(n) asm volatile("s_waitcnt vmcnt(" #n ")" ::: "memory")
; #define PG8_WAIT_L(n) asm volatile("s_waitcnt lgkmcnt(" #n ")" ::: "memory")
; #define PG8_BAR __builtin_amdgcn_s_barrier()
; #define PG8_SCHED __builtin_amdgcn_sched_barrier(0)
; #define PG8_STAGE(bufoff, gbase, voff) do { _Pragma("unroll") for (int _i = 0; _i < 2; ++_i) \
;         __builtin_amdgcn_global_load_lds((const GAS unsigned*)((const GAS char*)(gbase) + (voff)[_i]), (PG8_LAS unsigned*)(lds + (bufoff) + ldsw + _i * 8192), 16, 0, 0); } while (0)
; #define PG8_WAIT_V(n) asm volatile("s_waitcnt vmcnt(" #n ")" ::: "memory")
; #define PG8_BAR __builtin_amdgcn_s_barrier()
; template <class Epi, class Sched, bool ALIGN_EPI = false, bool SP2 = false>
; __device__ __forceinline__ void gemm_phase(PG8_LAS unsigned char* lds, PG8_LAS unsigned char* pf, const Gemm g, const Sched& S, const Epi& E, int wv) {
;     ...
;         for (int t = 0; t < ntu; t += 2) {
;             const bool last = (t == ntu - 2);
;             const GAS char* a1 = cA + (size_t)(t + 1) * kstep;
;             const GAS char* a2 = last ? nA : cA + (size_t)(t + 2) * kstep; const GAS char* b2 = last ? nB : cB + (size_t)(t + 2) * kstep;
;     ...
;             PG8_LDA(At, 1, 1); PG8_STAGE(PG8_SB(1, 0), b3, voffB); PG8_STAGE(PG8_SB(1, 1), b3 + hstepB, voffB); PG8_STAGE(PG8_SA(1, 0), a3, voffA);
;             PG8_WAIT_V(8); PG8_WAIT_L(0); PG8_BAR; PG8_MMA(1, 0, At, B0); PG8_MMA(1, 1, At, B1); PG8_BAR; PG8_SCHED;
	s_add_i32 s10, s23, s19
	v_lshl_add_u64 v[208:209], v[208:209], 0, s[16:17]
	s_mov_b32 m0, s10
	ds_read_b128 v[176:179], v171 offset:49152
	ds_read_b128 v[180:183], v171 offset:50176
	ds_read_b128 v[184:187], v171 offset:51200
	ds_read_b128 v[188:191], v171 offset:52224
	ds_read_b128 v[192:195], v171 offset:53248
	ds_read_b128 v[196:199], v171 offset:54272
	ds_read_b128 v[200:203], v171 offset:55296
	ds_read_b128 v[204:207], v171 offset:56320
	global_load_lds_dwordx4 v[208:209], off
	s_add_i32 m0, s10, 0x2000
	s_add_u32 s10, s14, 0x160080
	v_lshl_add_u64 v[208:209], v[214:215], 0, s[16:17]
	s_addc_u32 s11, s15, 0
	s_add_i32 s14, s24, s19
	global_load_lds_dwordx4 v[208:209], off
	v_lshl_add_u64 v[208:209], s[10:11], 0, v[160:161]
	s_mov_b32 m0, s14
	s_nop 0
	global_load_lds_dwordx4 v[208:209], off
	v_lshl_add_u64 v[208:209], s[10:11], 0, v[162:163]
	s_add_i32 m0, s14, 0x2000
	s_nop 0
	global_load_lds_dwordx4 v[208:209], off
	v_lshl_add_u64 v[208:209], v[216:217], 0, s[16:17]
	s_mov_b32 m0, s41
	s_nop 0
	global_load_lds_dwordx4 v[208:209], off
	v_lshl_add_u64 v[208:209], v[218:219], 0, s[16:17]
	s_mov_b32 m0, s42
	s_nop 0
	global_load_lds_dwordx4 v[208:209], off
	s_waitcnt vmcnt(8)
	s_waitcnt lgkmcnt(0)
	s_barrier
	s_waitcnt lgkmcnt(0)
	v_mfma_f32_16x16x32_bf16 v[92:95], v[128:131], v[176:179], v[92:95]
	v_mfma_f32_16x16x32_bf16 v[88:91], v[136:139], v[176:179], v[88:91]
	v_mfma_f32_16x16x32_bf16 v[84:87], v[128:131], v[184:187], v[84:87]
	v_mfma_f32_16x16x32_bf16 v[80:83], v[136:139], v[184:187], v[80:83]
	v_mfma_f32_16x16x32_bf16 v[76:79], v[128:131], v[192:195], v[76:79]
	v_mfma_f32_16x16x32_bf16 v[72:75], v[136:139], v[192:195], v[72:75]
	v_mfma_f32_16x16x32_bf16 v[68:71], v[128:131], v[200:203], v[68:71]
	v_mfma_f32_16x16x32_bf16 v[64:67], v[136:139], v[200:203], v[64:67]
	v_mfma_f32_16x16x32_bf16 v[92:95], v[132:135], v[180:183], v[92:95]
	v_mfma_f32_16x16x32_bf16 v[88:91], v[140:143], v[180:183], v[88:91]
	v_mfma_f32_16x16x32_bf16 v[84:87], v[132:135], v[188:191], v[84:87]
	v_mfma_f32_16x16x32_bf16 v[80:83], v[140:143], v[188:191], v[80:83]
	v_mfma_f32_16x16x32_bf16 v[76:79], v[132:135], v[196:199], v[76:79]
	v_mfma_f32_16x16x32_bf16 v[72:75], v[140:143], v[196:199], v[72:75]
	v_mfma_f32_16x16x32_bf16 v[68:71], v[132:135], v[204:207], v[68:71]
	v_mfma_f32_16x16x32_bf16 v[64:67], v[140:143], v[204:207], v[64:67]
	v_mfma_f32_16x16x32_bf16 v[28:31], v[144:147], v[176:179], v[28:31]
	v_mfma_f32_16x16x32_bf16 v[24:27], v[152:155], v[176:179], v[24:27]
	v_mfma_f32_16x16x32_bf16 v[20:23], v[144:147], v[184:187], v[20:23]
	v_mfma_f32_16x16x32_bf16 v[16:19], v[152:155], v[184:187], v[16:19]
	v_mfma_f32_16x16x32_bf16 v[12:15], v[144:147], v[192:195], v[12:15]
	v_mfma_f32_16x16x32_bf16 v[8:11], v[152:155], v[192:195], v[8:11]
	v_mfma_f32_16x16x32_bf16 v[4:7], v[144:147], v[200:203], v[4:7]
	v_mfma_f32_16x16x32_bf16 v[0:3], v[152:155], v[200:203], v[0:3]
	v_mfma_f32_16x16x32_bf16 v[28:31], v[148:151], v[180:183], v[28:31]
	v_mfma_f32_16x16x32_bf16 v[24:27], v[172:175], v[180:183], v[24:27]
	v_mfma_f32_16x16x32_bf16 v[20:23], v[148:151], v[188:191], v[20:23]
	v_mfma_f32_16x16x32_bf16 v[16:19], v[172:175], v[188:191], v[16:19]
	v_mfma_f32_16x16x32_bf16 v[12:15], v[148:151], v[196:199], v[12:15]
	v_mfma_f32_16x16x32_bf16 v[8:11], v[172:175], v[196:199], v[8:11]
	v_mfma_f32_16x16x32_bf16 v[4:7], v[148:151], v[204:207], v[4:7]
	v_mfma_f32_16x16x32_bf16 v[0:3], v[172:175], v[204:207], v[0:3]
	s_barrier
	s_add_i32 s22, s22, 2
	s_add_u32 s20, s20, 0x100
	s_addc_u32 s21, s21, 0
	s_cmpk_gt_u32 s22, 0x55
	s_mov_b64 s[10:11], s[12:13]
	s_cbranch_scc0 .LBB0_1725
	s_and_b64 vcc, exec, s[2:3]
	s_cbranch_vccz .LBB0_1728
	s_barrier

; #define PG8_STAGE(bufoff, gbase, voff) do { _Pragma("unroll") for (int _i = 0; _i < 2; ++_i) \
;         __builtin_amdgcn_global_load_lds((const GAS unsigned*)((const GAS char*)(gbase) + (voff)[_i]), (PG8_LAS unsigned*)(lds + (bufoff) + ldsw + _i * 8192), 16, 0, 0); } while (0)
; #define PG8_LDA(dst, b, h) do { _Pragma("unroll") for (int m = 0; m < 4; ++m) _Pragma("unroll") for (int k = 0; k < 2; ++k) dst[m][k] = *(const PG8_LAS bf16x8*)(lds + PG8_SA(b, h) + aoff + m * 2048 + k * 1024); } while (0)
; #define PG8_LDB(dst, b, h) do { _Pragma("unroll") for (int n = 0; n < 2; ++n) _Pragma("unroll") for (int k = 0; k < 2; ++k) dst[n][k] = *(const PG8_LAS bf16x8*)(lds + PG8_SB(b, h) + boff + n * 2048 + k * 1024); } while (0)
; #define PG8_MMA(ai, bj, At, Bt) do { __builtin_amdgcn_s_setprio(1); _Pragma("unroll") for (int m = 0; m < 4; ++m) _Pragma("unroll") for (int n = 0; n < 2; ++n) _Pragma("unroll") for (int k = 0; k < 2; ++k) \
;         acc[ai][bj][m][n] = __builtin_amdgcn_mfma_f32_16x16x32_bf16(Bt[n][k], At[m][k], acc[ai][bj][m][n], 0, 0, 0); __builtin_amdgcn_s_setprio(0); } while (0)
; #define PG8_WAIT_V(n) asm volatile("s_waitcnt vmcnt(" #n ")" ::: "memory")
; #define PG8_WAIT_L(n) asm volatile("s_waitcnt lgkmcnt(" #n ")" ::: "memory")
; #define PG8_BAR __builtin_amdgcn_s_barrier()
; #define PG8_SCHED __builtin_amdgcn_sched_barrier(0)
; #define PG8_STAGE(bufoff, gbase, voff) do { _Pragma("unroll") for (int _i = 0; _i < 2; ++_i) \
;         __builtin_amdgcn_global_load_lds((const GAS unsigned*)((const GAS char*)(gbase) + (voff)[_i]), (PG8_LAS unsigned*)(lds + (bufoff) + ldsw + _i * 8192), 16, 0, 0); } while (0)
; #define PG8_WAIT_V(n) asm volatile("s_waitcnt vmcnt(" #n ")" ::: "memory")
; template <class Epi, class Sched, bool ALIGN_EPI = false, bool SP2 = false>
; __device__ __forceinline__ void gemm_phase(PG8_LAS unsigned char* lds, PG8_LAS unsigned char* pf, const Gemm g, const Sched& S, const Epi& E, int wv) {
;     ...
;             PG8_LDB(B0, 0, 0); PG8_LDB(B1, 0, 1); PG8_SCHED; PG8_LDA(At, 0, 0); PG8_STAGE(PG8_SA(1, 1), a1 + (Sched::SPLIT ? hsA : (long)hstepA), voffA);
;             PG8_WAIT_V(8); PG8_WAIT_L(0); PG8_BAR; PG8_MMA(0, 0, At, B0); PG8_MMA(0, 1, At, B1); PG8_BAR; PG8_SCHED;
;             PG8_LDA(At, 0, 1); PG8_STAGE(PG8_SB(0, 0), b2, voffB); PG8_STAGE(PG8_SB(0, 1), b2 + hstepB, voffB); PG8_STAGE(PG8_SA(0, 0), a2, voffA);
.LBB0_1760:
	s_add_u32 s12, s10, 0x100
	s_addc_u32 s13, s11, 0
	s_add_i32 s24, 0, 0x10000
	s_cmpk_eq_i32 s23, 0x54
	s_cselect_b32 s37, s9, s13
	s_cselect_b32 s36, s8, s12
	s_cselect_b32 s15, s29, s22
	s_cselect_b32 s14, s28, s21
	s_add_i32 s25, 0, 0x14000
	v_add_u32_e32 v108, s24, v224
	v_add_u32_e32 v160, s25, v224
	ds_read_b128 v[92:95], v108
	ds_read_b128 v[100:103], v108 offset:1024
	ds_read_b128 v[104:107], v108 offset:2048
	ds_read_b128 v[108:111], v108 offset:3072
	ds_read_b128 v[112:115], v160
	ds_read_b128 v[116:119], v160 offset:1024
	ds_read_b128 v[152:155], v160 offset:2048
	ds_read_b128 v[170:173], v160 offset:3072
	v_lshl_add_u64 v[206:207], s[10:11], 0, v[168:169]
	s_add_i32 m0, s57, 0xc000
	ds_read_b128 v[174:177], v225
	ds_read_b128 v[178:181], v225 offset:1024
	ds_read_b128 v[182:185], v225 offset:2048
	ds_read_b128 v[186:189], v225 offset:3072
	ds_read_b128 v[190:193], v225 offset:4096
	ds_read_b128 v[194:197], v225 offset:5120
	ds_read_b128 v[198:201], v225 offset:6144
	ds_read_b128 v[202:205], v225 offset:7168
	global_load_lds_dwordx4 v[206:207], off
	v_lshl_add_u64 v[206:207], s[10:11], 0, v[166:167]
	s_add_i32 m0, s57, 0xe000
	s_nop 0
	global_load_lds_dwordx4 v[206:207], off
	s_waitcnt vmcnt(8)
	s_waitcnt lgkmcnt(0)
	s_barrier
	s_waitcnt lgkmcnt(0)
	v_mfma_f32_16x16x32_bf16 v[148:151], v[92:95], v[174:177], v[148:151]
	v_mfma_f32_16x16x32_bf16 v[144:147], v[104:107], v[174:177], v[144:147]
	v_mfma_f32_16x16x32_bf16 v[140:143], v[92:95], v[182:185], v[140:143]
	v_mfma_f32_16x16x32_bf16 v[136:139], v[104:107], v[182:185], v[136:139]
	v_mfma_f32_16x16x32_bf16 v[132:135], v[92:95], v[190:193], v[132:135]
	v_mfma_f32_16x16x32_bf16 v[128:131], v[104:107], v[190:193], v[128:131]
	v_mfma_f32_16x16x32_bf16 v[124:127], v[92:95], v[198:201], v[124:127]
	v_mfma_f32_16x16x32_bf16 v[120:123], v[104:107], v[198:201], v[120:123]
	v_mfma_f32_16x16x32_bf16 v[148:151], v[100:103], v[178:181], v[148:151]
	v_mfma_f32_16x16x32_bf16 v[144:147], v[108:111], v[178:181], v[144:147]
	v_mfma_f32_16x16x32_bf16 v[140:143], v[100:103], v[186:189], v[140:143]
	v_mfma_f32_16x16x32_bf16 v[136:139], v[108:111], v[186:189], v[136:139]
	v_mfma_f32_16x16x32_bf16 v[132:135], v[100:103], v[194:197], v[132:135]
	v_mfma_f32_16x16x32_bf16 v[128:131], v[108:111], v[194:197], v[128:131]
	v_mfma_f32_16x16x32_bf16 v[124:127], v[100:103], v[202:205], v[124:127]
	v_mfma_f32_16x16x32_bf16 v[120:123], v[108:111], v[202:205], v[120:123]
	v_mfma_f32_16x16x32_bf16 v[96:99], v[112:115], v[174:177], v[96:99]
	v_mfma_f32_16x16x32_bf16 v[88:91], v[152:155], v[174:177], v[88:91]
	v_mfma_f32_16x16x32_bf16 v[84:87], v[112:115], v[182:185], v[84:87]
	v_mfma_f32_16x16x32_bf16 v[80:83], v[152:155], v[182:185], v[80:83]
	v_mfma_f32_16x16x32_bf16 v[76:79], v[112:115], v[190:193], v[76:79]
	v_mfma_f32_16x16x32_bf16 v[72:75], v[152:155], v[190:193], v[72:75]
	v_mfma_f32_16x16x32_bf16 v[68:71], v[112:115], v[198:201], v[68:71]
	v_mfma_f32_16x16x32_bf16 v[64:67], v[152:155], v[198:201], v[64:67]
	v_mfma_f32_16x16x32_bf16 v[96:99], v[116:119], v[178:181], v[96:99]
	v_mfma_f32_16x16x32_bf16 v[88:91], v[170:173], v[178:181], v[88:91]
	v_mfma_f32_16x16x32_bf16 v[84:87], v[116:119], v[186:189], v[84:87]
	v_mfma_f32_16x16x32_bf16 v[80:83], v[170:173], v[186:189], v[80:83]
	v_mfma_f32_16x16x32_bf16 v[76:79], v[116:119], v[194:197], v[76:79]
	v_mfma_f32_16x16x32_bf16 v[72:75], v[170:173], v[194:197], v[72:75]
	v_mfma_f32_16x16x32_bf16 v[68:71], v[116:119], v[202:205], v[68:71]
	v_mfma_f32_16x16x32_bf16 v[64:67], v[170:173], v[202:205], v[64:67]
	s_barrier
	s_add_i32 s10, s24, s27
	v_lshl_add_u64 v[206:207], s[14:15], 0, v[158:159]
	s_mov_b32 m0, s10
	ds_read_b128 v[174:177], v225 offset:16384
	ds_read_b128 v[178:181], v225 offset:17408
	ds_read_b128 v[182:185], v225 offset:18432
	ds_read_b128 v[186:189], v225 offset:19456
	ds_read_b128 v[190:193], v225 offset:20480
	ds_read_b128 v[194:197], v225 offset:21504
	ds_read_b128 v[198:201], v225 offset:22528
	ds_read_b128 v[202:205], v225 offset:23552
	global_load_lds_dwordx4 v[206:207], off
	s_add_i32 m0, s10, 0x2000
	s_add_u32 s10, s14, 0x160000
	v_lshl_add_u64 v[208:209], s[14:15], 0, v[164:165]
	s_addc_u32 s11, s15, 0
	s_add_i32 s24, s25, s27
	global_load_lds_dwordx4 v[208:209], off
	v_lshl_add_u64 v[214:215], s[10:11], 0, v[158:159]
	s_mov_b32 m0, s24
	v_lshl_add_u64 v[216:217], s[36:37], 0, v[162:163]
	global_load_lds_dwordx4 v[214:215], off
	v_lshl_add_u64 v[214:215], s[10:11], 0, v[164:165]
	s_add_i32 m0, s24, 0x2000
	s_nop 0
	global_load_lds_dwordx4 v[214:215], off
	v_lshl_add_u64 v[214:215], s[36:37], 0, v[156:157]
	s_mov_b32 m0, s57
	s_nop 0
	global_load_lds_dwordx4 v[214:215], off
	s_mov_b32 m0, s58
	s_nop 0
	global_load_lds_dwordx4 v[216:217], off
	s_waitcnt vmcnt(8)
	s_waitcnt lgkmcnt(0)
	s_barrier
; #define PG8_STAGE(bufoff, gbase, voff) do { _Pragma("unroll") for (int _i = 0; _i < 2; ++_i) \
;         __builtin_amdgcn_global_load_lds((const GAS unsigned*)((const GAS char*)(gbase) + (voff)[_i]), (PG8_LAS unsigned*)(lds + (bufoff) + ldsw + _i * 8192), 16, 0, 0); } while (0)
; #define PG8_LDA(dst, b, h) do { _Pragma("unroll") for (int m = 0; m < 4; ++m) _Pragma("unroll") for (int k = 0; k < 2; ++k) dst[m][k] = *(const PG8_LAS bf16x8*)(lds + PG8_SA(b, h) + aoff + m * 2048 + k * 1024); } while (0)
; #define PG8_LDB(dst, b, h) do { _Pragma("unroll") for (int n = 0; n < 2; ++n) _Pragma("unroll") for (int k = 0; k < 2; ++k) dst[n][k] = *(const PG8_LAS bf16x8*)(lds + PG8_SB(b, h) + boff + n * 2048 + k * 1024); } while (0)
; #define PG8_MMA(ai, bj, At, Bt) do { __builtin_amdgcn_s_setprio(1); _Pragma("unroll") for (int m = 0; m < 4; ++m) _Pragma("unroll") for (int n = 0; n < 2; ++n) _Pragma("unroll") for (int k = 0; k < 2; ++k) \
;         acc[ai][bj][m][n] = __builtin_amdgcn_mfma_f32_16x16x32_bf16(Bt[n][k], At[m][k], acc[ai][bj][m][n], 0, 0, 0); __builtin_amdgcn_s_setprio(0); } while (0)
; #define PG8_WAIT_V(n) asm volatile("s_waitcnt vmcnt(" #n ")" ::: "memory")
; #define PG8_WAIT_L(n) asm volatile("s_waitcnt lgkmcnt(" #n ")" ::: "memory")
; #define PG8_BAR __builtin_amdgcn_s_barrier()
; #define PG8_SCHED __builtin_amdgcn_sched_barrier(0)
; #define PG8_STAGE(bufoff, gbase, voff) do { _Pragma("unroll") for (int _i = 0; _i < 2; ++_i) \
;         __builtin_amdgcn_global_load_lds((const GAS unsigned*)((const GAS char*)(gbase) + (voff)[_i]), (PG8_LAS unsigned*)(lds + (bufoff) + ldsw + _i * 8192), 16, 0, 0); } while (0)
; #define PG8_BAR __builtin_amdgcn_s_barrier()
; template <class Epi, class Sched, bool ALIGN_EPI = false, bool SP2 = false>
; __device__ __forceinline__ void gemm_phase(PG8_LAS unsigned char* lds, PG8_LAS unsigned char* pf, const Gemm g, const Sched& S, const Epi& E, int wv) {
;     ...
;             PG8_WAIT_V(8); PG8_WAIT_L(0); PG8_BAR; PG8_MMA(1, 0, At, B0); PG8_MMA(1, 1, At, B1); PG8_BAR; PG8_SCHED;
;             PG8_LDB(B0, 1, 0); PG8_LDB(B1, 1, 1); PG8_SCHED; PG8_LDA(At, 1, 0); PG8_STAGE(PG8_SA(0, 1), a2 + (Sched::SPLIT ? ((last && has_next) ? (nxt.kh > 0 ? -(long)hstepA : (long)hstepA) : hsA) : (long)hstepA), voffA);
;             PG8_WAIT_V(8); PG8_WAIT_L(0); PG8_BAR; PG8_MMA(0, 0, At, B0); PG8_MMA(0, 1, At, B1); PG8_BAR; PG8_SCHED;
	s_waitcnt lgkmcnt(0)
	v_mfma_f32_16x16x32_bf16 v[60:63], v[92:95], v[174:177], v[60:63]
	v_mfma_f32_16x16x32_bf16 v[56:59], v[104:107], v[174:177], v[56:59]
	v_mfma_f32_16x16x32_bf16 v[52:55], v[92:95], v[182:185], v[52:55]
	v_mfma_f32_16x16x32_bf16 v[48:51], v[104:107], v[182:185], v[48:51]
	v_mfma_f32_16x16x32_bf16 v[44:47], v[92:95], v[190:193], v[44:47]
	v_mfma_f32_16x16x32_bf16 v[40:43], v[104:107], v[190:193], v[40:43]
	v_mfma_f32_16x16x32_bf16 v[36:39], v[92:95], v[198:201], v[36:39]
	v_mfma_f32_16x16x32_bf16 v[32:35], v[104:107], v[198:201], v[32:35]
	v_mfma_f32_16x16x32_bf16 v[60:63], v[100:103], v[178:181], v[60:63]
	v_mfma_f32_16x16x32_bf16 v[56:59], v[108:111], v[178:181], v[56:59]
	v_mfma_f32_16x16x32_bf16 v[52:55], v[100:103], v[186:189], v[52:55]
	v_mfma_f32_16x16x32_bf16 v[48:51], v[108:111], v[186:189], v[48:51]
	v_mfma_f32_16x16x32_bf16 v[44:47], v[100:103], v[194:197], v[44:47]
	v_mfma_f32_16x16x32_bf16 v[40:43], v[108:111], v[194:197], v[40:43]
	v_mfma_f32_16x16x32_bf16 v[36:39], v[100:103], v[202:205], v[36:39]
	v_mfma_f32_16x16x32_bf16 v[32:35], v[108:111], v[202:205], v[32:35]
	v_mfma_f32_16x16x32_bf16 v[28:31], v[112:115], v[174:177], v[28:31]
	v_mfma_f32_16x16x32_bf16 v[24:27], v[152:155], v[174:177], v[24:27]
	v_mfma_f32_16x16x32_bf16 v[20:23], v[112:115], v[182:185], v[20:23]
	v_mfma_f32_16x16x32_bf16 v[16:19], v[152:155], v[182:185], v[16:19]
	v_mfma_f32_16x16x32_bf16 v[12:15], v[112:115], v[190:193], v[12:15]
	v_mfma_f32_16x16x32_bf16 v[8:11], v[152:155], v[190:193], v[8:11]
	v_mfma_f32_16x16x32_bf16 v[4:7], v[112:115], v[198:201], v[4:7]
	v_mfma_f32_16x16x32_bf16 v[0:3], v[152:155], v[198:201], v[0:3]
	v_mfma_f32_16x16x32_bf16 v[28:31], v[116:119], v[178:181], v[28:31]
	v_mfma_f32_16x16x32_bf16 v[24:27], v[170:173], v[178:181], v[24:27]
	v_mfma_f32_16x16x32_bf16 v[20:23], v[116:119], v[186:189], v[20:23]
	v_mfma_f32_16x16x32_bf16 v[16:19], v[170:173], v[186:189], v[16:19]
	v_mfma_f32_16x16x32_bf16 v[12:15], v[116:119], v[194:197], v[12:15]
	v_mfma_f32_16x16x32_bf16 v[8:11], v[170:173], v[194:197], v[8:11]
	v_mfma_f32_16x16x32_bf16 v[4:7], v[116:119], v[202:205], v[4:7]
	v_mfma_f32_16x16x32_bf16 v[0:3], v[170:173], v[202:205], v[0:3]
	s_barrier
	s_add_i32 s24, 0, 0x18000
	s_add_i32 s25, 0, 0x1c000
	v_add_u32_e32 v108, s24, v224
	v_add_u32_e32 v160, s25, v224
	ds_read_b128 v[92:95], v108
	ds_read_b128 v[100:103], v108 offset:1024
	ds_read_b128 v[104:107], v108 offset:2048
	ds_read_b128 v[108:111], v108 offset:3072
	ds_read_b128 v[112:115], v160
	ds_read_b128 v[116:119], v160 offset:1024
	ds_read_b128 v[152:155], v160 offset:2048
	ds_read_b128 v[170:173], v160 offset:3072
	s_add_u32 s10, s36, 0x160000
	s_addc_u32 s11, s37, 0
	s_mov_b32 m0, s59
	v_lshl_add_u64 v[218:219], s[10:11], 0, v[156:157]
	ds_read_b128 v[174:177], v225 offset:32768
	ds_read_b128 v[178:181], v225 offset:33792
	ds_read_b128 v[182:185], v225 offset:34816
	ds_read_b128 v[186:189], v225 offset:35840
	ds_read_b128 v[190:193], v225 offset:36864
	ds_read_b128 v[194:197], v225 offset:37888
	ds_read_b128 v[198:201], v225 offset:38912
	ds_read_b128 v[202:205], v225 offset:39936
	global_load_lds_dwordx4 v[218:219], off
	v_lshl_add_u64 v[218:219], s[10:11], 0, v[162:163]
	s_mov_b32 m0, s60
	s_nop 0
	global_load_lds_dwordx4 v[218:219], off
	s_waitcnt vmcnt(8)
	s_waitcnt lgkmcnt(0)
	s_barrier
	s_waitcnt lgkmcnt(0)
	v_mfma_f32_16x16x32_bf16 v[148:151], v[92:95], v[174:177], v[148:151]
	v_mfma_f32_16x16x32_bf16 v[144:147], v[104:107], v[174:177], v[144:147]
	v_mfma_f32_16x16x32_bf16 v[140:143], v[92:95], v[182:185], v[140:143]
	v_mfma_f32_16x16x32_bf16 v[136:139], v[104:107], v[182:185], v[136:139]
	v_mfma_f32_16x16x32_bf16 v[132:135], v[92:95], v[190:193], v[132:135]
	v_mfma_f32_16x16x32_bf16 v[128:131], v[104:107], v[190:193], v[128:131]
	v_mfma_f32_16x16x32_bf16 v[124:127], v[92:95], v[198:201], v[124:127]
	v_mfma_f32_16x16x32_bf16 v[120:123], v[104:107], v[198:201], v[120:123]
	v_mfma_f32_16x16x32_bf16 v[148:151], v[100:103], v[178:181], v[148:151]
	v_mfma_f32_16x16x32_bf16 v[144:147], v[108:111], v[178:181], v[144:147]
	v_mfma_f32_16x16x32_bf16 v[140:143], v[100:103], v[186:189], v[140:143]
	v_mfma_f32_16x16x32_bf16 v[136:139], v[108:111], v[186:189], v[136:139]
	v_mfma_f32_16x16x32_bf16 v[132:135], v[100:103], v[194:197], v[132:135]
	v_mfma_f32_16x16x32_bf16 v[128:131], v[108:111], v[194:197], v[128:131]
	v_mfma_f32_16x16x32_bf16 v[124:127], v[100:103], v[202:205], v[124:127]
	v_mfma_f32_16x16x32_bf16 v[120:123], v[108:111], v[202:205], v[120:123]
	v_mfma_f32_16x16x32_bf16 v[96:99], v[112:115], v[174:177], v[96:99]
	v_mfma_f32_16x16x32_bf16 v[88:91], v[152:155], v[174:177], v[88:91]
	v_mfma_f32_16x16x32_bf16 v[84:87], v[112:115], v[182:185], v[84:87]
	v_mfma_f32_16x16x32_bf16 v[80:83], v[152:155], v[182:185], v[80:83]
	v_mfma_f32_16x16x32_bf16 v[76:79], v[112:115], v[190:193], v[76:79]
	v_mfma_f32_16x16x32_bf16 v[72:75], v[152:155], v[190:193], v[72:75]
	v_mfma_f32_16x16x32_bf16 v[68:71], v[112:115], v[198:201], v[68:71]
	v_mfma_f32_16x16x32_bf16 v[64:67], v[152:155], v[198:201], v[64:67]
	v_mfma_f32_16x16x32_bf16 v[96:99], v[116:119], v[178:181], v[96:99]
	v_mfma_f32_16x16x32_bf16 v[88:91], v[170:173], v[178:181], v[88:91]
	v_mfma_f32_16x16x32_bf16 v[84:87], v[116:119], v[186:189], v[84:87]
	v_mfma_f32_16x16x32_bf16 v[80:83], v[170:173], v[186:189], v[80:83]
	v_mfma_f32_16x16x32_bf16 v[76:79], v[116:119], v[194:197], v[76:79]
	v_mfma_f32_16x16x32_bf16 v[72:75], v[170:173], v[194:197], v[72:75]
	v_mfma_f32_16x16x32_bf16 v[68:71], v[116:119], v[202:205], v[68:71]
	v_mfma_f32_16x16x32_bf16 v[64:67], v[170:173], v[202:205], v[64:67]
	s_barrier
; #define GAS __attribute__((address_space(1)))
; #define PG8_STAGE(bufoff, gbase, voff) do { _Pragma("unroll") for (int _i = 0; _i < 2; ++_i) \
;         __builtin_amdgcn_global_load_lds((const GAS unsigned*)((const GAS char*)(gbase) + (voff)[_i]), (PG8_LAS unsigned*)(lds + (bufoff) + ldsw + _i * 8192), 16, 0, 0); } while (0)
; #define PG8_LDA(dst, b, h) do { _Pragma("unroll") for (int m = 0; m < 4; ++m) _Pragma("unroll") for (int k = 0; k < 2; ++k) dst[m][k] = *(const PG8_LAS bf16x8*)(lds + PG8_SA(b, h) + aoff + m * 2048 + k * 1024); } while (0)
; #define PG8_MMA(ai, bj, At, Bt) do { __builtin_amdgcn_s_setprio(1); _Pragma("unroll") for (int m = 0; m < 4; ++m) _Pragma("unroll") for (int n = 0; n < 2; ++n) _Pragma("unroll") for (int k = 0; k < 2; ++k) \
;         acc[ai][bj][m][n] = __builtin_amdgcn_mfma_f32_16x16x32_bf16(Bt[n][k], At[m][k], acc[ai][bj][m][n], 0, 0, 0); __builtin_amdgcn_s_setprio(0); } while (0)
; #define PG8_WAIT_V(n) asm volatile("s_waitcnt vmcnt(" #n ")" ::: "memory")
; #define PG8_WAIT_L(n) asm volatile("s_waitcnt lgkmcnt(" #n ")" ::: "memory")
; #define PG8_BAR __builtin_amdgcn_s_barrier()
; #define PG8_SCHED __builtin_amdgcn_sched_barrier(0)
; #define PG8_STAGE(bufoff, gbase, voff) do { _Pragma("unroll") for (int _i = 0; _i < 2; ++_i) \
;         __builtin_amdgcn_global_load_lds((const GAS unsigned*)((const GAS char*)(gbase) + (voff)[_i]), (PG8_LAS unsigned*)(lds + (bufoff) + ldsw + _i * 8192), 16, 0, 0); } while (0)
; #define PG8_WAIT_V(n) asm volatile("s_waitcnt vmcnt(" #n ")" ::: "memory")
; #define PG8_BAR __builtin_amdgcn_s_barrier()
; template <class Epi, class Sched, bool ALIGN_EPI = false, bool SP2 = false>
; __device__ __forceinline__ void gemm_phase(PG8_LAS unsigned char* lds, PG8_LAS unsigned char* pf, const Gemm g, const Sched& S, const Epi& E, int wv) {
;     ...
;         for (int t = 0; t < ntu; t += 2) {
;             const bool last = (t == ntu - 2);
;             const GAS char* a1 = cA + (size_t)(t + 1) * kstep;
;             const GAS char* a2 = last ? nA : cA + (size_t)(t + 2) * kstep; const GAS char* b2 = last ? nB : cB + (size_t)(t + 2) * kstep;
;     ...
;             PG8_LDA(At, 1, 1); PG8_STAGE(PG8_SB(1, 0), b3, voffB); PG8_STAGE(PG8_SB(1, 1), b3 + hstepB, voffB); PG8_STAGE(PG8_SA(1, 0), a3, voffA);
;             PG8_WAIT_V(8); PG8_WAIT_L(0); PG8_BAR; PG8_MMA(1, 0, At, B0); PG8_MMA(1, 1, At, B1); PG8_BAR; PG8_SCHED;
	s_add_i32 s10, s24, s27
	v_lshl_add_u64 v[206:207], v[206:207], 0, s[16:17]
	s_mov_b32 m0, s10
	ds_read_b128 v[174:177], v225 offset:49152
	ds_read_b128 v[178:181], v225 offset:50176
	ds_read_b128 v[182:185], v225 offset:51200
	ds_read_b128 v[186:189], v225 offset:52224
	ds_read_b128 v[190:193], v225 offset:53248
	ds_read_b128 v[194:197], v225 offset:54272
	ds_read_b128 v[198:201], v225 offset:55296
	ds_read_b128 v[202:205], v225 offset:56320
	global_load_lds_dwordx4 v[206:207], off
	s_add_i32 m0, s10, 0x2000
	s_add_u32 s10, s14, 0x160080
	v_lshl_add_u64 v[206:207], v[208:209], 0, s[16:17]
	s_addc_u32 s11, s15, 0
	s_add_i32 s14, s25, s27
	global_load_lds_dwordx4 v[206:207], off
	v_lshl_add_u64 v[206:207], s[10:11], 0, v[158:159]
	s_mov_b32 m0, s14
	s_nop 0
	global_load_lds_dwordx4 v[206:207], off
	v_lshl_add_u64 v[206:207], s[10:11], 0, v[164:165]
	s_add_i32 m0, s14, 0x2000
	s_nop 0
	global_load_lds_dwordx4 v[206:207], off
	v_lshl_add_u64 v[206:207], v[214:215], 0, s[16:17]
	s_mov_b32 m0, s64
	s_nop 0
	global_load_lds_dwordx4 v[206:207], off
	v_lshl_add_u64 v[206:207], v[216:217], 0, s[16:17]
	s_mov_b32 m0, s65
	s_nop 0
	global_load_lds_dwordx4 v[206:207], off
	s_waitcnt vmcnt(8)
	s_waitcnt lgkmcnt(0)
	s_barrier
	s_waitcnt lgkmcnt(0)
	v_mfma_f32_16x16x32_bf16 v[60:63], v[92:95], v[174:177], v[60:63]
	v_mfma_f32_16x16x32_bf16 v[56:59], v[104:107], v[174:177], v[56:59]
	v_mfma_f32_16x16x32_bf16 v[52:55], v[92:95], v[182:185], v[52:55]
	v_mfma_f32_16x16x32_bf16 v[48:51], v[104:107], v[182:185], v[48:51]
	v_mfma_f32_16x16x32_bf16 v[44:47], v[92:95], v[190:193], v[44:47]
	v_mfma_f32_16x16x32_bf16 v[40:43], v[104:107], v[190:193], v[40:43]
	v_mfma_f32_16x16x32_bf16 v[36:39], v[92:95], v[198:201], v[36:39]
	v_mfma_f32_16x16x32_bf16 v[32:35], v[104:107], v[198:201], v[32:35]
	v_mfma_f32_16x16x32_bf16 v[60:63], v[100:103], v[178:181], v[60:63]
	v_mfma_f32_16x16x32_bf16 v[56:59], v[108:111], v[178:181], v[56:59]
	v_mfma_f32_16x16x32_bf16 v[52:55], v[100:103], v[186:189], v[52:55]
	v_mfma_f32_16x16x32_bf16 v[48:51], v[108:111], v[186:189], v[48:51]
	v_mfma_f32_16x16x32_bf16 v[44:47], v[100:103], v[194:197], v[44:47]
	v_mfma_f32_16x16x32_bf16 v[40:43], v[108:111], v[194:197], v[40:43]
	v_mfma_f32_16x16x32_bf16 v[36:39], v[100:103], v[202:205], v[36:39]
	v_mfma_f32_16x16x32_bf16 v[32:35], v[108:111], v[202:205], v[32:35]
	v_mfma_f32_16x16x32_bf16 v[28:31], v[112:115], v[174:177], v[28:31]
	v_mfma_f32_16x16x32_bf16 v[24:27], v[152:155], v[174:177], v[24:27]
	v_mfma_f32_16x16x32_bf16 v[20:23], v[112:115], v[182:185], v[20:23]
	v_mfma_f32_16x16x32_bf16 v[16:19], v[152:155], v[182:185], v[16:19]
	v_mfma_f32_16x16x32_bf16 v[12:15], v[112:115], v[190:193], v[12:15]
	v_mfma_f32_16x16x32_bf16 v[8:11], v[152:155], v[190:193], v[8:11]
	v_mfma_f32_16x16x32_bf16 v[4:7], v[112:115], v[198:201], v[4:7]
	v_mfma_f32_16x16x32_bf16 v[0:3], v[152:155], v[198:201], v[0:3]
	v_mfma_f32_16x16x32_bf16 v[28:31], v[116:119], v[178:181], v[28:31]
	v_mfma_f32_16x16x32_bf16 v[24:27], v[170:173], v[178:181], v[24:27]
	v_mfma_f32_16x16x32_bf16 v[20:23], v[116:119], v[186:189], v[20:23]
	v_mfma_f32_16x16x32_bf16 v[16:19], v[170:173], v[186:189], v[16:19]
	v_mfma_f32_16x16x32_bf16 v[12:15], v[116:119], v[194:197], v[12:15]
	v_mfma_f32_16x16x32_bf16 v[8:11], v[170:173], v[194:197], v[8:11]
	v_mfma_f32_16x16x32_bf16 v[4:7], v[116:119], v[202:205], v[4:7]
	v_mfma_f32_16x16x32_bf16 v[0:3], v[170:173], v[202:205], v[0:3]
	s_barrier
	s_add_i32 s23, s23, 2
	s_add_u32 s21, s21, 0x100
	s_addc_u32 s22, s22, 0
	s_cmpk_gt_u32 s23, 0x55
	s_mov_b64 s[10:11], s[12:13]
	s_cbranch_scc0 .LBB0_1760
	s_and_b64 vcc, exec, s[4:5]
	s_cbranch_vccz .LBB0_1763
	s_barrier
